# GEMM weight operands stored k-blocked [K/32][N][32] by the prep transposes so each LDS-DMA piece of the K-loop reads 1 KiB of contiguous memory (full cache lines) instead of 16 half lines
# speedup vs baseline: 1.0858x; 1.0858x over previous
.LBB0_13:
	s_lshr_b32 s13, s12, 4
	s_and_b32 s13, s13, 24
	s_and_b32 s14, s12, 7
	s_or_b32 s13, s13, s14
	s_lshl_b32 s13, s13, 10
	v_mov_b32 v8, v198
	s_or_b32 s14, s13, s65
	v_ashrrev_i32_e32 v12, 2, v8
	v_add_u32_e32 v0, s14, v12
	v_ashrrev_i32_e32 v1, 31, v0
	v_readlane_b32 s16, v253, 21
	s_lshl_b32 s15, s12, 5
	v_lshlrev_b64 v[0:1], 11, v[0:1]
	v_readlane_b32 s17, v253, 22
	v_lshlrev_b32_e32 v2, 4, v8
	s_and_b32 s13, s15, 0xf00
	v_lshl_add_u64 v[0:1], s[16:17], 0, v[0:1]
	v_and_b32_e32 v152, 48, v2
	v_lshl_add_u64 v[14:15], v[0:1], 0, v[152:153]
	v_add_u32_e32 v0, s13, v12
	v_ashrrev_i32_e32 v1, 31, v0
	v_lshlrev_b64 v[0:1], 6, v[0:1]
	v_lshl_add_u64 v[0:1], s[4:5], 0, v[0:1]
	v_add_co_u32_e32 v54, vcc, s62, v14
	v_lshl_add_u64 v[0:1], v[0:1], 0, v[152:153]
	s_nop 0
	v_addc_co_u32_e32 v55, vcc, 0, v15, vcc
	s_lshl_b32 s16, s11, 11
	s_lshl_b32 s17, s12, 6
	s_and_b32 s18, s10, 7
	v_add_co_u32_e32 v2, vcc, s62, v0
	s_and_b32 s16, s16, 0x780000
	s_and_b32 s19, s17, 0x6000
	s_lshl_b32 s18, s18, 10
	v_lshrrev_b32_e32 v6, 2, v8
	v_addc_co_u32_e32 v3, vcc, 0, v1, vcc
	v_and_b32_e32 v6, 12, v6
	v_ashrrev_i32_e32 v13, 31, v12
	s_movk_i32 s17, 0x1230
	s_add_u32 s16, s7, s16
	v_add_co_u32_e32 v4, vcc, s33, v0
	v_lshrrev_b32_e64 v10, v6, s17
	v_lshlrev_b64 v[6:7], 11, v[12:13]
	s_addc_u32 s17, s8, 0
	s_or_b32 s18, s18, s19
	v_addc_co_u32_e32 v5, vcc, 0, v1, vcc
	v_and_b32_e32 v22, 3, v8
	v_xor_b32_e32 v8, v10, v8
	v_lshl_add_u64 v[156:157], s[16:17], 0, v[6:7]
	s_or_b32 s16, s18, s65
	v_add_co_u32_e32 v20, vcc, s72, v0
	v_lshlrev_b32_e32 v9, 6, v12
	v_lshlrev_b32_e32 v8, 4, v8
	v_add_u32_e32 v12, s16, v12
	v_addc_co_u32_e32 v21, vcc, 0, v1, vcc
	s_nop 0
	v_readfirstlane_b32 s26, v14
	v_readfirstlane_b32 s27, v15
	v_readfirstlane_b32 s28, v0
	v_readfirstlane_b32 s29, v1
	v_lshrrev_b32_e32 v250, 6, v198
	s_nop 0
	v_readfirstlane_b32 s24, v250
	s_lshl_b32 s24, s24, 10
	v_lshrrev_b32_e32 v250, 2, v200
	v_lshrrev_b32_e32 v251, 4, v200
	v_lshlrev_b32_e32 v251, 2, v251
	v_mov_b32_e32 v248, 0x1230
	v_lshrrev_b32_e32 v251, v251, v248
	v_xor_b32_e32 v251, v251, v200
	v_and_b32_e32 v251, 3, v251
	v_lshlrev_b32_e32 v251, 4, v251
	v_lshl_add_u32 v244, v250, 11, v251
	v_add_u32_e32 v245, 0x20000, v244
	v_add_u32_e32 v246, 0x40000, v244
	v_add_u32_e32 v247, 0x60000, v244
	v_lshl_add_u32 v156, v250, 6, v251
	v_add_u32_e32 v157, 0x1000, v156
	v_add_u32_e32 v158, 0x2000, v156
	v_add_u32_e32 v159, 0x3000, v156
	s_mov_b32 s25, 0
	s_add_u32 m0, s25, s24
	s_nop 0
	global_load_lds_dwordx4 v244, s[26:27]
	s_add_u32 m0, m0, 0x1000
	s_nop 0
	global_load_lds_dwordx4 v245, s[26:27]
	s_add_u32 m0, m0, 0x1000
	s_nop 0
	global_load_lds_dwordx4 v156, s[28:29]
	s_add_u32 m0, m0, 0x1000
	s_nop 0
	global_load_lds_dwordx4 v157, s[28:29]
	s_add_u32 m0, m0, 0x1000
	s_nop 0
	global_load_lds_dwordx4 v158, s[28:29]
	s_add_u32 m0, m0, 0x1000
	s_nop 0
	global_load_lds_dwordx4 v159, s[28:29]
	s_add_u32 s26, s26, 64
	s_addc_u32 s27, s27, 0
	s_add_u32 s28, s28, 0x40000
	s_addc_u32 s29, s29, 0
	s_add_u32 s25, s25, 24576
	s_cmp_eq_u32 s25, 73728
	s_cselect_b32 s25, 0, s25
	s_add_u32 m0, s25, s24
	s_nop 0
	global_load_lds_dwordx4 v244, s[26:27]
	s_add_u32 m0, m0, 0x1000
	s_nop 0
	global_load_lds_dwordx4 v245, s[26:27]
	s_add_u32 m0, m0, 0x1000
	s_nop 0
	global_load_lds_dwordx4 v156, s[28:29]
	s_add_u32 m0, m0, 0x1000
	s_nop 0
	global_load_lds_dwordx4 v157, s[28:29]
	s_add_u32 m0, m0, 0x1000
	s_nop 0
	global_load_lds_dwordx4 v158, s[28:29]
	s_add_u32 m0, m0, 0x1000
	s_nop 0
	global_load_lds_dwordx4 v159, s[28:29]
	s_add_u32 s26, s26, 64
	s_addc_u32 s27, s27, 0
	s_add_u32 s28, s28, 0x40000
	s_addc_u32 s29, s29, 0
	s_add_u32 s25, s25, 24576
	s_cmp_eq_u32 s25, 73728
	s_cselect_b32 s25, 0, s25
	s_add_u32 m0, s25, s24
	s_nop 0
	global_load_lds_dwordx4 v244, s[26:27]
	s_add_u32 m0, m0, 0x1000
	s_nop 0
	global_load_lds_dwordx4 v245, s[26:27]
	s_add_u32 m0, m0, 0x1000
	s_nop 0
	global_load_lds_dwordx4 v156, s[28:29]
	s_add_u32 m0, m0, 0x1000
	s_nop 0
	global_load_lds_dwordx4 v157, s[28:29]
	s_add_u32 m0, m0, 0x1000
	s_nop 0
	global_load_lds_dwordx4 v158, s[28:29]
	s_add_u32 m0, m0, 0x1000
	s_nop 0
	global_load_lds_dwordx4 v159, s[28:29]
	s_add_u32 s26, s26, 64
	s_addc_u32 s27, s27, 0
	s_add_u32 s28, s28, 0x40000
	s_addc_u32 s29, s29, 0
	s_add_u32 s25, s25, 24576
	s_cmp_eq_u32 s25, 73728
	s_cselect_b32 s25, 0, s25
	v_mov_b32_e32 v24, 0
	v_mov_b32_e32 v25, v24
	v_mov_b32_e32 v26, v24
	v_mov_b32_e32 v27, v24
	v_mov_b32_e32 v28, v24
	v_mov_b32_e32 v29, v24
	v_mov_b32_e32 v84, v24
	v_mov_b32_e32 v85, v24
	v_mov_b32_e32 v86, v24
	v_mov_b32_e32 v87, v24
	v_mov_b32_e32 v88, v24
	v_mov_b32_e32 v89, v24
	v_mov_b32_e32 v90, v24
	v_mov_b32_e32 v91, v24
	v_mov_b32_e32 v92, v24
	v_mov_b32_e32 v93, v24
	v_mov_b32_e32 v94, v24
	v_mov_b32_e32 v95, v24
	v_mov_b32_e32 v96, v24
	v_mov_b32_e32 v97, v24
	v_mov_b32_e32 v98, v24
	v_mov_b32_e32 v99, v24
	v_mov_b32_e32 v54, v24
	v_mov_b32_e32 v55, v24
	v_mov_b32_e32 v100, v24
	v_mov_b32_e32 v101, v24
	v_mov_b32_e32 v30, v24
	v_mov_b32_e32 v31, v24
	v_mov_b32_e32 v32, v24
	v_mov_b32_e32 v33, v24
	v_mov_b32_e32 v34, v24
	v_mov_b32_e32 v35, v24
	v_mov_b32_e32 v36, v24
	v_mov_b32_e32 v37, v24
	v_mov_b32_e32 v38, v24
	v_mov_b32_e32 v39, v24
	v_mov_b32_e32 v40, v24
	v_mov_b32_e32 v41, v24
	v_mov_b32_e32 v42, v24
	v_mov_b32_e32 v43, v24
	v_mov_b32_e32 v44, v24
	v_mov_b32_e32 v45, v24
	v_mov_b32_e32 v46, v24
	v_mov_b32_e32 v47, v24
	v_mov_b32_e32 v48, v24
	v_mov_b32_e32 v49, v24
	v_mov_b32_e32 v50, v24
	v_mov_b32_e32 v51, v24
	v_mov_b32_e32 v52, v24
	v_mov_b32_e32 v53, v24
	v_mov_b32_e32 v102, v24
	v_mov_b32_e32 v103, v24
	v_mov_b32_e32 v104, v24
	v_mov_b32_e32 v105, v24
	v_mov_b32_e32 v106, v24
	v_mov_b32_e32 v107, v24
	v_mov_b32_e32 v116, v24
	v_mov_b32_e32 v117, v24
	v_mov_b32_e32 v118, v24
	v_mov_b32_e32 v119, v24
	v_mov_b32_e32 v128, v24
	v_mov_b32_e32 v129, v24
	v_mov_b32_e32 v130, v24
	v_mov_b32_e32 v131, v24
	v_mov_b32_e32 v108, v24
	v_mov_b32_e32 v109, v24
	v_mov_b32_e32 v110, v24
	v_mov_b32_e32 v111, v24
	v_mov_b32_e32 v112, v24
	v_mov_b32_e32 v113, v24
	v_mov_b32_e32 v114, v24
	v_mov_b32_e32 v115, v24
	v_mov_b32_e32 v120, v24
	v_mov_b32_e32 v121, v24
	v_mov_b32_e32 v122, v24
	v_mov_b32_e32 v123, v24
	v_mov_b32_e32 v124, v24
	v_mov_b32_e32 v125, v24
	v_mov_b32_e32 v126, v24
	v_mov_b32_e32 v127, v24
	v_mov_b32_e32 v64, v24
	v_mov_b32_e32 v65, v24
	v_mov_b32_e32 v66, v24
	v_mov_b32_e32 v67, v24
	v_mov_b32_e32 v68, v24
	v_mov_b32_e32 v69, v24
	v_mov_b32_e32 v70, v24
	v_mov_b32_e32 v71, v24
	v_mov_b32_e32 v80, v24
	v_mov_b32_e32 v81, v24
	v_mov_b32_e32 v82, v24
	v_mov_b32_e32 v83, v24
	v_mov_b32_e32 v56, v24
	v_mov_b32_e32 v57, v24
	v_mov_b32_e32 v58, v24
	v_mov_b32_e32 v59, v24
	v_mov_b32_e32 v132, v24
	v_mov_b32_e32 v133, v24
	v_mov_b32_e32 v134, v24
	v_mov_b32_e32 v135, v24
	v_mov_b32_e32 v136, v24
	v_mov_b32_e32 v137, v24
	v_mov_b32_e32 v138, v24
	v_mov_b32_e32 v139, v24
	v_mov_b32_e32 v140, v24
	v_mov_b32_e32 v141, v24
	v_mov_b32_e32 v142, v24
	v_mov_b32_e32 v143, v24
	v_mov_b32_e32 v144, v24
	v_mov_b32_e32 v145, v24
	v_mov_b32_e32 v146, v24
	v_mov_b32_e32 v147, v24
	v_mov_b32_e32 v76, v24
	v_mov_b32_e32 v77, v24
	v_mov_b32_e32 v78, v24
	v_mov_b32_e32 v79, v24
	v_mov_b32_e32 v72, v24
	v_mov_b32_e32 v73, v24
	v_mov_b32_e32 v74, v24
	v_mov_b32_e32 v75, v24
	v_mov_b32_e32 v60, v24
	v_mov_b32_e32 v61, v24
	v_mov_b32_e32 v62, v24
	v_mov_b32_e32 v63, v24
	v_mov_b32_e32 v148, v24
	v_mov_b32_e32 v149, v24
	v_mov_b32_e32 v150, v24
	v_mov_b32_e32 v151, v24
	s_waitcnt vmcnt(12)
	s_barrier
	s_mov_b32 s30, 0
	v_add_u32_e32 v248, s30, v155
	v_add_u32_e32 v249, s30, v160
	ds_read_b128 v[186:189], v248
	ds_read_b128 v[212:215], v249 offset:8192
	ds_read_b128 v[190:193], v248 offset:1024
	ds_read_b128 v[216:219], v249 offset:9216
	ds_read_b128 v[194:197], v248 offset:2048
	ds_read_b128 v[220:223], v249 offset:10240
	ds_read_b128 v[208:211], v248 offset:3072
	ds_read_b128 v[224:227], v249 offset:11264
	ds_read_b128 v[228:231], v249 offset:12288
	ds_read_b128 v[232:235], v249 offset:13312
	ds_read_b128 v[236:239], v249 offset:14336
	ds_read_b128 v[240:243], v249 offset:15360
	s_add_u32 s30, s30, 24576
	s_cmp_eq_u32 s30, 73728
	s_cselect_b32 s30, 0, s30
	s_waitcnt vmcnt(6)
	s_waitcnt lgkmcnt(0)
	s_barrier
	s_mov_b32 s31, 14
.Lgm0_loop:
	v_add_u32_e32 v248, s30, v155
	v_add_u32_e32 v249, s30, v160
	v_mfma_f32_16x16x32_bf16 v[128:131], v[212:215], v[186:189], v[128:131]
	ds_read_b128 v[0:3], v248
	v_mfma_f32_16x16x32_bf16 v[96:99], v[212:215], v[190:193], v[96:99]
	ds_read_b128 v[16:19], v249 offset:8192
	v_mfma_f32_16x16x32_bf16 v[108:111], v[212:215], v[194:197], v[108:111]
	ds_read_b128 v[4:7], v248 offset:1024
	v_mfma_f32_16x16x32_bf16 v[132:135], v[212:215], v[208:211], v[132:135]
	ds_read_b128 v[20:23], v249 offset:9216
	v_mfma_f32_16x16x32_bf16 v[116:119], v[216:219], v[186:189], v[116:119]
	ds_read_b128 v[8:11], v248 offset:2048
	v_mfma_f32_16x16x32_bf16 v[92:95], v[216:219], v[190:193], v[92:95]
	ds_read_b128 v[162:165], v249 offset:10240
	v_mfma_f32_16x16x32_bf16 v[112:115], v[216:219], v[194:197], v[112:115]
	ds_read_b128 v[12:15], v248 offset:3072
	v_mfma_f32_16x16x32_bf16 v[136:139], v[216:219], v[208:211], v[136:139]
	ds_read_b128 v[166:169], v249 offset:11264
	v_mfma_f32_16x16x32_bf16 v[104:107], v[220:223], v[186:189], v[104:107]
	ds_read_b128 v[170:173], v249 offset:12288
	v_mfma_f32_16x16x32_bf16 v[88:91], v[220:223], v[190:193], v[88:91]
	ds_read_b128 v[174:177], v249 offset:13312
	v_mfma_f32_16x16x32_bf16 v[120:123], v[220:223], v[194:197], v[120:123]
	ds_read_b128 v[178:181], v249 offset:14336
	v_mfma_f32_16x16x32_bf16 v[140:143], v[220:223], v[208:211], v[140:143]
	ds_read_b128 v[182:185], v249 offset:15360
	s_add_u32 m0, s25, s24
	v_mfma_f32_16x16x32_bf16 v[100:103], v[224:227], v[186:189], v[100:103]
	global_load_lds_dwordx4 v244, s[26:27]
	v_mfma_f32_16x16x32_bf16 v[84:87], v[224:227], v[190:193], v[84:87]
	v_mfma_f32_16x16x32_bf16 v[124:127], v[224:227], v[194:197], v[124:127]
	s_add_u32 m0, m0, 0x1000
	v_mfma_f32_16x16x32_bf16 v[144:147], v[224:227], v[208:211], v[144:147]
	global_load_lds_dwordx4 v245, s[26:27]
	v_mfma_f32_16x16x32_bf16 v[52:55], v[228:231], v[186:189], v[52:55]
	v_mfma_f32_16x16x32_bf16 v[36:39], v[228:231], v[190:193], v[36:39]
	s_add_u32 m0, m0, 0x1000
	v_mfma_f32_16x16x32_bf16 v[64:67], v[228:231], v[194:197], v[64:67]
	global_load_lds_dwordx4 v156, s[28:29]
	v_mfma_f32_16x16x32_bf16 v[76:79], v[228:231], v[208:211], v[76:79]
	v_mfma_f32_16x16x32_bf16 v[48:51], v[232:235], v[186:189], v[48:51]
	s_add_u32 m0, m0, 0x1000
	v_mfma_f32_16x16x32_bf16 v[32:35], v[232:235], v[190:193], v[32:35]
	global_load_lds_dwordx4 v157, s[28:29]
	v_mfma_f32_16x16x32_bf16 v[68:71], v[232:235], v[194:197], v[68:71]
	v_mfma_f32_16x16x32_bf16 v[72:75], v[232:235], v[208:211], v[72:75]
	s_add_u32 m0, m0, 0x1000
	v_mfma_f32_16x16x32_bf16 v[44:47], v[236:239], v[186:189], v[44:47]
	global_load_lds_dwordx4 v158, s[28:29]
	v_mfma_f32_16x16x32_bf16 v[28:31], v[236:239], v[190:193], v[28:31]
	v_mfma_f32_16x16x32_bf16 v[80:83], v[236:239], v[194:197], v[80:83]
	s_add_u32 m0, m0, 0x1000
	v_mfma_f32_16x16x32_bf16 v[60:63], v[236:239], v[208:211], v[60:63]
	global_load_lds_dwordx4 v159, s[28:29]
	v_mfma_f32_16x16x32_bf16 v[40:43], v[240:243], v[186:189], v[40:43]
	v_mfma_f32_16x16x32_bf16 v[24:27], v[240:243], v[190:193], v[24:27]
	v_mfma_f32_16x16x32_bf16 v[56:59], v[240:243], v[194:197], v[56:59]
	v_mfma_f32_16x16x32_bf16 v[148:151], v[240:243], v[208:211], v[148:151]
	s_add_u32 s26, s26, 64
	s_addc_u32 s27, s27, 0
	s_add_u32 s28, s28, 0x40000
	s_addc_u32 s29, s29, 0
	s_add_u32 s25, s25, 24576
	s_cmp_eq_u32 s25, 73728
	s_cselect_b32 s25, 0, s25
	s_add_u32 s30, s30, 24576
	s_cmp_eq_u32 s30, 73728
	s_cselect_b32 s30, 0, s30
	s_waitcnt vmcnt(6)
	s_waitcnt lgkmcnt(0)
	s_barrier
	v_add_u32_e32 v248, s30, v155
	v_add_u32_e32 v249, s30, v160
	v_mfma_f32_16x16x32_bf16 v[128:131], v[16:19], v[0:3], v[128:131]
	ds_read_b128 v[186:189], v248
	v_mfma_f32_16x16x32_bf16 v[96:99], v[16:19], v[4:7], v[96:99]
	ds_read_b128 v[212:215], v249 offset:8192
	v_mfma_f32_16x16x32_bf16 v[108:111], v[16:19], v[8:11], v[108:111]
	ds_read_b128 v[190:193], v248 offset:1024
	v_mfma_f32_16x16x32_bf16 v[132:135], v[16:19], v[12:15], v[132:135]
	ds_read_b128 v[216:219], v249 offset:9216
	v_mfma_f32_16x16x32_bf16 v[116:119], v[20:23], v[0:3], v[116:119]
	ds_read_b128 v[194:197], v248 offset:2048
	v_mfma_f32_16x16x32_bf16 v[92:95], v[20:23], v[4:7], v[92:95]
	ds_read_b128 v[220:223], v249 offset:10240
	v_mfma_f32_16x16x32_bf16 v[112:115], v[20:23], v[8:11], v[112:115]
	ds_read_b128 v[208:211], v248 offset:3072
	v_mfma_f32_16x16x32_bf16 v[136:139], v[20:23], v[12:15], v[136:139]
	ds_read_b128 v[224:227], v249 offset:11264
	v_mfma_f32_16x16x32_bf16 v[104:107], v[162:165], v[0:3], v[104:107]
	ds_read_b128 v[228:231], v249 offset:12288
	v_mfma_f32_16x16x32_bf16 v[88:91], v[162:165], v[4:7], v[88:91]
	ds_read_b128 v[232:235], v249 offset:13312
	v_mfma_f32_16x16x32_bf16 v[120:123], v[162:165], v[8:11], v[120:123]
	ds_read_b128 v[236:239], v249 offset:14336
	v_mfma_f32_16x16x32_bf16 v[140:143], v[162:165], v[12:15], v[140:143]
	ds_read_b128 v[240:243], v249 offset:15360
	s_add_u32 m0, s25, s24
	v_mfma_f32_16x16x32_bf16 v[100:103], v[166:169], v[0:3], v[100:103]
	global_load_lds_dwordx4 v244, s[26:27]
	v_mfma_f32_16x16x32_bf16 v[84:87], v[166:169], v[4:7], v[84:87]
	v_mfma_f32_16x16x32_bf16 v[124:127], v[166:169], v[8:11], v[124:127]
	s_add_u32 m0, m0, 0x1000
	v_mfma_f32_16x16x32_bf16 v[144:147], v[166:169], v[12:15], v[144:147]
	global_load_lds_dwordx4 v245, s[26:27]
	v_mfma_f32_16x16x32_bf16 v[52:55], v[170:173], v[0:3], v[52:55]
	v_mfma_f32_16x16x32_bf16 v[36:39], v[170:173], v[4:7], v[36:39]
	s_add_u32 m0, m0, 0x1000
	v_mfma_f32_16x16x32_bf16 v[64:67], v[170:173], v[8:11], v[64:67]
	global_load_lds_dwordx4 v156, s[28:29]
	v_mfma_f32_16x16x32_bf16 v[76:79], v[170:173], v[12:15], v[76:79]
	v_mfma_f32_16x16x32_bf16 v[48:51], v[174:177], v[0:3], v[48:51]
	s_add_u32 m0, m0, 0x1000
	v_mfma_f32_16x16x32_bf16 v[32:35], v[174:177], v[4:7], v[32:35]
	global_load_lds_dwordx4 v157, s[28:29]
	v_mfma_f32_16x16x32_bf16 v[68:71], v[174:177], v[8:11], v[68:71]
	v_mfma_f32_16x16x32_bf16 v[72:75], v[174:177], v[12:15], v[72:75]
	s_add_u32 m0, m0, 0x1000
	v_mfma_f32_16x16x32_bf16 v[44:47], v[178:181], v[0:3], v[44:47]
	global_load_lds_dwordx4 v158, s[28:29]
	v_mfma_f32_16x16x32_bf16 v[28:31], v[178:181], v[4:7], v[28:31]
	v_mfma_f32_16x16x32_bf16 v[80:83], v[178:181], v[8:11], v[80:83]
	s_add_u32 m0, m0, 0x1000
	v_mfma_f32_16x16x32_bf16 v[60:63], v[178:181], v[12:15], v[60:63]
	global_load_lds_dwordx4 v159, s[28:29]
	v_mfma_f32_16x16x32_bf16 v[40:43], v[182:185], v[0:3], v[40:43]
	v_mfma_f32_16x16x32_bf16 v[24:27], v[182:185], v[4:7], v[24:27]
	v_mfma_f32_16x16x32_bf16 v[56:59], v[182:185], v[8:11], v[56:59]
	v_mfma_f32_16x16x32_bf16 v[148:151], v[182:185], v[12:15], v[148:151]
	s_add_u32 s26, s26, 64
	s_addc_u32 s27, s27, 0
	s_add_u32 s28, s28, 0x40000
	s_addc_u32 s29, s29, 0
	s_add_u32 s25, s25, 24576
	s_cmp_eq_u32 s25, 73728
	s_cselect_b32 s25, 0, s25
	s_add_u32 s30, s30, 24576
	s_cmp_eq_u32 s30, 73728
	s_cselect_b32 s30, 0, s30
	s_waitcnt vmcnt(6)
	s_waitcnt lgkmcnt(0)
	s_barrier
	s_sub_u32 s31, s31, 1
	s_cmp_lg_u32 s31, 0
	s_cbranch_scc1 .Lgm0_loop
	v_add_u32_e32 v248, s30, v155
	v_add_u32_e32 v249, s30, v160
	v_mfma_f32_16x16x32_bf16 v[128:131], v[212:215], v[186:189], v[128:131]
	ds_read_b128 v[0:3], v248
	v_mfma_f32_16x16x32_bf16 v[96:99], v[212:215], v[190:193], v[96:99]
	ds_read_b128 v[16:19], v249 offset:8192
	v_mfma_f32_16x16x32_bf16 v[108:111], v[212:215], v[194:197], v[108:111]
	ds_read_b128 v[4:7], v248 offset:1024
	v_mfma_f32_16x16x32_bf16 v[132:135], v[212:215], v[208:211], v[132:135]
	ds_read_b128 v[20:23], v249 offset:9216
	v_mfma_f32_16x16x32_bf16 v[116:119], v[216:219], v[186:189], v[116:119]
	ds_read_b128 v[8:11], v248 offset:2048
	v_mfma_f32_16x16x32_bf16 v[92:95], v[216:219], v[190:193], v[92:95]
	ds_read_b128 v[162:165], v249 offset:10240
	v_mfma_f32_16x16x32_bf16 v[112:115], v[216:219], v[194:197], v[112:115]
	ds_read_b128 v[12:15], v248 offset:3072
	v_mfma_f32_16x16x32_bf16 v[136:139], v[216:219], v[208:211], v[136:139]
	ds_read_b128 v[166:169], v249 offset:11264
	v_mfma_f32_16x16x32_bf16 v[104:107], v[220:223], v[186:189], v[104:107]
	ds_read_b128 v[170:173], v249 offset:12288
	v_mfma_f32_16x16x32_bf16 v[88:91], v[220:223], v[190:193], v[88:91]
	ds_read_b128 v[174:177], v249 offset:13312
	v_mfma_f32_16x16x32_bf16 v[120:123], v[220:223], v[194:197], v[120:123]
	ds_read_b128 v[178:181], v249 offset:14336
	v_mfma_f32_16x16x32_bf16 v[140:143], v[220:223], v[208:211], v[140:143]
	ds_read_b128 v[182:185], v249 offset:15360
	s_add_u32 m0, s25, s24
	v_mfma_f32_16x16x32_bf16 v[100:103], v[224:227], v[186:189], v[100:103]
	global_load_lds_dwordx4 v244, s[26:27]
	v_mfma_f32_16x16x32_bf16 v[84:87], v[224:227], v[190:193], v[84:87]
	v_mfma_f32_16x16x32_bf16 v[124:127], v[224:227], v[194:197], v[124:127]
	s_add_u32 m0, m0, 0x1000
	v_mfma_f32_16x16x32_bf16 v[144:147], v[224:227], v[208:211], v[144:147]
	global_load_lds_dwordx4 v245, s[26:27]
	v_mfma_f32_16x16x32_bf16 v[52:55], v[228:231], v[186:189], v[52:55]
	v_mfma_f32_16x16x32_bf16 v[36:39], v[228:231], v[190:193], v[36:39]
	s_add_u32 m0, m0, 0x1000
	v_mfma_f32_16x16x32_bf16 v[64:67], v[228:231], v[194:197], v[64:67]
	global_load_lds_dwordx4 v156, s[28:29]
	v_mfma_f32_16x16x32_bf16 v[76:79], v[228:231], v[208:211], v[76:79]
	v_mfma_f32_16x16x32_bf16 v[48:51], v[232:235], v[186:189], v[48:51]
	s_add_u32 m0, m0, 0x1000
	v_mfma_f32_16x16x32_bf16 v[32:35], v[232:235], v[190:193], v[32:35]
	global_load_lds_dwordx4 v157, s[28:29]
	v_mfma_f32_16x16x32_bf16 v[68:71], v[232:235], v[194:197], v[68:71]
	v_mfma_f32_16x16x32_bf16 v[72:75], v[232:235], v[208:211], v[72:75]
	s_add_u32 m0, m0, 0x1000
	v_mfma_f32_16x16x32_bf16 v[44:47], v[236:239], v[186:189], v[44:47]
	global_load_lds_dwordx4 v158, s[28:29]
	v_mfma_f32_16x16x32_bf16 v[28:31], v[236:239], v[190:193], v[28:31]
	v_mfma_f32_16x16x32_bf16 v[80:83], v[236:239], v[194:197], v[80:83]
	s_add_u32 m0, m0, 0x1000
	v_mfma_f32_16x16x32_bf16 v[60:63], v[236:239], v[208:211], v[60:63]
	global_load_lds_dwordx4 v159, s[28:29]
	v_mfma_f32_16x16x32_bf16 v[40:43], v[240:243], v[186:189], v[40:43]
	v_mfma_f32_16x16x32_bf16 v[24:27], v[240:243], v[190:193], v[24:27]
	v_mfma_f32_16x16x32_bf16 v[56:59], v[240:243], v[194:197], v[56:59]
	v_mfma_f32_16x16x32_bf16 v[148:151], v[240:243], v[208:211], v[148:151]
	s_add_u32 s26, s26, 64
	s_addc_u32 s27, s27, 0
	s_add_u32 s28, s28, 0x40000
	s_addc_u32 s29, s29, 0
	s_add_u32 s25, s25, 24576
	s_cmp_eq_u32 s25, 73728
	s_cselect_b32 s25, 0, s25
	s_add_u32 s30, s30, 24576
	s_cmp_eq_u32 s30, 73728
	s_cselect_b32 s30, 0, s30
	s_waitcnt vmcnt(6)
	s_waitcnt lgkmcnt(0)
	s_barrier
	v_add_u32_e32 v248, s30, v155
	v_add_u32_e32 v249, s30, v160
	v_mfma_f32_16x16x32_bf16 v[128:131], v[16:19], v[0:3], v[128:131]
	ds_read_b128 v[186:189], v248
	v_mfma_f32_16x16x32_bf16 v[96:99], v[16:19], v[4:7], v[96:99]
	ds_read_b128 v[212:215], v249 offset:8192
	v_mfma_f32_16x16x32_bf16 v[108:111], v[16:19], v[8:11], v[108:111]
	ds_read_b128 v[190:193], v248 offset:1024
	v_mfma_f32_16x16x32_bf16 v[132:135], v[16:19], v[12:15], v[132:135]
	ds_read_b128 v[216:219], v249 offset:9216
	v_mfma_f32_16x16x32_bf16 v[116:119], v[20:23], v[0:3], v[116:119]
	ds_read_b128 v[194:197], v248 offset:2048
	v_mfma_f32_16x16x32_bf16 v[92:95], v[20:23], v[4:7], v[92:95]
	ds_read_b128 v[220:223], v249 offset:10240
	v_mfma_f32_16x16x32_bf16 v[112:115], v[20:23], v[8:11], v[112:115]
	ds_read_b128 v[208:211], v248 offset:3072
	v_mfma_f32_16x16x32_bf16 v[136:139], v[20:23], v[12:15], v[136:139]
	ds_read_b128 v[224:227], v249 offset:11264
	v_mfma_f32_16x16x32_bf16 v[104:107], v[162:165], v[0:3], v[104:107]
	ds_read_b128 v[228:231], v249 offset:12288
	v_mfma_f32_16x16x32_bf16 v[88:91], v[162:165], v[4:7], v[88:91]
	ds_read_b128 v[232:235], v249 offset:13312
	v_mfma_f32_16x16x32_bf16 v[120:123], v[162:165], v[8:11], v[120:123]
	ds_read_b128 v[236:239], v249 offset:14336
	v_mfma_f32_16x16x32_bf16 v[140:143], v[162:165], v[12:15], v[140:143]
	ds_read_b128 v[240:243], v249 offset:15360
	v_mfma_f32_16x16x32_bf16 v[100:103], v[166:169], v[0:3], v[100:103]
	v_mfma_f32_16x16x32_bf16 v[84:87], v[166:169], v[4:7], v[84:87]
	v_mfma_f32_16x16x32_bf16 v[124:127], v[166:169], v[8:11], v[124:127]
	v_mfma_f32_16x16x32_bf16 v[144:147], v[166:169], v[12:15], v[144:147]
	v_mfma_f32_16x16x32_bf16 v[52:55], v[170:173], v[0:3], v[52:55]
	v_mfma_f32_16x16x32_bf16 v[36:39], v[170:173], v[4:7], v[36:39]
	v_mfma_f32_16x16x32_bf16 v[64:67], v[170:173], v[8:11], v[64:67]
	v_mfma_f32_16x16x32_bf16 v[76:79], v[170:173], v[12:15], v[76:79]
	v_mfma_f32_16x16x32_bf16 v[48:51], v[174:177], v[0:3], v[48:51]
	v_mfma_f32_16x16x32_bf16 v[32:35], v[174:177], v[4:7], v[32:35]
	v_mfma_f32_16x16x32_bf16 v[68:71], v[174:177], v[8:11], v[68:71]
	v_mfma_f32_16x16x32_bf16 v[72:75], v[174:177], v[12:15], v[72:75]
	v_mfma_f32_16x16x32_bf16 v[44:47], v[178:181], v[0:3], v[44:47]
	v_mfma_f32_16x16x32_bf16 v[28:31], v[178:181], v[4:7], v[28:31]
	v_mfma_f32_16x16x32_bf16 v[80:83], v[178:181], v[8:11], v[80:83]
	v_mfma_f32_16x16x32_bf16 v[60:63], v[178:181], v[12:15], v[60:63]
	v_mfma_f32_16x16x32_bf16 v[40:43], v[182:185], v[0:3], v[40:43]
	v_mfma_f32_16x16x32_bf16 v[24:27], v[182:185], v[4:7], v[24:27]
	v_mfma_f32_16x16x32_bf16 v[56:59], v[182:185], v[8:11], v[56:59]
	v_mfma_f32_16x16x32_bf16 v[148:151], v[182:185], v[12:15], v[148:151]
	s_add_u32 s30, s30, 24576
	s_cmp_eq_u32 s30, 73728
	s_cselect_b32 s30, 0, s30
	s_waitcnt vmcnt(0)
	s_waitcnt lgkmcnt(0)
	s_barrier
	v_add_u32_e32 v248, s30, v155
	v_add_u32_e32 v249, s30, v160
	v_mfma_f32_16x16x32_bf16 v[128:131], v[212:215], v[186:189], v[128:131]
	ds_read_b128 v[0:3], v248
	v_mfma_f32_16x16x32_bf16 v[96:99], v[212:215], v[190:193], v[96:99]
	ds_read_b128 v[16:19], v249 offset:8192
	v_mfma_f32_16x16x32_bf16 v[108:111], v[212:215], v[194:197], v[108:111]
	ds_read_b128 v[4:7], v248 offset:1024
	v_mfma_f32_16x16x32_bf16 v[132:135], v[212:215], v[208:211], v[132:135]
	ds_read_b128 v[20:23], v249 offset:9216
	v_mfma_f32_16x16x32_bf16 v[116:119], v[216:219], v[186:189], v[116:119]
	ds_read_b128 v[8:11], v248 offset:2048
	v_mfma_f32_16x16x32_bf16 v[92:95], v[216:219], v[190:193], v[92:95]
	ds_read_b128 v[162:165], v249 offset:10240
	v_mfma_f32_16x16x32_bf16 v[112:115], v[216:219], v[194:197], v[112:115]
	ds_read_b128 v[12:15], v248 offset:3072
	v_mfma_f32_16x16x32_bf16 v[136:139], v[216:219], v[208:211], v[136:139]
	ds_read_b128 v[166:169], v249 offset:11264
	v_mfma_f32_16x16x32_bf16 v[104:107], v[220:223], v[186:189], v[104:107]
	ds_read_b128 v[170:173], v249 offset:12288
	v_mfma_f32_16x16x32_bf16 v[88:91], v[220:223], v[190:193], v[88:91]
	ds_read_b128 v[174:177], v249 offset:13312
	v_mfma_f32_16x16x32_bf16 v[120:123], v[220:223], v[194:197], v[120:123]
	ds_read_b128 v[178:181], v249 offset:14336
	v_mfma_f32_16x16x32_bf16 v[140:143], v[220:223], v[208:211], v[140:143]
	ds_read_b128 v[182:185], v249 offset:15360
	v_mfma_f32_16x16x32_bf16 v[100:103], v[224:227], v[186:189], v[100:103]
	v_mfma_f32_16x16x32_bf16 v[84:87], v[224:227], v[190:193], v[84:87]
	v_mfma_f32_16x16x32_bf16 v[124:127], v[224:227], v[194:197], v[124:127]
	v_mfma_f32_16x16x32_bf16 v[144:147], v[224:227], v[208:211], v[144:147]
	v_mfma_f32_16x16x32_bf16 v[52:55], v[228:231], v[186:189], v[52:55]
	v_mfma_f32_16x16x32_bf16 v[36:39], v[228:231], v[190:193], v[36:39]
	v_mfma_f32_16x16x32_bf16 v[64:67], v[228:231], v[194:197], v[64:67]
	v_mfma_f32_16x16x32_bf16 v[76:79], v[228:231], v[208:211], v[76:79]
	v_mfma_f32_16x16x32_bf16 v[48:51], v[232:235], v[186:189], v[48:51]
	v_mfma_f32_16x16x32_bf16 v[32:35], v[232:235], v[190:193], v[32:35]
	v_mfma_f32_16x16x32_bf16 v[68:71], v[232:235], v[194:197], v[68:71]
	v_mfma_f32_16x16x32_bf16 v[72:75], v[232:235], v[208:211], v[72:75]
	v_mfma_f32_16x16x32_bf16 v[44:47], v[236:239], v[186:189], v[44:47]
	v_mfma_f32_16x16x32_bf16 v[28:31], v[236:239], v[190:193], v[28:31]
	v_mfma_f32_16x16x32_bf16 v[80:83], v[236:239], v[194:197], v[80:83]
	v_mfma_f32_16x16x32_bf16 v[60:63], v[236:239], v[208:211], v[60:63]
	v_mfma_f32_16x16x32_bf16 v[40:43], v[240:243], v[186:189], v[40:43]
	v_mfma_f32_16x16x32_bf16 v[24:27], v[240:243], v[190:193], v[24:27]
	v_mfma_f32_16x16x32_bf16 v[56:59], v[240:243], v[194:197], v[56:59]
	v_mfma_f32_16x16x32_bf16 v[148:151], v[240:243], v[208:211], v[148:151]
	s_add_u32 s30, s30, 24576
	s_cmp_eq_u32 s30, 73728
	s_cselect_b32 s30, 0, s30
	s_waitcnt lgkmcnt(0)
	s_barrier
	v_mfma_f32_16x16x32_bf16 v[128:131], v[16:19], v[0:3], v[128:131]
	v_mfma_f32_16x16x32_bf16 v[96:99], v[16:19], v[4:7], v[96:99]
	v_mfma_f32_16x16x32_bf16 v[108:111], v[16:19], v[8:11], v[108:111]
	v_mfma_f32_16x16x32_bf16 v[132:135], v[16:19], v[12:15], v[132:135]
	v_mfma_f32_16x16x32_bf16 v[116:119], v[20:23], v[0:3], v[116:119]
	v_mfma_f32_16x16x32_bf16 v[92:95], v[20:23], v[4:7], v[92:95]
	v_mfma_f32_16x16x32_bf16 v[112:115], v[20:23], v[8:11], v[112:115]
	v_mfma_f32_16x16x32_bf16 v[136:139], v[20:23], v[12:15], v[136:139]
	v_mfma_f32_16x16x32_bf16 v[104:107], v[162:165], v[0:3], v[104:107]
	v_mfma_f32_16x16x32_bf16 v[88:91], v[162:165], v[4:7], v[88:91]
	v_mfma_f32_16x16x32_bf16 v[120:123], v[162:165], v[8:11], v[120:123]
	v_mfma_f32_16x16x32_bf16 v[140:143], v[162:165], v[12:15], v[140:143]
	v_mfma_f32_16x16x32_bf16 v[100:103], v[166:169], v[0:3], v[100:103]
	v_mfma_f32_16x16x32_bf16 v[84:87], v[166:169], v[4:7], v[84:87]
	v_mfma_f32_16x16x32_bf16 v[124:127], v[166:169], v[8:11], v[124:127]
	v_mfma_f32_16x16x32_bf16 v[144:147], v[166:169], v[12:15], v[144:147]
	v_mfma_f32_16x16x32_bf16 v[52:55], v[170:173], v[0:3], v[52:55]
	v_mfma_f32_16x16x32_bf16 v[36:39], v[170:173], v[4:7], v[36:39]
	v_mfma_f32_16x16x32_bf16 v[64:67], v[170:173], v[8:11], v[64:67]
	v_mfma_f32_16x16x32_bf16 v[76:79], v[170:173], v[12:15], v[76:79]
	v_mfma_f32_16x16x32_bf16 v[48:51], v[174:177], v[0:3], v[48:51]
	v_mfma_f32_16x16x32_bf16 v[32:35], v[174:177], v[4:7], v[32:35]
	v_mfma_f32_16x16x32_bf16 v[68:71], v[174:177], v[8:11], v[68:71]
	v_mfma_f32_16x16x32_bf16 v[72:75], v[174:177], v[12:15], v[72:75]
	v_mfma_f32_16x16x32_bf16 v[44:47], v[178:181], v[0:3], v[44:47]
	v_mfma_f32_16x16x32_bf16 v[28:31], v[178:181], v[4:7], v[28:31]
	v_mfma_f32_16x16x32_bf16 v[80:83], v[178:181], v[8:11], v[80:83]
	v_mfma_f32_16x16x32_bf16 v[60:63], v[178:181], v[12:15], v[60:63]
	v_mfma_f32_16x16x32_bf16 v[40:43], v[182:185], v[0:3], v[40:43]
	v_mfma_f32_16x16x32_bf16 v[24:27], v[182:185], v[4:7], v[24:27]
	v_mfma_f32_16x16x32_bf16 v[56:59], v[182:185], v[8:11], v[56:59]
	v_mfma_f32_16x16x32_bf16 v[148:151], v[182:185], v[12:15], v[148:151]
	s_add_i32 s12, s12, s6
	s_add_i32 s11, s11, s9
	s_add_i32 s10, s10, s6
	s_cmpk_gt_u32 s12, 0x1ff
	s_cselect_b32 s23, 1, 0
	v_mov_b32 v250, v198
	s_nop 0
	v_and_b32_e32 v251, 15, v250
	v_bfe_u32 v156, v250, 4, 2
	v_bfe_u32 v157, v250, 6, 1
	v_bfe_u32 v158, v250, 7, 1
	v_lshl_add_u32 v158, v158, 6, s14
	v_add_u32_e32 v158, v158, v251
	v_lshl_add_u32 v157, v157, 7, s13
	v_lshl_add_u32 v159, v156, 2, v157
	v_lshlrev_b32_e32 v230, 6, v158
	v_lshlrev_b32_e32 v161, 1, v159
	v_lshl_add_u32 v228, v158, 13, v161
	v_and_b32_e32 v161, 1, v156
	v_mul_u32_u24_e32 v161, 24, v161
	v_add_u32_e32 v229, v228, v161
	s_mov_b32 s30, s92
	s_mov_b32 s31, s93
	global_load_dwordx4 v[0:3], v230, s[94:95]
	global_load_dwordx4 v[4:7], v230, s[94:95] offset:16
	global_load_dwordx4 v[8:11], v230, s[94:95] offset:32
	global_load_dwordx4 v[12:15], v230, s[94:95] offset:48
	global_load_dwordx4 v[16:19], v230, s[94:95] offset:1024
	global_load_dwordx4 v[20:23], v230, s[94:95] offset:1040
	global_load_dwordx4 v[162:165], v230, s[94:95] offset:1056
	global_load_dwordx4 v[166:169], v230, s[94:95] offset:1072
	global_load_dwordx4 v[170:173], v230, s[94:95] offset:2048
	global_load_dwordx4 v[174:177], v230, s[94:95] offset:2064
	global_load_dwordx4 v[178:181], v230, s[94:95] offset:2080
	global_load_dwordx4 v[182:185], v230, s[94:95] offset:2096
	global_load_dwordx4 v[186:189], v230, s[94:95] offset:3072
	global_load_dwordx4 v[190:193], v230, s[94:95] offset:3088
	global_load_dwordx4 v[194:197], v230, s[94:95] offset:3104
	global_load_dwordx4 v[208:211], v230, s[94:95] offset:3120
	s_waitcnt vmcnt(12)
	v_add_f32_e32 v231, v0, v1
	v_add_f32_e32 v248, v2, v3
	v_add_f32_e32 v231, v231, v248
	v_add_f32_e32 v249, v4, v5
	v_add_f32_e32 v248, v6, v7
	v_add_f32_e32 v249, v249, v248
	v_add_f32_e32 v231, v231, v249
	v_add_f32_e32 v249, v8, v9
	v_add_f32_e32 v248, v10, v11
	v_add_f32_e32 v249, v249, v248
	v_add_f32_e32 v231, v231, v249
	v_add_f32_e32 v249, v12, v13
	v_add_f32_e32 v248, v14, v15
	v_add_f32_e32 v249, v249, v248
	v_add_f32_e32 v231, v231, v249
	v_fmamk_f32 v231, v231, 0x3a800000, v199
	v_cmp_gt_f32_e32 vcc, s73, v231
	v_mul_f32_e32 v248, 0x4b800000, v231
	s_nop 0
	v_cndmask_b32_e32 v231, v231, v248, vcc
	v_rsq_f32_e32 v231, v231
	s_nop 0
	v_mul_f32_e32 v248, 0x45800000, v231
	v_cndmask_b32_e32 v231, v231, v248, vcc
	v_mul_f32_e32 v212, v128, v231
	v_mul_f32_e32 v249, v129, v231
	v_mul_f32_e32 v213, v130, v231
	v_mul_f32_e32 v248, v131, v231
	v_max_f32_e32 v212, 0, v212
	v_max_f32_e32 v249, 0, v249
	v_max_f32_e32 v213, 0, v213
	v_max_f32_e32 v248, 0, v248
	v_mul_f32_e32 v212, v212, v212
	v_mul_f32_e32 v249, v249, v249
	v_mul_f32_e32 v213, v213, v213
	v_mul_f32_e32 v248, v248, v248
	v_cvt_pk_bf16_f32 v212, v212, v249
	v_cvt_pk_bf16_f32 v213, v213, v248
	v_mul_f32_e32 v214, v116, v231
	v_mul_f32_e32 v249, v117, v231
	v_mul_f32_e32 v215, v118, v231
	v_mul_f32_e32 v248, v119, v231
	v_max_f32_e32 v214, 0, v214
	v_max_f32_e32 v249, 0, v249
	v_max_f32_e32 v215, 0, v215
	v_max_f32_e32 v248, 0, v248
	v_mul_f32_e32 v214, v214, v214
	v_mul_f32_e32 v249, v249, v249
	v_mul_f32_e32 v215, v215, v215
	v_mul_f32_e32 v248, v248, v248
	v_cvt_pk_bf16_f32 v214, v214, v249
	v_cvt_pk_bf16_f32 v215, v215, v248
	s_nop 1
	v_permlane16_swap_b32_e32 v212, v214
	v_permlane16_swap_b32_e32 v213, v215
	global_store_dwordx4 v229, v[212:215], s[30:31]
	v_mul_f32_e32 v216, v104, v231
	v_mul_f32_e32 v249, v105, v231
	v_mul_f32_e32 v217, v106, v231
	v_mul_f32_e32 v248, v107, v231
	v_max_f32_e32 v216, 0, v216
	v_max_f32_e32 v249, 0, v249
	v_max_f32_e32 v217, 0, v217
	v_max_f32_e32 v248, 0, v248
	v_mul_f32_e32 v216, v216, v216
	v_mul_f32_e32 v249, v249, v249
	v_mul_f32_e32 v217, v217, v217
	v_mul_f32_e32 v248, v248, v248
	v_cvt_pk_bf16_f32 v216, v216, v249
	v_cvt_pk_bf16_f32 v217, v217, v248
	v_mul_f32_e32 v218, v100, v231
	v_mul_f32_e32 v249, v101, v231
	v_mul_f32_e32 v219, v102, v231
	v_mul_f32_e32 v248, v103, v231
	v_max_f32_e32 v218, 0, v218
	v_max_f32_e32 v249, 0, v249
	v_max_f32_e32 v219, 0, v219
	v_max_f32_e32 v248, 0, v248
	v_mul_f32_e32 v218, v218, v218
	v_mul_f32_e32 v249, v249, v249
	v_mul_f32_e32 v219, v219, v219
	v_mul_f32_e32 v248, v248, v248
	v_cvt_pk_bf16_f32 v218, v218, v249
	v_cvt_pk_bf16_f32 v219, v219, v248
	s_nop 1
	v_permlane16_swap_b32_e32 v216, v218
	v_permlane16_swap_b32_e32 v217, v219
	global_store_dwordx4 v229, v[216:219], s[30:31] offset:64
	v_mul_f32_e32 v220, v52, v231
	v_mul_f32_e32 v249, v53, v231
	v_mul_f32_e32 v221, v54, v231
	v_mul_f32_e32 v248, v55, v231
	v_max_f32_e32 v220, 0, v220
	v_max_f32_e32 v249, 0, v249
	v_max_f32_e32 v221, 0, v221
	v_max_f32_e32 v248, 0, v248
	v_mul_f32_e32 v220, v220, v220
	v_mul_f32_e32 v249, v249, v249
	v_mul_f32_e32 v221, v221, v221
	v_mul_f32_e32 v248, v248, v248
	v_cvt_pk_bf16_f32 v220, v220, v249
	v_cvt_pk_bf16_f32 v221, v221, v248
	v_mul_f32_e32 v222, v48, v231
	v_mul_f32_e32 v249, v49, v231
	v_mul_f32_e32 v223, v50, v231
	v_mul_f32_e32 v248, v51, v231
	v_max_f32_e32 v222, 0, v222
	v_max_f32_e32 v249, 0, v249
	v_max_f32_e32 v223, 0, v223
	v_max_f32_e32 v248, 0, v248
	v_mul_f32_e32 v222, v222, v222
	v_mul_f32_e32 v249, v249, v249
	v_mul_f32_e32 v223, v223, v223
	v_mul_f32_e32 v248, v248, v248
	v_cvt_pk_bf16_f32 v222, v222, v249
	v_cvt_pk_bf16_f32 v223, v223, v248
	s_nop 1
	v_permlane16_swap_b32_e32 v220, v222
	v_permlane16_swap_b32_e32 v221, v223
	global_store_dwordx4 v229, v[220:223], s[30:31] offset:128
	v_mul_f32_e32 v224, v44, v231
	v_mul_f32_e32 v249, v45, v231
	v_mul_f32_e32 v225, v46, v231
	v_mul_f32_e32 v248, v47, v231
	v_max_f32_e32 v224, 0, v224
	v_max_f32_e32 v249, 0, v249
	v_max_f32_e32 v225, 0, v225
	v_max_f32_e32 v248, 0, v248
	v_mul_f32_e32 v224, v224, v224
	v_mul_f32_e32 v249, v249, v249
	v_mul_f32_e32 v225, v225, v225
	v_mul_f32_e32 v248, v248, v248
	v_cvt_pk_bf16_f32 v224, v224, v249
	v_cvt_pk_bf16_f32 v225, v225, v248
	v_mul_f32_e32 v226, v40, v231
	v_mul_f32_e32 v249, v41, v231
	v_mul_f32_e32 v227, v42, v231
	v_mul_f32_e32 v248, v43, v231
	v_max_f32_e32 v226, 0, v226
	v_max_f32_e32 v249, 0, v249
	v_max_f32_e32 v227, 0, v227
	v_max_f32_e32 v248, 0, v248
	v_mul_f32_e32 v226, v226, v226
	v_mul_f32_e32 v249, v249, v249
	v_mul_f32_e32 v227, v227, v227
	v_mul_f32_e32 v248, v248, v248
	v_cvt_pk_bf16_f32 v226, v226, v249
	v_cvt_pk_bf16_f32 v227, v227, v248
	s_nop 1
	v_permlane16_swap_b32_e32 v224, v226
	v_permlane16_swap_b32_e32 v225, v227
	global_store_dwordx4 v229, v[224:227], s[30:31] offset:192
	s_add_u32 s30, s30, 0x20000
	s_addc_u32 s31, s31, 0
	s_waitcnt vmcnt(12)
	v_add_f32_e32 v231, v16, v17
	v_add_f32_e32 v248, v18, v19
	v_add_f32_e32 v231, v231, v248
	v_add_f32_e32 v249, v20, v21
	v_add_f32_e32 v248, v22, v23
	v_add_f32_e32 v249, v249, v248
	v_add_f32_e32 v231, v231, v249
	v_add_f32_e32 v249, v162, v163
	v_add_f32_e32 v248, v164, v165
	v_add_f32_e32 v249, v249, v248
	v_add_f32_e32 v231, v231, v249
	v_add_f32_e32 v249, v166, v167
	v_add_f32_e32 v248, v168, v169
	v_add_f32_e32 v249, v249, v248
	v_add_f32_e32 v231, v231, v249
	v_fmamk_f32 v231, v231, 0x3a800000, v199
	v_cmp_gt_f32_e32 vcc, s73, v231
	v_mul_f32_e32 v248, 0x4b800000, v231
	s_nop 0
	v_cndmask_b32_e32 v231, v231, v248, vcc
	v_rsq_f32_e32 v231, v231
	s_nop 0
	v_mul_f32_e32 v248, 0x45800000, v231
	v_cndmask_b32_e32 v231, v231, v248, vcc
	v_mul_f32_e32 v212, v96, v231
	v_mul_f32_e32 v249, v97, v231
	v_mul_f32_e32 v213, v98, v231
	v_mul_f32_e32 v248, v99, v231
	v_max_f32_e32 v212, 0, v212
	v_max_f32_e32 v249, 0, v249
	v_max_f32_e32 v213, 0, v213
	v_max_f32_e32 v248, 0, v248
	v_mul_f32_e32 v212, v212, v212
	v_mul_f32_e32 v249, v249, v249
	v_mul_f32_e32 v213, v213, v213
	v_mul_f32_e32 v248, v248, v248
	v_cvt_pk_bf16_f32 v212, v212, v249
	v_cvt_pk_bf16_f32 v213, v213, v248
	v_mul_f32_e32 v214, v92, v231
	v_mul_f32_e32 v249, v93, v231
	v_mul_f32_e32 v215, v94, v231
	v_mul_f32_e32 v248, v95, v231
	v_max_f32_e32 v214, 0, v214
	v_max_f32_e32 v249, 0, v249
	v_max_f32_e32 v215, 0, v215
	v_max_f32_e32 v248, 0, v248
	v_mul_f32_e32 v214, v214, v214
	v_mul_f32_e32 v249, v249, v249
	v_mul_f32_e32 v215, v215, v215
	v_mul_f32_e32 v248, v248, v248
	v_cvt_pk_bf16_f32 v214, v214, v249
	v_cvt_pk_bf16_f32 v215, v215, v248
	s_nop 1
	v_permlane16_swap_b32_e32 v212, v214
	v_permlane16_swap_b32_e32 v213, v215
	global_store_dwordx4 v229, v[212:215], s[30:31]
	v_mul_f32_e32 v216, v88, v231
	v_mul_f32_e32 v249, v89, v231
	v_mul_f32_e32 v217, v90, v231
	v_mul_f32_e32 v248, v91, v231
	v_max_f32_e32 v216, 0, v216
	v_max_f32_e32 v249, 0, v249
	v_max_f32_e32 v217, 0, v217
	v_max_f32_e32 v248, 0, v248
	v_mul_f32_e32 v216, v216, v216
	v_mul_f32_e32 v249, v249, v249
	v_mul_f32_e32 v217, v217, v217
	v_mul_f32_e32 v248, v248, v248
	v_cvt_pk_bf16_f32 v216, v216, v249
	v_cvt_pk_bf16_f32 v217, v217, v248
	v_mul_f32_e32 v218, v84, v231
	v_mul_f32_e32 v249, v85, v231
	v_mul_f32_e32 v219, v86, v231
	v_mul_f32_e32 v248, v87, v231
	v_max_f32_e32 v218, 0, v218
	v_max_f32_e32 v249, 0, v249
	v_max_f32_e32 v219, 0, v219
	v_max_f32_e32 v248, 0, v248
	v_mul_f32_e32 v218, v218, v218
	v_mul_f32_e32 v249, v249, v249
	v_mul_f32_e32 v219, v219, v219
	v_mul_f32_e32 v248, v248, v248
	v_cvt_pk_bf16_f32 v218, v218, v249
	v_cvt_pk_bf16_f32 v219, v219, v248
	s_nop 1
	v_permlane16_swap_b32_e32 v216, v218
	v_permlane16_swap_b32_e32 v217, v219
	global_store_dwordx4 v229, v[216:219], s[30:31] offset:64
	v_mul_f32_e32 v220, v36, v231
	v_mul_f32_e32 v249, v37, v231
	v_mul_f32_e32 v221, v38, v231
	v_mul_f32_e32 v248, v39, v231
	v_max_f32_e32 v220, 0, v220
	v_max_f32_e32 v249, 0, v249
	v_max_f32_e32 v221, 0, v221
	v_max_f32_e32 v248, 0, v248
	v_mul_f32_e32 v220, v220, v220
	v_mul_f32_e32 v249, v249, v249
	v_mul_f32_e32 v221, v221, v221
	v_mul_f32_e32 v248, v248, v248
	v_cvt_pk_bf16_f32 v220, v220, v249
	v_cvt_pk_bf16_f32 v221, v221, v248
	v_mul_f32_e32 v222, v32, v231
	v_mul_f32_e32 v249, v33, v231
	v_mul_f32_e32 v223, v34, v231
	v_mul_f32_e32 v248, v35, v231
	v_max_f32_e32 v222, 0, v222
	v_max_f32_e32 v249, 0, v249
	v_max_f32_e32 v223, 0, v223
	v_max_f32_e32 v248, 0, v248
	v_mul_f32_e32 v222, v222, v222
	v_mul_f32_e32 v249, v249, v249
	v_mul_f32_e32 v223, v223, v223
	v_mul_f32_e32 v248, v248, v248
	v_cvt_pk_bf16_f32 v222, v222, v249
	v_cvt_pk_bf16_f32 v223, v223, v248
	s_nop 1
	v_permlane16_swap_b32_e32 v220, v222
	v_permlane16_swap_b32_e32 v221, v223
	global_store_dwordx4 v229, v[220:223], s[30:31] offset:128
	v_mul_f32_e32 v224, v28, v231
	v_mul_f32_e32 v249, v29, v231
	v_mul_f32_e32 v225, v30, v231
	v_mul_f32_e32 v248, v31, v231
	v_max_f32_e32 v224, 0, v224
	v_max_f32_e32 v249, 0, v249
	v_max_f32_e32 v225, 0, v225
	v_max_f32_e32 v248, 0, v248
	v_mul_f32_e32 v224, v224, v224
	v_mul_f32_e32 v249, v249, v249
	v_mul_f32_e32 v225, v225, v225
	v_mul_f32_e32 v248, v248, v248
	v_cvt_pk_bf16_f32 v224, v224, v249
	v_cvt_pk_bf16_f32 v225, v225, v248
	v_mul_f32_e32 v226, v24, v231
	v_mul_f32_e32 v249, v25, v231
	v_mul_f32_e32 v227, v26, v231
	v_mul_f32_e32 v248, v27, v231
	v_max_f32_e32 v226, 0, v226
	v_max_f32_e32 v249, 0, v249
	v_max_f32_e32 v227, 0, v227
	v_max_f32_e32 v248, 0, v248
	v_mul_f32_e32 v226, v226, v226
	v_mul_f32_e32 v249, v249, v249
	v_mul_f32_e32 v227, v227, v227
	v_mul_f32_e32 v248, v248, v248
	v_cvt_pk_bf16_f32 v226, v226, v249
	v_cvt_pk_bf16_f32 v227, v227, v248
	s_nop 1
	v_permlane16_swap_b32_e32 v224, v226
	v_permlane16_swap_b32_e32 v225, v227
	global_store_dwordx4 v229, v[224:227], s[30:31] offset:192
	s_add_u32 s30, s30, 0x20000
	s_addc_u32 s31, s31, 0
	s_waitcnt vmcnt(12)
	v_add_f32_e32 v231, v170, v171
	v_add_f32_e32 v248, v172, v173
	v_add_f32_e32 v231, v231, v248
	v_add_f32_e32 v249, v174, v175
	v_add_f32_e32 v248, v176, v177
	v_add_f32_e32 v249, v249, v248
	v_add_f32_e32 v231, v231, v249
	v_add_f32_e32 v249, v178, v179
	v_add_f32_e32 v248, v180, v181
	v_add_f32_e32 v249, v249, v248
	v_add_f32_e32 v231, v231, v249
	v_add_f32_e32 v249, v182, v183
	v_add_f32_e32 v248, v184, v185
	v_add_f32_e32 v249, v249, v248
	v_add_f32_e32 v231, v231, v249
	v_fmamk_f32 v231, v231, 0x3a800000, v199
	v_cmp_gt_f32_e32 vcc, s73, v231
	v_mul_f32_e32 v248, 0x4b800000, v231
	s_nop 0
	v_cndmask_b32_e32 v231, v231, v248, vcc
	v_rsq_f32_e32 v231, v231
	s_nop 0
	v_mul_f32_e32 v248, 0x45800000, v231
	v_cndmask_b32_e32 v231, v231, v248, vcc
	v_mul_f32_e32 v212, v108, v231
	v_mul_f32_e32 v249, v109, v231
	v_mul_f32_e32 v213, v110, v231
	v_mul_f32_e32 v248, v111, v231
	v_max_f32_e32 v212, 0, v212
	v_max_f32_e32 v249, 0, v249
	v_max_f32_e32 v213, 0, v213
	v_max_f32_e32 v248, 0, v248
	v_mul_f32_e32 v212, v212, v212
	v_mul_f32_e32 v249, v249, v249
	v_mul_f32_e32 v213, v213, v213
	v_mul_f32_e32 v248, v248, v248
	v_cvt_pk_bf16_f32 v212, v212, v249
	v_cvt_pk_bf16_f32 v213, v213, v248
	v_mul_f32_e32 v214, v112, v231
	v_mul_f32_e32 v249, v113, v231
	v_mul_f32_e32 v215, v114, v231
	v_mul_f32_e32 v248, v115, v231
	v_max_f32_e32 v214, 0, v214
	v_max_f32_e32 v249, 0, v249
	v_max_f32_e32 v215, 0, v215
	v_max_f32_e32 v248, 0, v248
	v_mul_f32_e32 v214, v214, v214
	v_mul_f32_e32 v249, v249, v249
	v_mul_f32_e32 v215, v215, v215
	v_mul_f32_e32 v248, v248, v248
	v_cvt_pk_bf16_f32 v214, v214, v249
	v_cvt_pk_bf16_f32 v215, v215, v248
	s_nop 1
	v_permlane16_swap_b32_e32 v212, v214
	v_permlane16_swap_b32_e32 v213, v215
	global_store_dwordx4 v229, v[212:215], s[30:31]
	v_mul_f32_e32 v216, v120, v231
	v_mul_f32_e32 v249, v121, v231
	v_mul_f32_e32 v217, v122, v231
	v_mul_f32_e32 v248, v123, v231
	v_max_f32_e32 v216, 0, v216
	v_max_f32_e32 v249, 0, v249
	v_max_f32_e32 v217, 0, v217
	v_max_f32_e32 v248, 0, v248
	v_mul_f32_e32 v216, v216, v216
	v_mul_f32_e32 v249, v249, v249
	v_mul_f32_e32 v217, v217, v217
	v_mul_f32_e32 v248, v248, v248
	v_cvt_pk_bf16_f32 v216, v216, v249
	v_cvt_pk_bf16_f32 v217, v217, v248
	v_mul_f32_e32 v218, v124, v231
	v_mul_f32_e32 v249, v125, v231
	v_mul_f32_e32 v219, v126, v231
	v_mul_f32_e32 v248, v127, v231
	v_max_f32_e32 v218, 0, v218
	v_max_f32_e32 v249, 0, v249
	v_max_f32_e32 v219, 0, v219
	v_max_f32_e32 v248, 0, v248
	v_mul_f32_e32 v218, v218, v218
	v_mul_f32_e32 v249, v249, v249
	v_mul_f32_e32 v219, v219, v219
	v_mul_f32_e32 v248, v248, v248
	v_cvt_pk_bf16_f32 v218, v218, v249
	v_cvt_pk_bf16_f32 v219, v219, v248
	s_nop 1
	v_permlane16_swap_b32_e32 v216, v218
	v_permlane16_swap_b32_e32 v217, v219
	global_store_dwordx4 v229, v[216:219], s[30:31] offset:64
	v_mul_f32_e32 v220, v64, v231
	v_mul_f32_e32 v249, v65, v231
	v_mul_f32_e32 v221, v66, v231
	v_mul_f32_e32 v248, v67, v231
	v_max_f32_e32 v220, 0, v220
	v_max_f32_e32 v249, 0, v249
	v_max_f32_e32 v221, 0, v221
	v_max_f32_e32 v248, 0, v248
	v_mul_f32_e32 v220, v220, v220
	v_mul_f32_e32 v249, v249, v249
	v_mul_f32_e32 v221, v221, v221
	v_mul_f32_e32 v248, v248, v248
	v_cvt_pk_bf16_f32 v220, v220, v249
	v_cvt_pk_bf16_f32 v221, v221, v248
	v_mul_f32_e32 v222, v68, v231
	v_mul_f32_e32 v249, v69, v231
	v_mul_f32_e32 v223, v70, v231
	v_mul_f32_e32 v248, v71, v231
	v_max_f32_e32 v222, 0, v222
	v_max_f32_e32 v249, 0, v249
	v_max_f32_e32 v223, 0, v223
	v_max_f32_e32 v248, 0, v248
	v_mul_f32_e32 v222, v222, v222
	v_mul_f32_e32 v249, v249, v249
	v_mul_f32_e32 v223, v223, v223
	v_mul_f32_e32 v248, v248, v248
	v_cvt_pk_bf16_f32 v222, v222, v249
	v_cvt_pk_bf16_f32 v223, v223, v248
	s_nop 1
	v_permlane16_swap_b32_e32 v220, v222
	v_permlane16_swap_b32_e32 v221, v223
	global_store_dwordx4 v229, v[220:223], s[30:31] offset:128
	v_mul_f32_e32 v224, v80, v231
	v_mul_f32_e32 v249, v81, v231
	v_mul_f32_e32 v225, v82, v231
	v_mul_f32_e32 v248, v83, v231
	v_max_f32_e32 v224, 0, v224
	v_max_f32_e32 v249, 0, v249
	v_max_f32_e32 v225, 0, v225
	v_max_f32_e32 v248, 0, v248
	v_mul_f32_e32 v224, v224, v224
	v_mul_f32_e32 v249, v249, v249
	v_mul_f32_e32 v225, v225, v225
	v_mul_f32_e32 v248, v248, v248
	v_cvt_pk_bf16_f32 v224, v224, v249
	v_cvt_pk_bf16_f32 v225, v225, v248
	v_mul_f32_e32 v226, v56, v231
	v_mul_f32_e32 v249, v57, v231
	v_mul_f32_e32 v227, v58, v231
	v_mul_f32_e32 v248, v59, v231
	v_max_f32_e32 v226, 0, v226
	v_max_f32_e32 v249, 0, v249
	v_max_f32_e32 v227, 0, v227
	v_max_f32_e32 v248, 0, v248
	v_mul_f32_e32 v226, v226, v226
	v_mul_f32_e32 v249, v249, v249
	v_mul_f32_e32 v227, v227, v227
	v_mul_f32_e32 v248, v248, v248
	v_cvt_pk_bf16_f32 v226, v226, v249
	v_cvt_pk_bf16_f32 v227, v227, v248
	s_nop 1
	v_permlane16_swap_b32_e32 v224, v226
	v_permlane16_swap_b32_e32 v225, v227
	global_store_dwordx4 v229, v[224:227], s[30:31] offset:192
	s_add_u32 s30, s30, 0x20000
	s_addc_u32 s31, s31, 0
	s_waitcnt vmcnt(12)
	v_add_f32_e32 v231, v186, v187
	v_add_f32_e32 v248, v188, v189
	v_add_f32_e32 v231, v231, v248
	v_add_f32_e32 v249, v190, v191
	v_add_f32_e32 v248, v192, v193
	v_add_f32_e32 v249, v249, v248
	v_add_f32_e32 v231, v231, v249
	v_add_f32_e32 v249, v194, v195
	v_add_f32_e32 v248, v196, v197
	v_add_f32_e32 v249, v249, v248
	v_add_f32_e32 v231, v231, v249
	v_add_f32_e32 v249, v208, v209
	v_add_f32_e32 v248, v210, v211
	v_add_f32_e32 v249, v249, v248
	v_add_f32_e32 v231, v231, v249
	v_fmamk_f32 v231, v231, 0x3a800000, v199
	v_cmp_gt_f32_e32 vcc, s73, v231
	v_mul_f32_e32 v248, 0x4b800000, v231
	s_nop 0
	v_cndmask_b32_e32 v231, v231, v248, vcc
	v_rsq_f32_e32 v231, v231
	s_nop 0
	v_mul_f32_e32 v248, 0x45800000, v231
	v_cndmask_b32_e32 v231, v231, v248, vcc
	v_mul_f32_e32 v212, v132, v231
	v_mul_f32_e32 v249, v133, v231
	v_mul_f32_e32 v213, v134, v231
	v_mul_f32_e32 v248, v135, v231
	v_max_f32_e32 v212, 0, v212
	v_max_f32_e32 v249, 0, v249
	v_max_f32_e32 v213, 0, v213
	v_max_f32_e32 v248, 0, v248
	v_mul_f32_e32 v212, v212, v212
	v_mul_f32_e32 v249, v249, v249
	v_mul_f32_e32 v213, v213, v213
	v_mul_f32_e32 v248, v248, v248
	v_cvt_pk_bf16_f32 v212, v212, v249
	v_cvt_pk_bf16_f32 v213, v213, v248
	v_mul_f32_e32 v214, v136, v231
	v_mul_f32_e32 v249, v137, v231
	v_mul_f32_e32 v215, v138, v231
	v_mul_f32_e32 v248, v139, v231
	v_max_f32_e32 v214, 0, v214
	v_max_f32_e32 v249, 0, v249
	v_max_f32_e32 v215, 0, v215
	v_max_f32_e32 v248, 0, v248
	v_mul_f32_e32 v214, v214, v214
	v_mul_f32_e32 v249, v249, v249
	v_mul_f32_e32 v215, v215, v215
	v_mul_f32_e32 v248, v248, v248
	v_cvt_pk_bf16_f32 v214, v214, v249
	v_cvt_pk_bf16_f32 v215, v215, v248
	s_nop 1
	v_permlane16_swap_b32_e32 v212, v214
	v_permlane16_swap_b32_e32 v213, v215
	global_store_dwordx4 v229, v[212:215], s[30:31]
	v_mul_f32_e32 v216, v140, v231
	v_mul_f32_e32 v249, v141, v231
	v_mul_f32_e32 v217, v142, v231
	v_mul_f32_e32 v248, v143, v231
	v_max_f32_e32 v216, 0, v216
	v_max_f32_e32 v249, 0, v249
	v_max_f32_e32 v217, 0, v217
	v_max_f32_e32 v248, 0, v248
	v_mul_f32_e32 v216, v216, v216
	v_mul_f32_e32 v249, v249, v249
	v_mul_f32_e32 v217, v217, v217
	v_mul_f32_e32 v248, v248, v248
	v_cvt_pk_bf16_f32 v216, v216, v249
	v_cvt_pk_bf16_f32 v217, v217, v248
	v_mul_f32_e32 v218, v144, v231
	v_mul_f32_e32 v249, v145, v231
	v_mul_f32_e32 v219, v146, v231
	v_mul_f32_e32 v248, v147, v231
	v_max_f32_e32 v218, 0, v218
	v_max_f32_e32 v249, 0, v249
	v_max_f32_e32 v219, 0, v219
	v_max_f32_e32 v248, 0, v248
	v_mul_f32_e32 v218, v218, v218
	v_mul_f32_e32 v249, v249, v249
	v_mul_f32_e32 v219, v219, v219
	v_mul_f32_e32 v248, v248, v248
	v_cvt_pk_bf16_f32 v218, v218, v249
	v_cvt_pk_bf16_f32 v219, v219, v248
	s_nop 1
	v_permlane16_swap_b32_e32 v216, v218
	v_permlane16_swap_b32_e32 v217, v219
	global_store_dwordx4 v229, v[216:219], s[30:31] offset:64
	v_mul_f32_e32 v220, v76, v231
	v_mul_f32_e32 v249, v77, v231
	v_mul_f32_e32 v221, v78, v231
	v_mul_f32_e32 v248, v79, v231
	v_max_f32_e32 v220, 0, v220
	v_max_f32_e32 v249, 0, v249
	v_max_f32_e32 v221, 0, v221
	v_max_f32_e32 v248, 0, v248
	v_mul_f32_e32 v220, v220, v220
	v_mul_f32_e32 v249, v249, v249
	v_mul_f32_e32 v221, v221, v221
	v_mul_f32_e32 v248, v248, v248
	v_cvt_pk_bf16_f32 v220, v220, v249
	v_cvt_pk_bf16_f32 v221, v221, v248
	v_mul_f32_e32 v222, v72, v231
	v_mul_f32_e32 v249, v73, v231
	v_mul_f32_e32 v223, v74, v231
	v_mul_f32_e32 v248, v75, v231
	v_max_f32_e32 v222, 0, v222
	v_max_f32_e32 v249, 0, v249
	v_max_f32_e32 v223, 0, v223
	v_max_f32_e32 v248, 0, v248
	v_mul_f32_e32 v222, v222, v222
	v_mul_f32_e32 v249, v249, v249
	v_mul_f32_e32 v223, v223, v223
	v_mul_f32_e32 v248, v248, v248
	v_cvt_pk_bf16_f32 v222, v222, v249
	v_cvt_pk_bf16_f32 v223, v223, v248
	s_nop 1
	v_permlane16_swap_b32_e32 v220, v222
	v_permlane16_swap_b32_e32 v221, v223
	global_store_dwordx4 v229, v[220:223], s[30:31] offset:128
	v_mul_f32_e32 v224, v60, v231
	v_mul_f32_e32 v249, v61, v231
	v_mul_f32_e32 v225, v62, v231
	v_mul_f32_e32 v248, v63, v231
	v_max_f32_e32 v224, 0, v224
	v_max_f32_e32 v249, 0, v249
	v_max_f32_e32 v225, 0, v225
	v_max_f32_e32 v248, 0, v248
	v_mul_f32_e32 v224, v224, v224
	v_mul_f32_e32 v249, v249, v249
	v_mul_f32_e32 v225, v225, v225
	v_mul_f32_e32 v248, v248, v248
	v_cvt_pk_bf16_f32 v224, v224, v249
	v_cvt_pk_bf16_f32 v225, v225, v248
	v_mul_f32_e32 v226, v148, v231
	v_mul_f32_e32 v249, v149, v231
	v_mul_f32_e32 v227, v150, v231
	v_mul_f32_e32 v248, v151, v231
	v_max_f32_e32 v226, 0, v226
	v_max_f32_e32 v249, 0, v249
	v_max_f32_e32 v227, 0, v227
	v_max_f32_e32 v248, 0, v248
	v_mul_f32_e32 v226, v226, v226
	v_mul_f32_e32 v249, v249, v249
	v_mul_f32_e32 v227, v227, v227
	v_mul_f32_e32 v248, v248, v248
	v_cvt_pk_bf16_f32 v226, v226, v249
	v_cvt_pk_bf16_f32 v227, v227, v248
	s_nop 1
	v_permlane16_swap_b32_e32 v224, v226
	v_permlane16_swap_b32_e32 v225, v227
	global_store_dwordx4 v229, v[224:227], s[30:31] offset:192
	s_add_u32 s30, s30, 0x20000
	s_addc_u32 s31, s31, 0
	s_cmp_lg_u32 s23, 0
	s_cbranch_scc0 .LBB0_13

.LBB0_24:
	s_lshr_b32 s10, s18, 2
	s_and_b32 s10, s10, 24
	s_and_b32 s11, s18, 7
	s_or_b32 s10, s10, s11
	s_lshl_b32 s10, s10, 10
	v_mov_b32 v8, v198
	s_or_b32 s10, s10, s65
	v_ashrrev_i32_e32 v12, 2, v8
	v_add_u32_e32 v0, s10, v12
	s_waitcnt lgkmcnt(0)
	v_ashrrev_i32_e32 v1, 31, v0
	s_lshl_b32 s11, s18, 5
	v_lshlrev_b64 v[0:1], 11, v[0:1]
	v_lshlrev_b32_e32 v2, 4, v8
	s_and_b32 s11, s11, 0x300
	v_lshl_add_u64 v[0:1], s[96:97], 0, v[0:1]
	v_and_b32_e32 v152, 48, v2
	v_lshl_add_u64 v[14:15], v[0:1], 0, v[152:153]
	v_add_u32_e32 v0, s11, v12
	v_ashrrev_i32_e32 v1, 31, v0
	v_lshlrev_b64 v[0:1], 6, v[0:1]
	v_lshl_add_u64 v[0:1], s[4:5], 0, v[0:1]
	v_add_co_u32_e32 v54, vcc, s62, v14
	v_lshl_add_u64 v[0:1], v[0:1], 0, v[152:153]
	s_nop 0
	v_addc_co_u32_e32 v55, vcc, 0, v15, vcc
	s_lshl_b32 s20, s17, 11
	s_lshl_b32 s21, s18, 8
	s_and_b32 s22, s16, 7
	v_add_co_u32_e32 v2, vcc, s62, v0
	s_and_b32 s20, s20, 0x180000
	s_and_b32 s23, s21, 0x6000
	s_lshl_b32 s22, s22, 10
	v_lshrrev_b32_e32 v6, 2, v8
	v_addc_co_u32_e32 v3, vcc, 0, v1, vcc
	v_and_b32_e32 v6, 12, v6
	v_ashrrev_i32_e32 v13, 31, v12
	s_movk_i32 s21, 0x1230
	s_add_u32 s20, s13, s20
	v_add_co_u32_e32 v4, vcc, s33, v0
	v_lshrrev_b32_e64 v10, v6, s21
	v_lshlrev_b64 v[6:7], 11, v[12:13]
	s_addc_u32 s21, s14, 0
	s_or_b32 s22, s22, s23
	v_addc_co_u32_e32 v5, vcc, 0, v1, vcc
	v_and_b32_e32 v22, 3, v8
	v_xor_b32_e32 v8, v10, v8
	v_lshl_add_u64 v[156:157], s[20:21], 0, v[6:7]
	s_or_b32 s20, s22, s65
	v_add_co_u32_e32 v20, vcc, s72, v0
	v_lshlrev_b32_e32 v9, 6, v12
	v_lshlrev_b32_e32 v8, 4, v8
	v_add_u32_e32 v12, s20, v12
	v_addc_co_u32_e32 v21, vcc, 0, v1, vcc
	s_nop 0
	v_readfirstlane_b32 s26, v14
	v_readfirstlane_b32 s27, v15
	v_readfirstlane_b32 s28, v0
	v_readfirstlane_b32 s29, v1
	v_lshrrev_b32_e32 v250, 6, v198
	s_nop 0
	v_readfirstlane_b32 s24, v250
	s_lshl_b32 s24, s24, 10
	v_lshrrev_b32_e32 v250, 2, v200
	v_lshrrev_b32_e32 v251, 4, v200
	v_lshlrev_b32_e32 v251, 2, v251
	v_mov_b32_e32 v248, 0x1230
	v_lshrrev_b32_e32 v251, v251, v248
	v_xor_b32_e32 v251, v251, v200
	v_and_b32_e32 v251, 3, v251
	v_lshlrev_b32_e32 v251, 4, v251
	v_lshl_add_u32 v244, v250, 11, v251
	v_add_u32_e32 v245, 0x20000, v244
	v_add_u32_e32 v246, 0x40000, v244
	v_add_u32_e32 v247, 0x60000, v244
	v_lshl_add_u32 v156, v250, 6, v251
	v_add_u32_e32 v157, 0x1000, v156
	v_add_u32_e32 v158, 0x2000, v156
	v_add_u32_e32 v159, 0x3000, v156
	s_mov_b32 s25, 0
	s_add_u32 m0, s25, s24
	s_nop 0
	global_load_lds_dwordx4 v244, s[26:27]
	s_add_u32 m0, m0, 0x1000
	s_nop 0
	global_load_lds_dwordx4 v245, s[26:27]
	s_add_u32 m0, m0, 0x1000
	s_nop 0
	global_load_lds_dwordx4 v156, s[28:29]
	s_add_u32 m0, m0, 0x1000
	s_nop 0
	global_load_lds_dwordx4 v157, s[28:29]
	s_add_u32 m0, m0, 0x1000
	s_nop 0
	global_load_lds_dwordx4 v158, s[28:29]
	s_add_u32 m0, m0, 0x1000
	s_nop 0
	global_load_lds_dwordx4 v159, s[28:29]
	s_add_u32 s26, s26, 64
	s_addc_u32 s27, s27, 0
	s_add_u32 s28, s28, 0x10000
	s_addc_u32 s29, s29, 0
	s_add_u32 s25, s25, 24576
	s_cmp_eq_u32 s25, 73728
	s_cselect_b32 s25, 0, s25
	s_add_u32 m0, s25, s24
	s_nop 0
	global_load_lds_dwordx4 v244, s[26:27]
	s_add_u32 m0, m0, 0x1000
	s_nop 0
	global_load_lds_dwordx4 v245, s[26:27]
	s_add_u32 m0, m0, 0x1000
	s_nop 0
	global_load_lds_dwordx4 v156, s[28:29]
	s_add_u32 m0, m0, 0x1000
	s_nop 0
	global_load_lds_dwordx4 v157, s[28:29]
	s_add_u32 m0, m0, 0x1000
	s_nop 0
	global_load_lds_dwordx4 v158, s[28:29]
	s_add_u32 m0, m0, 0x1000
	s_nop 0
	global_load_lds_dwordx4 v159, s[28:29]
	s_add_u32 s26, s26, 64
	s_addc_u32 s27, s27, 0
	s_add_u32 s28, s28, 0x10000
	s_addc_u32 s29, s29, 0
	s_add_u32 s25, s25, 24576
	s_cmp_eq_u32 s25, 73728
	s_cselect_b32 s25, 0, s25
	s_add_u32 m0, s25, s24
	s_nop 0
	global_load_lds_dwordx4 v244, s[26:27]
	s_add_u32 m0, m0, 0x1000
	s_nop 0
	global_load_lds_dwordx4 v245, s[26:27]
	s_add_u32 m0, m0, 0x1000
	s_nop 0
	global_load_lds_dwordx4 v156, s[28:29]
	s_add_u32 m0, m0, 0x1000
	s_nop 0
	global_load_lds_dwordx4 v157, s[28:29]
	s_add_u32 m0, m0, 0x1000
	s_nop 0
	global_load_lds_dwordx4 v158, s[28:29]
	s_add_u32 m0, m0, 0x1000
	s_nop 0
	global_load_lds_dwordx4 v159, s[28:29]
	s_add_u32 s26, s26, 64
	s_addc_u32 s27, s27, 0
	s_add_u32 s28, s28, 0x10000
	s_addc_u32 s29, s29, 0
	s_add_u32 s25, s25, 24576
	s_cmp_eq_u32 s25, 73728
	s_cselect_b32 s25, 0, s25
	v_mov_b32_e32 v24, 0
	v_mov_b32_e32 v25, v24
	v_mov_b32_e32 v26, v24
	v_mov_b32_e32 v27, v24
	v_mov_b32_e32 v28, v24
	v_mov_b32_e32 v29, v24
	v_mov_b32_e32 v60, v24
	v_mov_b32_e32 v61, v24
	v_mov_b32_e32 v62, v24
	v_mov_b32_e32 v63, v24
	v_mov_b32_e32 v64, v24
	v_mov_b32_e32 v65, v24
	v_mov_b32_e32 v66, v24
	v_mov_b32_e32 v67, v24
	v_mov_b32_e32 v72, v24
	v_mov_b32_e32 v73, v24
	v_mov_b32_e32 v74, v24
	v_mov_b32_e32 v75, v24
	v_mov_b32_e32 v80, v24
	v_mov_b32_e32 v81, v24
	v_mov_b32_e32 v82, v24
	v_mov_b32_e32 v83, v24
	v_mov_b32_e32 v56, v24
	v_mov_b32_e32 v57, v24
	v_mov_b32_e32 v58, v24
	v_mov_b32_e32 v59, v24
	v_mov_b32_e32 v68, v24
	v_mov_b32_e32 v69, v24
	v_mov_b32_e32 v30, v24
	v_mov_b32_e32 v31, v24
	v_mov_b32_e32 v32, v24
	v_mov_b32_e32 v33, v24
	v_mov_b32_e32 v34, v24
	v_mov_b32_e32 v35, v24
	v_mov_b32_e32 v36, v24
	v_mov_b32_e32 v37, v24
	v_mov_b32_e32 v38, v24
	v_mov_b32_e32 v39, v24
	v_mov_b32_e32 v40, v24
	v_mov_b32_e32 v41, v24
	v_mov_b32_e32 v42, v24
	v_mov_b32_e32 v43, v24
	v_mov_b32_e32 v48, v24
	v_mov_b32_e32 v49, v24
	v_mov_b32_e32 v50, v24
	v_mov_b32_e32 v51, v24
	v_mov_b32_e32 v70, v24
	v_mov_b32_e32 v71, v24
	v_mov_b32_e32 v100, v24
	v_mov_b32_e32 v101, v24
	v_mov_b32_e32 v102, v24
	v_mov_b32_e32 v103, v24
	v_mov_b32_e32 v104, v24
	v_mov_b32_e32 v105, v24
	v_mov_b32_e32 v106, v24
	v_mov_b32_e32 v107, v24
	v_mov_b32_e32 v120, v24
	v_mov_b32_e32 v121, v24
	v_mov_b32_e32 v122, v24
	v_mov_b32_e32 v123, v24
	v_mov_b32_e32 v128, v24
	v_mov_b32_e32 v129, v24
	v_mov_b32_e32 v130, v24
	v_mov_b32_e32 v131, v24
	v_mov_b32_e32 v108, v24
	v_mov_b32_e32 v109, v24
	v_mov_b32_e32 v110, v24
	v_mov_b32_e32 v111, v24
	v_mov_b32_e32 v112, v24
	v_mov_b32_e32 v113, v24
	v_mov_b32_e32 v114, v24
	v_mov_b32_e32 v115, v24
	v_mov_b32_e32 v116, v24
	v_mov_b32_e32 v117, v24
	v_mov_b32_e32 v118, v24
	v_mov_b32_e32 v119, v24
	v_mov_b32_e32 v124, v24
	v_mov_b32_e32 v125, v24
	v_mov_b32_e32 v126, v24
	v_mov_b32_e32 v127, v24
	v_mov_b32_e32 v88, v24
	v_mov_b32_e32 v89, v24
	v_mov_b32_e32 v90, v24
	v_mov_b32_e32 v91, v24
	v_mov_b32_e32 v92, v24
	v_mov_b32_e32 v93, v24
	v_mov_b32_e32 v94, v24
	v_mov_b32_e32 v95, v24
	v_mov_b32_e32 v96, v24
	v_mov_b32_e32 v97, v24
	v_mov_b32_e32 v98, v24
	v_mov_b32_e32 v99, v24
	v_mov_b32_e32 v84, v24
	v_mov_b32_e32 v85, v24
	v_mov_b32_e32 v86, v24
	v_mov_b32_e32 v87, v24
	v_mov_b32_e32 v132, v24
	v_mov_b32_e32 v133, v24
	v_mov_b32_e32 v134, v24
	v_mov_b32_e32 v135, v24
	v_mov_b32_e32 v136, v24
	v_mov_b32_e32 v137, v24
	v_mov_b32_e32 v138, v24
	v_mov_b32_e32 v139, v24
	v_mov_b32_e32 v140, v24
	v_mov_b32_e32 v141, v24
	v_mov_b32_e32 v142, v24
	v_mov_b32_e32 v143, v24
	v_mov_b32_e32 v144, v24
	v_mov_b32_e32 v145, v24
	v_mov_b32_e32 v146, v24
	v_mov_b32_e32 v147, v24
	v_mov_b32_e32 v76, v24
	v_mov_b32_e32 v77, v24
	v_mov_b32_e32 v78, v24
	v_mov_b32_e32 v79, v24
	v_mov_b32_e32 v52, v24
	v_mov_b32_e32 v53, v24
	v_mov_b32_e32 v54, v24
	v_mov_b32_e32 v55, v24
	v_mov_b32_e32 v44, v24
	v_mov_b32_e32 v45, v24
	v_mov_b32_e32 v46, v24
	v_mov_b32_e32 v47, v24
	v_mov_b32_e32 v148, v24
	v_mov_b32_e32 v149, v24
	v_mov_b32_e32 v150, v24
	v_mov_b32_e32 v151, v24
	s_waitcnt vmcnt(12)
	s_barrier
	s_mov_b32 s30, 0
	v_add_u32_e32 v248, s30, v155
	v_add_u32_e32 v249, s30, v160
	ds_read_b128 v[186:189], v248
	ds_read_b128 v[212:215], v249 offset:8192
	ds_read_b128 v[190:193], v248 offset:1024
	ds_read_b128 v[216:219], v249 offset:9216
	ds_read_b128 v[194:197], v248 offset:2048
	ds_read_b128 v[220:223], v249 offset:10240
	ds_read_b128 v[208:211], v248 offset:3072
	ds_read_b128 v[224:227], v249 offset:11264
	ds_read_b128 v[228:231], v249 offset:12288
	ds_read_b128 v[232:235], v249 offset:13312
	ds_read_b128 v[236:239], v249 offset:14336
	ds_read_b128 v[240:243], v249 offset:15360
	s_add_u32 s30, s30, 24576
	s_cmp_eq_u32 s30, 73728
	s_cselect_b32 s30, 0, s30
	s_waitcnt vmcnt(6)
	s_waitcnt lgkmcnt(0)
	s_barrier
	s_mov_b32 s31, 14
.Lgm1_loop:
	v_add_u32_e32 v248, s30, v155
	v_add_u32_e32 v249, s30, v160
	v_mfma_f32_16x16x32_bf16 v[128:131], v[212:215], v[186:189], v[128:131]
	ds_read_b128 v[0:3], v248
	v_mfma_f32_16x16x32_bf16 v[80:83], v[212:215], v[190:193], v[80:83]
	ds_read_b128 v[16:19], v249 offset:8192
	v_mfma_f32_16x16x32_bf16 v[108:111], v[212:215], v[194:197], v[108:111]
	ds_read_b128 v[4:7], v248 offset:1024
	v_mfma_f32_16x16x32_bf16 v[132:135], v[212:215], v[208:211], v[132:135]
	ds_read_b128 v[20:23], v249 offset:9216
	v_mfma_f32_16x16x32_bf16 v[120:123], v[216:219], v[186:189], v[120:123]
	ds_read_b128 v[8:11], v248 offset:2048
	v_mfma_f32_16x16x32_bf16 v[72:75], v[216:219], v[190:193], v[72:75]
	ds_read_b128 v[162:165], v249 offset:10240
	v_mfma_f32_16x16x32_bf16 v[112:115], v[216:219], v[194:197], v[112:115]
	ds_read_b128 v[12:15], v248 offset:3072
	v_mfma_f32_16x16x32_bf16 v[136:139], v[216:219], v[208:211], v[136:139]
	ds_read_b128 v[166:169], v249 offset:11264
	v_mfma_f32_16x16x32_bf16 v[104:107], v[220:223], v[186:189], v[104:107]
	ds_read_b128 v[170:173], v249 offset:12288
	v_mfma_f32_16x16x32_bf16 v[64:67], v[220:223], v[190:193], v[64:67]
	ds_read_b128 v[174:177], v249 offset:13312
	v_mfma_f32_16x16x32_bf16 v[116:119], v[220:223], v[194:197], v[116:119]
	ds_read_b128 v[178:181], v249 offset:14336
	v_mfma_f32_16x16x32_bf16 v[140:143], v[220:223], v[208:211], v[140:143]
	ds_read_b128 v[182:185], v249 offset:15360
	s_add_u32 m0, s25, s24
	v_mfma_f32_16x16x32_bf16 v[100:103], v[224:227], v[186:189], v[100:103]
	global_load_lds_dwordx4 v244, s[26:27]
	v_mfma_f32_16x16x32_bf16 v[60:63], v[224:227], v[190:193], v[60:63]
	v_mfma_f32_16x16x32_bf16 v[124:127], v[224:227], v[194:197], v[124:127]
	s_add_u32 m0, m0, 0x1000
	v_mfma_f32_16x16x32_bf16 v[144:147], v[224:227], v[208:211], v[144:147]
	global_load_lds_dwordx4 v245, s[26:27]
	v_mfma_f32_16x16x32_bf16 v[68:71], v[228:231], v[186:189], v[68:71]
	v_mfma_f32_16x16x32_bf16 v[36:39], v[228:231], v[190:193], v[36:39]
	s_add_u32 m0, m0, 0x1000
	v_mfma_f32_16x16x32_bf16 v[88:91], v[228:231], v[194:197], v[88:91]
	global_load_lds_dwordx4 v156, s[28:29]
	v_mfma_f32_16x16x32_bf16 v[76:79], v[228:231], v[208:211], v[76:79]
	v_mfma_f32_16x16x32_bf16 v[56:59], v[232:235], v[186:189], v[56:59]
	s_add_u32 m0, m0, 0x1000
	v_mfma_f32_16x16x32_bf16 v[32:35], v[232:235], v[190:193], v[32:35]
	global_load_lds_dwordx4 v157, s[28:29]
	v_mfma_f32_16x16x32_bf16 v[92:95], v[232:235], v[194:197], v[92:95]
	v_mfma_f32_16x16x32_bf16 v[52:55], v[232:235], v[208:211], v[52:55]
	s_add_u32 m0, m0, 0x1000
	v_mfma_f32_16x16x32_bf16 v[48:51], v[236:239], v[186:189], v[48:51]
	global_load_lds_dwordx4 v158, s[28:29]
	v_mfma_f32_16x16x32_bf16 v[28:31], v[236:239], v[190:193], v[28:31]
	v_mfma_f32_16x16x32_bf16 v[96:99], v[236:239], v[194:197], v[96:99]
	s_add_u32 m0, m0, 0x1000
	v_mfma_f32_16x16x32_bf16 v[44:47], v[236:239], v[208:211], v[44:47]
	global_load_lds_dwordx4 v159, s[28:29]
	v_mfma_f32_16x16x32_bf16 v[40:43], v[240:243], v[186:189], v[40:43]
	v_mfma_f32_16x16x32_bf16 v[24:27], v[240:243], v[190:193], v[24:27]
	v_mfma_f32_16x16x32_bf16 v[84:87], v[240:243], v[194:197], v[84:87]
	v_mfma_f32_16x16x32_bf16 v[148:151], v[240:243], v[208:211], v[148:151]
	s_add_u32 s26, s26, 64
	s_addc_u32 s27, s27, 0
	s_add_u32 s28, s28, 0x10000
	s_addc_u32 s29, s29, 0
	s_add_u32 s25, s25, 24576
	s_cmp_eq_u32 s25, 73728
	s_cselect_b32 s25, 0, s25
	s_add_u32 s30, s30, 24576
	s_cmp_eq_u32 s30, 73728
	s_cselect_b32 s30, 0, s30
	s_waitcnt vmcnt(6)
	s_waitcnt lgkmcnt(0)
	s_barrier
	v_add_u32_e32 v248, s30, v155
	v_add_u32_e32 v249, s30, v160
	v_mfma_f32_16x16x32_bf16 v[128:131], v[16:19], v[0:3], v[128:131]
	ds_read_b128 v[186:189], v248
	v_mfma_f32_16x16x32_bf16 v[80:83], v[16:19], v[4:7], v[80:83]
	ds_read_b128 v[212:215], v249 offset:8192
	v_mfma_f32_16x16x32_bf16 v[108:111], v[16:19], v[8:11], v[108:111]
	ds_read_b128 v[190:193], v248 offset:1024
	v_mfma_f32_16x16x32_bf16 v[132:135], v[16:19], v[12:15], v[132:135]
	ds_read_b128 v[216:219], v249 offset:9216
	v_mfma_f32_16x16x32_bf16 v[120:123], v[20:23], v[0:3], v[120:123]
	ds_read_b128 v[194:197], v248 offset:2048
	v_mfma_f32_16x16x32_bf16 v[72:75], v[20:23], v[4:7], v[72:75]
	ds_read_b128 v[220:223], v249 offset:10240
	v_mfma_f32_16x16x32_bf16 v[112:115], v[20:23], v[8:11], v[112:115]
	ds_read_b128 v[208:211], v248 offset:3072
	v_mfma_f32_16x16x32_bf16 v[136:139], v[20:23], v[12:15], v[136:139]
	ds_read_b128 v[224:227], v249 offset:11264
	v_mfma_f32_16x16x32_bf16 v[104:107], v[162:165], v[0:3], v[104:107]
	ds_read_b128 v[228:231], v249 offset:12288
	v_mfma_f32_16x16x32_bf16 v[64:67], v[162:165], v[4:7], v[64:67]
	ds_read_b128 v[232:235], v249 offset:13312
	v_mfma_f32_16x16x32_bf16 v[116:119], v[162:165], v[8:11], v[116:119]
	ds_read_b128 v[236:239], v249 offset:14336
	v_mfma_f32_16x16x32_bf16 v[140:143], v[162:165], v[12:15], v[140:143]
	ds_read_b128 v[240:243], v249 offset:15360
	s_add_u32 m0, s25, s24
	v_mfma_f32_16x16x32_bf16 v[100:103], v[166:169], v[0:3], v[100:103]
	global_load_lds_dwordx4 v244, s[26:27]
	v_mfma_f32_16x16x32_bf16 v[60:63], v[166:169], v[4:7], v[60:63]
	v_mfma_f32_16x16x32_bf16 v[124:127], v[166:169], v[8:11], v[124:127]
	s_add_u32 m0, m0, 0x1000
	v_mfma_f32_16x16x32_bf16 v[144:147], v[166:169], v[12:15], v[144:147]
	global_load_lds_dwordx4 v245, s[26:27]
	v_mfma_f32_16x16x32_bf16 v[68:71], v[170:173], v[0:3], v[68:71]
	v_mfma_f32_16x16x32_bf16 v[36:39], v[170:173], v[4:7], v[36:39]
	s_add_u32 m0, m0, 0x1000
	v_mfma_f32_16x16x32_bf16 v[88:91], v[170:173], v[8:11], v[88:91]
	global_load_lds_dwordx4 v156, s[28:29]
	v_mfma_f32_16x16x32_bf16 v[76:79], v[170:173], v[12:15], v[76:79]
	v_mfma_f32_16x16x32_bf16 v[56:59], v[174:177], v[0:3], v[56:59]
	s_add_u32 m0, m0, 0x1000
	v_mfma_f32_16x16x32_bf16 v[32:35], v[174:177], v[4:7], v[32:35]
	global_load_lds_dwordx4 v157, s[28:29]
	v_mfma_f32_16x16x32_bf16 v[92:95], v[174:177], v[8:11], v[92:95]
	v_mfma_f32_16x16x32_bf16 v[52:55], v[174:177], v[12:15], v[52:55]
	s_add_u32 m0, m0, 0x1000
	v_mfma_f32_16x16x32_bf16 v[48:51], v[178:181], v[0:3], v[48:51]
	global_load_lds_dwordx4 v158, s[28:29]
	v_mfma_f32_16x16x32_bf16 v[28:31], v[178:181], v[4:7], v[28:31]
	v_mfma_f32_16x16x32_bf16 v[96:99], v[178:181], v[8:11], v[96:99]
	s_add_u32 m0, m0, 0x1000
	v_mfma_f32_16x16x32_bf16 v[44:47], v[178:181], v[12:15], v[44:47]
	global_load_lds_dwordx4 v159, s[28:29]
	v_mfma_f32_16x16x32_bf16 v[40:43], v[182:185], v[0:3], v[40:43]
	v_mfma_f32_16x16x32_bf16 v[24:27], v[182:185], v[4:7], v[24:27]
	v_mfma_f32_16x16x32_bf16 v[84:87], v[182:185], v[8:11], v[84:87]
	v_mfma_f32_16x16x32_bf16 v[148:151], v[182:185], v[12:15], v[148:151]
	s_add_u32 s26, s26, 64
	s_addc_u32 s27, s27, 0
	s_add_u32 s28, s28, 0x10000
	s_addc_u32 s29, s29, 0
	s_add_u32 s25, s25, 24576
	s_cmp_eq_u32 s25, 73728
	s_cselect_b32 s25, 0, s25
	s_add_u32 s30, s30, 24576
	s_cmp_eq_u32 s30, 73728
	s_cselect_b32 s30, 0, s30
	s_waitcnt vmcnt(6)
	s_waitcnt lgkmcnt(0)
	s_barrier
	s_sub_u32 s31, s31, 1
	s_cmp_lg_u32 s31, 0
	s_cbranch_scc1 .Lgm1_loop
	v_add_u32_e32 v248, s30, v155
	v_add_u32_e32 v249, s30, v160
	v_mfma_f32_16x16x32_bf16 v[128:131], v[212:215], v[186:189], v[128:131]
	ds_read_b128 v[0:3], v248
	v_mfma_f32_16x16x32_bf16 v[80:83], v[212:215], v[190:193], v[80:83]
	ds_read_b128 v[16:19], v249 offset:8192
	v_mfma_f32_16x16x32_bf16 v[108:111], v[212:215], v[194:197], v[108:111]
	ds_read_b128 v[4:7], v248 offset:1024
	v_mfma_f32_16x16x32_bf16 v[132:135], v[212:215], v[208:211], v[132:135]
	ds_read_b128 v[20:23], v249 offset:9216
	v_mfma_f32_16x16x32_bf16 v[120:123], v[216:219], v[186:189], v[120:123]
	ds_read_b128 v[8:11], v248 offset:2048
	v_mfma_f32_16x16x32_bf16 v[72:75], v[216:219], v[190:193], v[72:75]
	ds_read_b128 v[162:165], v249 offset:10240
	v_mfma_f32_16x16x32_bf16 v[112:115], v[216:219], v[194:197], v[112:115]
	ds_read_b128 v[12:15], v248 offset:3072
	v_mfma_f32_16x16x32_bf16 v[136:139], v[216:219], v[208:211], v[136:139]
	ds_read_b128 v[166:169], v249 offset:11264
	v_mfma_f32_16x16x32_bf16 v[104:107], v[220:223], v[186:189], v[104:107]
	ds_read_b128 v[170:173], v249 offset:12288
	v_mfma_f32_16x16x32_bf16 v[64:67], v[220:223], v[190:193], v[64:67]
	ds_read_b128 v[174:177], v249 offset:13312
	v_mfma_f32_16x16x32_bf16 v[116:119], v[220:223], v[194:197], v[116:119]
	ds_read_b128 v[178:181], v249 offset:14336
	v_mfma_f32_16x16x32_bf16 v[140:143], v[220:223], v[208:211], v[140:143]
	ds_read_b128 v[182:185], v249 offset:15360
	s_add_u32 m0, s25, s24
	v_mfma_f32_16x16x32_bf16 v[100:103], v[224:227], v[186:189], v[100:103]
	global_load_lds_dwordx4 v244, s[26:27]
	v_mfma_f32_16x16x32_bf16 v[60:63], v[224:227], v[190:193], v[60:63]
	v_mfma_f32_16x16x32_bf16 v[124:127], v[224:227], v[194:197], v[124:127]
	s_add_u32 m0, m0, 0x1000
	v_mfma_f32_16x16x32_bf16 v[144:147], v[224:227], v[208:211], v[144:147]
	global_load_lds_dwordx4 v245, s[26:27]
	v_mfma_f32_16x16x32_bf16 v[68:71], v[228:231], v[186:189], v[68:71]
	v_mfma_f32_16x16x32_bf16 v[36:39], v[228:231], v[190:193], v[36:39]
	s_add_u32 m0, m0, 0x1000
	v_mfma_f32_16x16x32_bf16 v[88:91], v[228:231], v[194:197], v[88:91]
	global_load_lds_dwordx4 v156, s[28:29]
	v_mfma_f32_16x16x32_bf16 v[76:79], v[228:231], v[208:211], v[76:79]
	v_mfma_f32_16x16x32_bf16 v[56:59], v[232:235], v[186:189], v[56:59]
	s_add_u32 m0, m0, 0x1000
	v_mfma_f32_16x16x32_bf16 v[32:35], v[232:235], v[190:193], v[32:35]
	global_load_lds_dwordx4 v157, s[28:29]
	v_mfma_f32_16x16x32_bf16 v[92:95], v[232:235], v[194:197], v[92:95]
	v_mfma_f32_16x16x32_bf16 v[52:55], v[232:235], v[208:211], v[52:55]
	s_add_u32 m0, m0, 0x1000
	v_mfma_f32_16x16x32_bf16 v[48:51], v[236:239], v[186:189], v[48:51]
	global_load_lds_dwordx4 v158, s[28:29]
	v_mfma_f32_16x16x32_bf16 v[28:31], v[236:239], v[190:193], v[28:31]
	v_mfma_f32_16x16x32_bf16 v[96:99], v[236:239], v[194:197], v[96:99]
	s_add_u32 m0, m0, 0x1000
	v_mfma_f32_16x16x32_bf16 v[44:47], v[236:239], v[208:211], v[44:47]
	global_load_lds_dwordx4 v159, s[28:29]
	v_mfma_f32_16x16x32_bf16 v[40:43], v[240:243], v[186:189], v[40:43]
	v_mfma_f32_16x16x32_bf16 v[24:27], v[240:243], v[190:193], v[24:27]
	v_mfma_f32_16x16x32_bf16 v[84:87], v[240:243], v[194:197], v[84:87]
	v_mfma_f32_16x16x32_bf16 v[148:151], v[240:243], v[208:211], v[148:151]
	s_add_u32 s26, s26, 64
	s_addc_u32 s27, s27, 0
	s_add_u32 s28, s28, 0x10000
	s_addc_u32 s29, s29, 0
	s_add_u32 s25, s25, 24576
	s_cmp_eq_u32 s25, 73728
	s_cselect_b32 s25, 0, s25
	s_add_u32 s30, s30, 24576
	s_cmp_eq_u32 s30, 73728
	s_cselect_b32 s30, 0, s30
	s_waitcnt vmcnt(6)
	s_waitcnt lgkmcnt(0)
	s_barrier
	v_add_u32_e32 v248, s30, v155
	v_add_u32_e32 v249, s30, v160
	v_mfma_f32_16x16x32_bf16 v[128:131], v[16:19], v[0:3], v[128:131]
	ds_read_b128 v[186:189], v248
	v_mfma_f32_16x16x32_bf16 v[80:83], v[16:19], v[4:7], v[80:83]
	ds_read_b128 v[212:215], v249 offset:8192
	v_mfma_f32_16x16x32_bf16 v[108:111], v[16:19], v[8:11], v[108:111]
	ds_read_b128 v[190:193], v248 offset:1024
	v_mfma_f32_16x16x32_bf16 v[132:135], v[16:19], v[12:15], v[132:135]
	ds_read_b128 v[216:219], v249 offset:9216
	v_mfma_f32_16x16x32_bf16 v[120:123], v[20:23], v[0:3], v[120:123]
	ds_read_b128 v[194:197], v248 offset:2048
	v_mfma_f32_16x16x32_bf16 v[72:75], v[20:23], v[4:7], v[72:75]
	ds_read_b128 v[220:223], v249 offset:10240
	v_mfma_f32_16x16x32_bf16 v[112:115], v[20:23], v[8:11], v[112:115]
	ds_read_b128 v[208:211], v248 offset:3072
	v_mfma_f32_16x16x32_bf16 v[136:139], v[20:23], v[12:15], v[136:139]
	ds_read_b128 v[224:227], v249 offset:11264
	v_mfma_f32_16x16x32_bf16 v[104:107], v[162:165], v[0:3], v[104:107]
	ds_read_b128 v[228:231], v249 offset:12288
	v_mfma_f32_16x16x32_bf16 v[64:67], v[162:165], v[4:7], v[64:67]
	ds_read_b128 v[232:235], v249 offset:13312
	v_mfma_f32_16x16x32_bf16 v[116:119], v[162:165], v[8:11], v[116:119]
	ds_read_b128 v[236:239], v249 offset:14336
	v_mfma_f32_16x16x32_bf16 v[140:143], v[162:165], v[12:15], v[140:143]
	ds_read_b128 v[240:243], v249 offset:15360
	v_mfma_f32_16x16x32_bf16 v[100:103], v[166:169], v[0:3], v[100:103]
	v_mfma_f32_16x16x32_bf16 v[60:63], v[166:169], v[4:7], v[60:63]
	v_mfma_f32_16x16x32_bf16 v[124:127], v[166:169], v[8:11], v[124:127]
	v_mfma_f32_16x16x32_bf16 v[144:147], v[166:169], v[12:15], v[144:147]
	v_mfma_f32_16x16x32_bf16 v[68:71], v[170:173], v[0:3], v[68:71]
	v_mfma_f32_16x16x32_bf16 v[36:39], v[170:173], v[4:7], v[36:39]
	v_mfma_f32_16x16x32_bf16 v[88:91], v[170:173], v[8:11], v[88:91]
	v_mfma_f32_16x16x32_bf16 v[76:79], v[170:173], v[12:15], v[76:79]
	v_mfma_f32_16x16x32_bf16 v[56:59], v[174:177], v[0:3], v[56:59]
	v_mfma_f32_16x16x32_bf16 v[32:35], v[174:177], v[4:7], v[32:35]
	v_mfma_f32_16x16x32_bf16 v[92:95], v[174:177], v[8:11], v[92:95]
	v_mfma_f32_16x16x32_bf16 v[52:55], v[174:177], v[12:15], v[52:55]
	v_mfma_f32_16x16x32_bf16 v[48:51], v[178:181], v[0:3], v[48:51]
	v_mfma_f32_16x16x32_bf16 v[28:31], v[178:181], v[4:7], v[28:31]
	v_mfma_f32_16x16x32_bf16 v[96:99], v[178:181], v[8:11], v[96:99]
	v_mfma_f32_16x16x32_bf16 v[44:47], v[178:181], v[12:15], v[44:47]
	v_mfma_f32_16x16x32_bf16 v[40:43], v[182:185], v[0:3], v[40:43]
	v_mfma_f32_16x16x32_bf16 v[24:27], v[182:185], v[4:7], v[24:27]
	v_mfma_f32_16x16x32_bf16 v[84:87], v[182:185], v[8:11], v[84:87]
	v_mfma_f32_16x16x32_bf16 v[148:151], v[182:185], v[12:15], v[148:151]
	s_add_u32 s30, s30, 24576
	s_cmp_eq_u32 s30, 73728
	s_cselect_b32 s30, 0, s30
	s_waitcnt vmcnt(0)
	s_waitcnt lgkmcnt(0)
	s_barrier
	v_add_u32_e32 v248, s30, v155
	v_add_u32_e32 v249, s30, v160
	v_mfma_f32_16x16x32_bf16 v[128:131], v[212:215], v[186:189], v[128:131]
	ds_read_b128 v[0:3], v248
	v_mfma_f32_16x16x32_bf16 v[80:83], v[212:215], v[190:193], v[80:83]
	ds_read_b128 v[16:19], v249 offset:8192
	v_mfma_f32_16x16x32_bf16 v[108:111], v[212:215], v[194:197], v[108:111]
	ds_read_b128 v[4:7], v248 offset:1024
	v_mfma_f32_16x16x32_bf16 v[132:135], v[212:215], v[208:211], v[132:135]
	ds_read_b128 v[20:23], v249 offset:9216
	v_mfma_f32_16x16x32_bf16 v[120:123], v[216:219], v[186:189], v[120:123]
	ds_read_b128 v[8:11], v248 offset:2048
	v_mfma_f32_16x16x32_bf16 v[72:75], v[216:219], v[190:193], v[72:75]
	ds_read_b128 v[162:165], v249 offset:10240
	v_mfma_f32_16x16x32_bf16 v[112:115], v[216:219], v[194:197], v[112:115]
	ds_read_b128 v[12:15], v248 offset:3072
	v_mfma_f32_16x16x32_bf16 v[136:139], v[216:219], v[208:211], v[136:139]
	ds_read_b128 v[166:169], v249 offset:11264
	v_mfma_f32_16x16x32_bf16 v[104:107], v[220:223], v[186:189], v[104:107]
	ds_read_b128 v[170:173], v249 offset:12288
	v_mfma_f32_16x16x32_bf16 v[64:67], v[220:223], v[190:193], v[64:67]
	ds_read_b128 v[174:177], v249 offset:13312
	v_mfma_f32_16x16x32_bf16 v[116:119], v[220:223], v[194:197], v[116:119]
	ds_read_b128 v[178:181], v249 offset:14336
	v_mfma_f32_16x16x32_bf16 v[140:143], v[220:223], v[208:211], v[140:143]
	ds_read_b128 v[182:185], v249 offset:15360
	v_mfma_f32_16x16x32_bf16 v[100:103], v[224:227], v[186:189], v[100:103]
	v_mfma_f32_16x16x32_bf16 v[60:63], v[224:227], v[190:193], v[60:63]
	v_mfma_f32_16x16x32_bf16 v[124:127], v[224:227], v[194:197], v[124:127]
	v_mfma_f32_16x16x32_bf16 v[144:147], v[224:227], v[208:211], v[144:147]
	v_mfma_f32_16x16x32_bf16 v[68:71], v[228:231], v[186:189], v[68:71]
	v_mfma_f32_16x16x32_bf16 v[36:39], v[228:231], v[190:193], v[36:39]
	v_mfma_f32_16x16x32_bf16 v[88:91], v[228:231], v[194:197], v[88:91]
	v_mfma_f32_16x16x32_bf16 v[76:79], v[228:231], v[208:211], v[76:79]
	v_mfma_f32_16x16x32_bf16 v[56:59], v[232:235], v[186:189], v[56:59]
	v_mfma_f32_16x16x32_bf16 v[32:35], v[232:235], v[190:193], v[32:35]
	v_mfma_f32_16x16x32_bf16 v[92:95], v[232:235], v[194:197], v[92:95]
	v_mfma_f32_16x16x32_bf16 v[52:55], v[232:235], v[208:211], v[52:55]
	v_mfma_f32_16x16x32_bf16 v[48:51], v[236:239], v[186:189], v[48:51]
	v_mfma_f32_16x16x32_bf16 v[28:31], v[236:239], v[190:193], v[28:31]
	v_mfma_f32_16x16x32_bf16 v[96:99], v[236:239], v[194:197], v[96:99]
	v_mfma_f32_16x16x32_bf16 v[44:47], v[236:239], v[208:211], v[44:47]
	v_mfma_f32_16x16x32_bf16 v[40:43], v[240:243], v[186:189], v[40:43]
	v_mfma_f32_16x16x32_bf16 v[24:27], v[240:243], v[190:193], v[24:27]
	v_mfma_f32_16x16x32_bf16 v[84:87], v[240:243], v[194:197], v[84:87]
	v_mfma_f32_16x16x32_bf16 v[148:151], v[240:243], v[208:211], v[148:151]
	s_add_u32 s30, s30, 24576
	s_cmp_eq_u32 s30, 73728
	s_cselect_b32 s30, 0, s30
	s_waitcnt lgkmcnt(0)
	s_barrier
	v_mfma_f32_16x16x32_bf16 v[128:131], v[16:19], v[0:3], v[128:131]
	v_mfma_f32_16x16x32_bf16 v[80:83], v[16:19], v[4:7], v[80:83]
	v_mfma_f32_16x16x32_bf16 v[108:111], v[16:19], v[8:11], v[108:111]
	v_mfma_f32_16x16x32_bf16 v[132:135], v[16:19], v[12:15], v[132:135]
	v_mfma_f32_16x16x32_bf16 v[120:123], v[20:23], v[0:3], v[120:123]
	v_mfma_f32_16x16x32_bf16 v[72:75], v[20:23], v[4:7], v[72:75]
	v_mfma_f32_16x16x32_bf16 v[112:115], v[20:23], v[8:11], v[112:115]
	v_mfma_f32_16x16x32_bf16 v[136:139], v[20:23], v[12:15], v[136:139]
	v_mfma_f32_16x16x32_bf16 v[104:107], v[162:165], v[0:3], v[104:107]
	v_mfma_f32_16x16x32_bf16 v[64:67], v[162:165], v[4:7], v[64:67]
	v_mfma_f32_16x16x32_bf16 v[116:119], v[162:165], v[8:11], v[116:119]
	v_mfma_f32_16x16x32_bf16 v[140:143], v[162:165], v[12:15], v[140:143]
	v_mfma_f32_16x16x32_bf16 v[100:103], v[166:169], v[0:3], v[100:103]
	v_mfma_f32_16x16x32_bf16 v[60:63], v[166:169], v[4:7], v[60:63]
	v_mfma_f32_16x16x32_bf16 v[124:127], v[166:169], v[8:11], v[124:127]
	v_mfma_f32_16x16x32_bf16 v[144:147], v[166:169], v[12:15], v[144:147]
	v_mfma_f32_16x16x32_bf16 v[68:71], v[170:173], v[0:3], v[68:71]
	v_mfma_f32_16x16x32_bf16 v[36:39], v[170:173], v[4:7], v[36:39]
	v_mfma_f32_16x16x32_bf16 v[88:91], v[170:173], v[8:11], v[88:91]
	v_mfma_f32_16x16x32_bf16 v[76:79], v[170:173], v[12:15], v[76:79]
	v_mfma_f32_16x16x32_bf16 v[56:59], v[174:177], v[0:3], v[56:59]
	v_mfma_f32_16x16x32_bf16 v[32:35], v[174:177], v[4:7], v[32:35]
	v_mfma_f32_16x16x32_bf16 v[92:95], v[174:177], v[8:11], v[92:95]
	v_mfma_f32_16x16x32_bf16 v[52:55], v[174:177], v[12:15], v[52:55]
	v_mfma_f32_16x16x32_bf16 v[48:51], v[178:181], v[0:3], v[48:51]
	v_mfma_f32_16x16x32_bf16 v[28:31], v[178:181], v[4:7], v[28:31]
	v_mfma_f32_16x16x32_bf16 v[96:99], v[178:181], v[8:11], v[96:99]
	v_mfma_f32_16x16x32_bf16 v[44:47], v[178:181], v[12:15], v[44:47]
	v_mfma_f32_16x16x32_bf16 v[40:43], v[182:185], v[0:3], v[40:43]
	v_mfma_f32_16x16x32_bf16 v[24:27], v[182:185], v[4:7], v[24:27]
	v_mfma_f32_16x16x32_bf16 v[84:87], v[182:185], v[8:11], v[84:87]
	v_mfma_f32_16x16x32_bf16 v[148:151], v[182:185], v[12:15], v[148:151]
	v_mov_b32 v250, v198
	s_nop 0
	v_and_b32_e32 v251, 15, v250
	v_bfe_u32 v156, v250, 4, 2
	v_bfe_u32 v157, v250, 6, 1
	v_bfe_u32 v158, v250, 7, 1
	v_lshl_add_u32 v158, v158, 6, s10
	v_add_u32_e32 v158, v158, v251
	v_lshl_add_u32 v157, v157, 7, s11
	v_lshl_add_u32 v159, v156, 2, v157
	v_lshlrev_b32_e32 v246, 2, v159
	v_lshl_add_u32 v244, v158, 12, v246
	v_lshlrev_b32_e32 v161, 1, v159
	v_lshl_add_u32 v245, v158, 11, v161
	v_and_b32_e32 v254, 1, v156
	v_mul_u32_u24_e32 v254, 24, v254
	v_add_u32_e32 v254, v254, v245
	v_lshrrev_b32_e32 v161, 6, v157
	v_lshlrev_b32_e32 v161, 2, v161
	v_lshl_add_u32 v247, v158, 6, v161
	v_xor_b32_e32 v248, 16, v200
	v_lshlrev_b32_e32 v248, 2, v248
	v_xor_b32_e32 v249, 32, v200
	v_lshlrev_b32_e32 v249, 2, v249
	s_mov_b32 s24, s6
	s_mov_b32 s25, s7
	s_mov_b32 s26, s78
	s_mov_b32 s27, s79
	v_readlane_b32 s28, v253, 21
	v_readlane_b32 s29, v253, 22
	s_mov_b32 s30, s94
	s_mov_b32 s31, s95
	global_load_dwordx4 v[208:211], v246, s[8:9]
	global_load_dwordx4 v[212:215], v246, s[8:9] offset:64
	global_load_dwordx4 v[216:219], v246, s[8:9] offset:128
	global_load_dwordx4 v[220:223], v246, s[8:9] offset:192
	global_load_dwordx4 v[224:227], v246, s[8:9] offset:256
	global_load_dwordx4 v[228:231], v246, s[8:9] offset:320
	global_load_dwordx4 v[232:235], v246, s[8:9] offset:384
	global_load_dwordx4 v[236:239], v246, s[8:9] offset:448
	global_load_dwordx4 v[0:3], v244, s[24:25]
	global_load_dwordx4 v[4:7], v244, s[24:25] offset:64
	global_load_dwordx4 v[8:11], v244, s[24:25] offset:128
	global_load_dwordx4 v[12:15], v244, s[24:25] offset:192
	global_load_dwordx4 v[16:19], v244, s[24:25] offset:256
	global_load_dwordx4 v[20:23], v244, s[24:25] offset:320
	global_load_dwordx4 v[162:165], v244, s[24:25] offset:384
	global_load_dwordx4 v[166:169], v244, s[24:25] offset:448
	s_add_u32 s24, s24, 0x10000
	s_addc_u32 s25, s25, 0
	global_load_dwordx4 v[170:173], v244, s[24:25]
	global_load_dwordx4 v[174:177], v244, s[24:25] offset:64
	global_load_dwordx4 v[178:181], v244, s[24:25] offset:128
	global_load_dwordx4 v[182:185], v244, s[24:25] offset:192
	global_load_dwordx4 v[186:189], v244, s[24:25] offset:256
	global_load_dwordx4 v[190:193], v244, s[24:25] offset:320
	global_load_dwordx4 v[194:197], v244, s[24:25] offset:384
	global_load_dwordx4 v[240:243], v244, s[24:25] offset:448
	s_add_u32 s24, s24, 0x10000
	s_addc_u32 s25, s25, 0
	s_waitcnt vmcnt(12)
	v_add_f32_e32 v0, v128, v0
	v_add_f32_e32 v1, v129, v1
	v_add_f32_e32 v2, v130, v2
	v_add_f32_e32 v3, v131, v3
	global_store_dwordx4 v244, v[0:3], s[26:27]
	v_mul_f32_e32 v158, v0, v0
	v_mul_f32_e32 v159, v1, v1
	v_mul_f32_e32 v250, v2, v2
	v_mul_f32_e32 v251, v3, v3
	v_add_f32_e32 v158, v158, v159
	v_add_f32_e32 v250, v250, v251
	v_add_f32_e32 v161, v158, v250
	v_mul_f32_e32 v156, v0, v208
	v_mul_f32_e32 v157, v1, v209
	v_mul_f32_e32 v158, v2, v210
	v_mul_f32_e32 v159, v3, v211
	v_cvt_pk_bf16_f32 v156, v156, v157
	v_cvt_pk_bf16_f32 v157, v158, v159
	v_add_f32_e32 v4, v120, v4
	v_add_f32_e32 v5, v121, v5
	v_add_f32_e32 v6, v122, v6
	v_add_f32_e32 v7, v123, v7
	global_store_dwordx4 v244, v[4:7], s[26:27] offset:64
	v_mul_f32_e32 v158, v4, v4
	v_mul_f32_e32 v159, v5, v5
	v_mul_f32_e32 v250, v6, v6
	v_mul_f32_e32 v251, v7, v7
	v_add_f32_e32 v158, v158, v159
	v_add_f32_e32 v250, v250, v251
	v_add_f32_e32 v158, v158, v250
	v_add_f32_e32 v161, v161, v158
	v_mul_f32_e32 v158, v4, v212
	v_mul_f32_e32 v159, v5, v213
	v_mul_f32_e32 v250, v6, v214
	v_mul_f32_e32 v251, v7, v215
	v_cvt_pk_bf16_f32 v158, v158, v159
	v_cvt_pk_bf16_f32 v159, v250, v251
	s_nop 1
	v_permlane16_swap_b32_e32 v156, v158
	v_permlane16_swap_b32_e32 v157, v159
	global_store_dwordx4 v254, v[156:159], s[28:29]
	v_add_f32_e32 v8, v104, v8
	v_add_f32_e32 v9, v105, v9
	v_add_f32_e32 v10, v106, v10
	v_add_f32_e32 v11, v107, v11
	global_store_dwordx4 v244, v[8:11], s[26:27] offset:128
	v_mul_f32_e32 v158, v8, v8
	v_mul_f32_e32 v159, v9, v9
	v_mul_f32_e32 v250, v10, v10
	v_mul_f32_e32 v251, v11, v11
	v_add_f32_e32 v158, v158, v159
	v_add_f32_e32 v250, v250, v251
	v_add_f32_e32 v158, v158, v250
	v_add_f32_e32 v161, v161, v158
	v_mul_f32_e32 v156, v8, v216
	v_mul_f32_e32 v157, v9, v217
	v_mul_f32_e32 v158, v10, v218
	v_mul_f32_e32 v159, v11, v219
	v_cvt_pk_bf16_f32 v156, v156, v157
	v_cvt_pk_bf16_f32 v157, v158, v159
	v_add_f32_e32 v12, v100, v12
	v_add_f32_e32 v13, v101, v13
	v_add_f32_e32 v14, v102, v14
	v_add_f32_e32 v15, v103, v15
	global_store_dwordx4 v244, v[12:15], s[26:27] offset:192
	v_mul_f32_e32 v158, v12, v12
	v_mul_f32_e32 v159, v13, v13
	v_mul_f32_e32 v250, v14, v14
	v_mul_f32_e32 v251, v15, v15
	v_add_f32_e32 v158, v158, v159
	v_add_f32_e32 v250, v250, v251
	v_add_f32_e32 v158, v158, v250
	v_add_f32_e32 v161, v161, v158
	v_mul_f32_e32 v158, v12, v220
	v_mul_f32_e32 v159, v13, v221
	v_mul_f32_e32 v250, v14, v222
	v_mul_f32_e32 v251, v15, v223
	v_cvt_pk_bf16_f32 v158, v158, v159
	v_cvt_pk_bf16_f32 v159, v250, v251
	s_nop 1
	v_permlane16_swap_b32_e32 v156, v158
	v_permlane16_swap_b32_e32 v157, v159
	global_store_dwordx4 v254, v[156:159], s[28:29] offset:64
	ds_bpermute_b32 v158, v248, v161
	s_waitcnt lgkmcnt(0)
	v_add_f32_e32 v161, v161, v158
	ds_bpermute_b32 v158, v249, v161
	s_waitcnt lgkmcnt(0)
	v_add_f32_e32 v161, v161, v158
	global_store_dword v247, v161, s[30:31]
	global_load_dwordx4 v[0:3], v244, s[24:25]
	global_load_dwordx4 v[4:7], v244, s[24:25] offset:64
	global_load_dwordx4 v[8:11], v244, s[24:25] offset:128
	global_load_dwordx4 v[12:15], v244, s[24:25] offset:192
	s_waitcnt vmcnt(19)
	v_add_f32_e32 v16, v68, v16
	v_add_f32_e32 v17, v69, v17
	v_add_f32_e32 v18, v70, v18
	v_add_f32_e32 v19, v71, v19
	global_store_dwordx4 v244, v[16:19], s[26:27] offset:256
	v_mul_f32_e32 v158, v16, v16
	v_mul_f32_e32 v159, v17, v17
	v_mul_f32_e32 v250, v18, v18
	v_mul_f32_e32 v251, v19, v19
	v_add_f32_e32 v158, v158, v159
	v_add_f32_e32 v250, v250, v251
	v_add_f32_e32 v161, v158, v250
	v_mul_f32_e32 v156, v16, v224
	v_mul_f32_e32 v157, v17, v225
	v_mul_f32_e32 v158, v18, v226
	v_mul_f32_e32 v159, v19, v227
	v_cvt_pk_bf16_f32 v156, v156, v157
	v_cvt_pk_bf16_f32 v157, v158, v159
	v_add_f32_e32 v20, v56, v20
	v_add_f32_e32 v21, v57, v21
	v_add_f32_e32 v22, v58, v22
	v_add_f32_e32 v23, v59, v23
	global_store_dwordx4 v244, v[20:23], s[26:27] offset:320
	v_mul_f32_e32 v158, v20, v20
	v_mul_f32_e32 v159, v21, v21
	v_mul_f32_e32 v250, v22, v22
	v_mul_f32_e32 v251, v23, v23
	v_add_f32_e32 v158, v158, v159
	v_add_f32_e32 v250, v250, v251
	v_add_f32_e32 v158, v158, v250
	v_add_f32_e32 v161, v161, v158
	v_mul_f32_e32 v158, v20, v228
	v_mul_f32_e32 v159, v21, v229
	v_mul_f32_e32 v250, v22, v230
	v_mul_f32_e32 v251, v23, v231
	v_cvt_pk_bf16_f32 v158, v158, v159
	v_cvt_pk_bf16_f32 v159, v250, v251
	s_nop 1
	v_permlane16_swap_b32_e32 v156, v158
	v_permlane16_swap_b32_e32 v157, v159
	global_store_dwordx4 v254, v[156:159], s[28:29] offset:128
	v_add_f32_e32 v162, v48, v162
	v_add_f32_e32 v163, v49, v163
	v_add_f32_e32 v164, v50, v164
	v_add_f32_e32 v165, v51, v165
	global_store_dwordx4 v244, v[162:165], s[26:27] offset:384
	v_mul_f32_e32 v158, v162, v162
	v_mul_f32_e32 v159, v163, v163
	v_mul_f32_e32 v250, v164, v164
	v_mul_f32_e32 v251, v165, v165
	v_add_f32_e32 v158, v158, v159
	v_add_f32_e32 v250, v250, v251
	v_add_f32_e32 v158, v158, v250
	v_add_f32_e32 v161, v161, v158
	v_mul_f32_e32 v156, v162, v232
	v_mul_f32_e32 v157, v163, v233
	v_mul_f32_e32 v158, v164, v234
	v_mul_f32_e32 v159, v165, v235
	v_cvt_pk_bf16_f32 v156, v156, v157
	v_cvt_pk_bf16_f32 v157, v158, v159
	v_add_f32_e32 v166, v40, v166
	v_add_f32_e32 v167, v41, v167
	v_add_f32_e32 v168, v42, v168
	v_add_f32_e32 v169, v43, v169
	global_store_dwordx4 v244, v[166:169], s[26:27] offset:448
	v_mul_f32_e32 v158, v166, v166
	v_mul_f32_e32 v159, v167, v167
	v_mul_f32_e32 v250, v168, v168
	v_mul_f32_e32 v251, v169, v169
	v_add_f32_e32 v158, v158, v159
	v_add_f32_e32 v250, v250, v251
	v_add_f32_e32 v158, v158, v250
	v_add_f32_e32 v161, v161, v158
	v_mul_f32_e32 v158, v166, v236
	v_mul_f32_e32 v159, v167, v237
	v_mul_f32_e32 v250, v168, v238
	v_mul_f32_e32 v251, v169, v239
	v_cvt_pk_bf16_f32 v158, v158, v159
	v_cvt_pk_bf16_f32 v159, v250, v251
	s_nop 1
	v_permlane16_swap_b32_e32 v156, v158
	v_permlane16_swap_b32_e32 v157, v159
	global_store_dwordx4 v254, v[156:159], s[28:29] offset:192
	ds_bpermute_b32 v158, v248, v161
	s_waitcnt lgkmcnt(0)
	v_add_f32_e32 v161, v161, v158
	ds_bpermute_b32 v158, v249, v161
	s_waitcnt lgkmcnt(0)
	v_add_f32_e32 v161, v161, v158
	global_store_dword v247, v161, s[30:31] offset:4
	s_add_u32 s26, s26, 0x10000
	s_addc_u32 s27, s27, 0
	s_add_u32 s28, s28, 0x8000
	s_addc_u32 s29, s29, 0
	s_add_u32 s30, s30, 0x400
	s_addc_u32 s31, s31, 0
	global_load_dwordx4 v[16:19], v244, s[24:25] offset:256
	global_load_dwordx4 v[20:23], v244, s[24:25] offset:320
	global_load_dwordx4 v[162:165], v244, s[24:25] offset:384
	global_load_dwordx4 v[166:169], v244, s[24:25] offset:448
	s_add_u32 s24, s24, 0x10000
	s_addc_u32 s25, s25, 0
	s_waitcnt vmcnt(26)
	v_add_f32_e32 v170, v80, v170
	v_add_f32_e32 v171, v81, v171
	v_add_f32_e32 v172, v82, v172
	v_add_f32_e32 v173, v83, v173
	global_store_dwordx4 v244, v[170:173], s[26:27]
	v_mul_f32_e32 v158, v170, v170
	v_mul_f32_e32 v159, v171, v171
	v_mul_f32_e32 v250, v172, v172
	v_mul_f32_e32 v251, v173, v173
	v_add_f32_e32 v158, v158, v159
	v_add_f32_e32 v250, v250, v251
	v_add_f32_e32 v161, v158, v250
	v_mul_f32_e32 v156, v170, v208
	v_mul_f32_e32 v157, v171, v209
	v_mul_f32_e32 v158, v172, v210
	v_mul_f32_e32 v159, v173, v211
	v_cvt_pk_bf16_f32 v156, v156, v157
	v_cvt_pk_bf16_f32 v157, v158, v159
	v_add_f32_e32 v174, v72, v174
	v_add_f32_e32 v175, v73, v175
	v_add_f32_e32 v176, v74, v176
	v_add_f32_e32 v177, v75, v177
	global_store_dwordx4 v244, v[174:177], s[26:27] offset:64
	v_mul_f32_e32 v158, v174, v174
	v_mul_f32_e32 v159, v175, v175
	v_mul_f32_e32 v250, v176, v176
	v_mul_f32_e32 v251, v177, v177
	v_add_f32_e32 v158, v158, v159
	v_add_f32_e32 v250, v250, v251
	v_add_f32_e32 v158, v158, v250
	v_add_f32_e32 v161, v161, v158
	v_mul_f32_e32 v158, v174, v212
	v_mul_f32_e32 v159, v175, v213
	v_mul_f32_e32 v250, v176, v214
	v_mul_f32_e32 v251, v177, v215
	v_cvt_pk_bf16_f32 v158, v158, v159
	v_cvt_pk_bf16_f32 v159, v250, v251
	s_nop 1
	v_permlane16_swap_b32_e32 v156, v158
	v_permlane16_swap_b32_e32 v157, v159
	global_store_dwordx4 v254, v[156:159], s[28:29]
	v_add_f32_e32 v178, v64, v178
	v_add_f32_e32 v179, v65, v179
	v_add_f32_e32 v180, v66, v180
	v_add_f32_e32 v181, v67, v181
	global_store_dwordx4 v244, v[178:181], s[26:27] offset:128
	v_mul_f32_e32 v158, v178, v178
	v_mul_f32_e32 v159, v179, v179
	v_mul_f32_e32 v250, v180, v180
	v_mul_f32_e32 v251, v181, v181
	v_add_f32_e32 v158, v158, v159
	v_add_f32_e32 v250, v250, v251
	v_add_f32_e32 v158, v158, v250
	v_add_f32_e32 v161, v161, v158
	v_mul_f32_e32 v156, v178, v216
	v_mul_f32_e32 v157, v179, v217
	v_mul_f32_e32 v158, v180, v218
	v_mul_f32_e32 v159, v181, v219
	v_cvt_pk_bf16_f32 v156, v156, v157
	v_cvt_pk_bf16_f32 v157, v158, v159
	v_add_f32_e32 v182, v60, v182
	v_add_f32_e32 v183, v61, v183
	v_add_f32_e32 v184, v62, v184
	v_add_f32_e32 v185, v63, v185
	global_store_dwordx4 v244, v[182:185], s[26:27] offset:192
	v_mul_f32_e32 v158, v182, v182
	v_mul_f32_e32 v159, v183, v183
	v_mul_f32_e32 v250, v184, v184
	v_mul_f32_e32 v251, v185, v185
	v_add_f32_e32 v158, v158, v159
	v_add_f32_e32 v250, v250, v251
	v_add_f32_e32 v158, v158, v250
	v_add_f32_e32 v161, v161, v158
	v_mul_f32_e32 v158, v182, v220
	v_mul_f32_e32 v159, v183, v221
	v_mul_f32_e32 v250, v184, v222
	v_mul_f32_e32 v251, v185, v223
	v_cvt_pk_bf16_f32 v158, v158, v159
	v_cvt_pk_bf16_f32 v159, v250, v251
	s_nop 1
	v_permlane16_swap_b32_e32 v156, v158
	v_permlane16_swap_b32_e32 v157, v159
	global_store_dwordx4 v254, v[156:159], s[28:29] offset:64
	ds_bpermute_b32 v158, v248, v161
	s_waitcnt lgkmcnt(0)
	v_add_f32_e32 v161, v161, v158
	ds_bpermute_b32 v158, v249, v161
	s_waitcnt lgkmcnt(0)
	v_add_f32_e32 v161, v161, v158
	global_store_dword v247, v161, s[30:31]
	global_load_dwordx4 v[170:173], v244, s[24:25]
	global_load_dwordx4 v[174:177], v244, s[24:25] offset:64
	global_load_dwordx4 v[178:181], v244, s[24:25] offset:128
	global_load_dwordx4 v[182:185], v244, s[24:25] offset:192
	s_waitcnt vmcnt(33)
	v_add_f32_e32 v186, v36, v186
	v_add_f32_e32 v187, v37, v187
	v_add_f32_e32 v188, v38, v188
	v_add_f32_e32 v189, v39, v189
	global_store_dwordx4 v244, v[186:189], s[26:27] offset:256
	v_mul_f32_e32 v158, v186, v186
	v_mul_f32_e32 v159, v187, v187
	v_mul_f32_e32 v250, v188, v188
	v_mul_f32_e32 v251, v189, v189
	v_add_f32_e32 v158, v158, v159
	v_add_f32_e32 v250, v250, v251
	v_add_f32_e32 v161, v158, v250
	v_mul_f32_e32 v156, v186, v224
	v_mul_f32_e32 v157, v187, v225
	v_mul_f32_e32 v158, v188, v226
	v_mul_f32_e32 v159, v189, v227
	v_cvt_pk_bf16_f32 v156, v156, v157
	v_cvt_pk_bf16_f32 v157, v158, v159
	v_add_f32_e32 v190, v32, v190
	v_add_f32_e32 v191, v33, v191
	v_add_f32_e32 v192, v34, v192
	v_add_f32_e32 v193, v35, v193
	global_store_dwordx4 v244, v[190:193], s[26:27] offset:320
	v_mul_f32_e32 v158, v190, v190
	v_mul_f32_e32 v159, v191, v191
	v_mul_f32_e32 v250, v192, v192
	v_mul_f32_e32 v251, v193, v193
	v_add_f32_e32 v158, v158, v159
	v_add_f32_e32 v250, v250, v251
	v_add_f32_e32 v158, v158, v250
	v_add_f32_e32 v161, v161, v158
	v_mul_f32_e32 v158, v190, v228
	v_mul_f32_e32 v159, v191, v229
	v_mul_f32_e32 v250, v192, v230
	v_mul_f32_e32 v251, v193, v231
	v_cvt_pk_bf16_f32 v158, v158, v159
	v_cvt_pk_bf16_f32 v159, v250, v251
	s_nop 1
	v_permlane16_swap_b32_e32 v156, v158
	v_permlane16_swap_b32_e32 v157, v159
	global_store_dwordx4 v254, v[156:159], s[28:29] offset:128
	v_add_f32_e32 v194, v28, v194
	v_add_f32_e32 v195, v29, v195
	v_add_f32_e32 v196, v30, v196
	v_add_f32_e32 v197, v31, v197
	global_store_dwordx4 v244, v[194:197], s[26:27] offset:384
	v_mul_f32_e32 v158, v194, v194
	v_mul_f32_e32 v159, v195, v195
	v_mul_f32_e32 v250, v196, v196
	v_mul_f32_e32 v251, v197, v197
	v_add_f32_e32 v158, v158, v159
	v_add_f32_e32 v250, v250, v251
	v_add_f32_e32 v158, v158, v250
	v_add_f32_e32 v161, v161, v158
	v_mul_f32_e32 v156, v194, v232
	v_mul_f32_e32 v157, v195, v233
	v_mul_f32_e32 v158, v196, v234
	v_mul_f32_e32 v159, v197, v235
	v_cvt_pk_bf16_f32 v156, v156, v157
	v_cvt_pk_bf16_f32 v157, v158, v159
	v_add_f32_e32 v240, v24, v240
	v_add_f32_e32 v241, v25, v241
	v_add_f32_e32 v242, v26, v242
	v_add_f32_e32 v243, v27, v243
	global_store_dwordx4 v244, v[240:243], s[26:27] offset:448
	v_mul_f32_e32 v158, v240, v240
	v_mul_f32_e32 v159, v241, v241
	v_mul_f32_e32 v250, v242, v242
	v_mul_f32_e32 v251, v243, v243
	v_add_f32_e32 v158, v158, v159
	v_add_f32_e32 v250, v250, v251
	v_add_f32_e32 v158, v158, v250
	v_add_f32_e32 v161, v161, v158
	v_mul_f32_e32 v158, v240, v236
	v_mul_f32_e32 v159, v241, v237
	v_mul_f32_e32 v250, v242, v238
	v_mul_f32_e32 v251, v243, v239
	v_cvt_pk_bf16_f32 v158, v158, v159
	v_cvt_pk_bf16_f32 v159, v250, v251
	s_nop 1
	v_permlane16_swap_b32_e32 v156, v158
	v_permlane16_swap_b32_e32 v157, v159
	global_store_dwordx4 v254, v[156:159], s[28:29] offset:192
	ds_bpermute_b32 v158, v248, v161
	s_waitcnt lgkmcnt(0)
	v_add_f32_e32 v161, v161, v158
	ds_bpermute_b32 v158, v249, v161
	s_waitcnt lgkmcnt(0)
	v_add_f32_e32 v161, v161, v158
	global_store_dword v247, v161, s[30:31] offset:4
	s_add_u32 s26, s26, 0x10000
	s_addc_u32 s27, s27, 0
	s_add_u32 s28, s28, 0x8000
	s_addc_u32 s29, s29, 0
	s_add_u32 s30, s30, 0x400
	s_addc_u32 s31, s31, 0
	global_load_dwordx4 v[186:189], v244, s[24:25] offset:256
	global_load_dwordx4 v[190:193], v244, s[24:25] offset:320
	global_load_dwordx4 v[194:197], v244, s[24:25] offset:384
	global_load_dwordx4 v[240:243], v244, s[24:25] offset:448
	s_add_u32 s24, s24, 0x10000
	s_addc_u32 s25, s25, 0
	s_waitcnt vmcnt(33)
	v_add_f32_e32 v0, v108, v0
	v_add_f32_e32 v1, v109, v1
	v_add_f32_e32 v2, v110, v2
	v_add_f32_e32 v3, v111, v3
	global_store_dwordx4 v244, v[0:3], s[26:27]
	v_mul_f32_e32 v158, v0, v0
	v_mul_f32_e32 v159, v1, v1
	v_mul_f32_e32 v250, v2, v2
	v_mul_f32_e32 v251, v3, v3
	v_add_f32_e32 v158, v158, v159
	v_add_f32_e32 v250, v250, v251
	v_add_f32_e32 v161, v158, v250
	v_mul_f32_e32 v156, v0, v208
	v_mul_f32_e32 v157, v1, v209
	v_mul_f32_e32 v158, v2, v210
	v_mul_f32_e32 v159, v3, v211
	v_cvt_pk_bf16_f32 v156, v156, v157
	v_cvt_pk_bf16_f32 v157, v158, v159
	v_add_f32_e32 v4, v112, v4
	v_add_f32_e32 v5, v113, v5
	v_add_f32_e32 v6, v114, v6
	v_add_f32_e32 v7, v115, v7
	global_store_dwordx4 v244, v[4:7], s[26:27] offset:64
	v_mul_f32_e32 v158, v4, v4
	v_mul_f32_e32 v159, v5, v5
	v_mul_f32_e32 v250, v6, v6
	v_mul_f32_e32 v251, v7, v7
	v_add_f32_e32 v158, v158, v159
	v_add_f32_e32 v250, v250, v251
	v_add_f32_e32 v158, v158, v250
	v_add_f32_e32 v161, v161, v158
	v_mul_f32_e32 v158, v4, v212
	v_mul_f32_e32 v159, v5, v213
	v_mul_f32_e32 v250, v6, v214
	v_mul_f32_e32 v251, v7, v215
	v_cvt_pk_bf16_f32 v158, v158, v159
	v_cvt_pk_bf16_f32 v159, v250, v251
	s_nop 1
	v_permlane16_swap_b32_e32 v156, v158
	v_permlane16_swap_b32_e32 v157, v159
	global_store_dwordx4 v254, v[156:159], s[28:29]
	v_add_f32_e32 v8, v116, v8
	v_add_f32_e32 v9, v117, v9
	v_add_f32_e32 v10, v118, v10
	v_add_f32_e32 v11, v119, v11
	global_store_dwordx4 v244, v[8:11], s[26:27] offset:128
	v_mul_f32_e32 v158, v8, v8
	v_mul_f32_e32 v159, v9, v9
	v_mul_f32_e32 v250, v10, v10
	v_mul_f32_e32 v251, v11, v11
	v_add_f32_e32 v158, v158, v159
	v_add_f32_e32 v250, v250, v251
	v_add_f32_e32 v158, v158, v250
	v_add_f32_e32 v161, v161, v158
	v_mul_f32_e32 v156, v8, v216
	v_mul_f32_e32 v157, v9, v217
	v_mul_f32_e32 v158, v10, v218
	v_mul_f32_e32 v159, v11, v219
	v_cvt_pk_bf16_f32 v156, v156, v157
	v_cvt_pk_bf16_f32 v157, v158, v159
	v_add_f32_e32 v12, v124, v12
	v_add_f32_e32 v13, v125, v13
	v_add_f32_e32 v14, v126, v14
	v_add_f32_e32 v15, v127, v15
	global_store_dwordx4 v244, v[12:15], s[26:27] offset:192
	v_mul_f32_e32 v158, v12, v12
	v_mul_f32_e32 v159, v13, v13
	v_mul_f32_e32 v250, v14, v14
	v_mul_f32_e32 v251, v15, v15
	v_add_f32_e32 v158, v158, v159
	v_add_f32_e32 v250, v250, v251
	v_add_f32_e32 v158, v158, v250
	v_add_f32_e32 v161, v161, v158
	v_mul_f32_e32 v158, v12, v220
	v_mul_f32_e32 v159, v13, v221
	v_mul_f32_e32 v250, v14, v222
	v_mul_f32_e32 v251, v15, v223
	v_cvt_pk_bf16_f32 v158, v158, v159
	v_cvt_pk_bf16_f32 v159, v250, v251
	s_nop 1
	v_permlane16_swap_b32_e32 v156, v158
	v_permlane16_swap_b32_e32 v157, v159
	global_store_dwordx4 v254, v[156:159], s[28:29] offset:64
	ds_bpermute_b32 v158, v248, v161
	s_waitcnt lgkmcnt(0)
	v_add_f32_e32 v161, v161, v158
	ds_bpermute_b32 v158, v249, v161
	s_waitcnt lgkmcnt(0)
	v_add_f32_e32 v161, v161, v158
	global_store_dword v247, v161, s[30:31]
	s_waitcnt vmcnt(29)
	v_add_f32_e32 v16, v88, v16
	v_add_f32_e32 v17, v89, v17
	v_add_f32_e32 v18, v90, v18
	v_add_f32_e32 v19, v91, v19
	global_store_dwordx4 v244, v[16:19], s[26:27] offset:256
	v_mul_f32_e32 v158, v16, v16
	v_mul_f32_e32 v159, v17, v17
	v_mul_f32_e32 v250, v18, v18
	v_mul_f32_e32 v251, v19, v19
	v_add_f32_e32 v158, v158, v159
	v_add_f32_e32 v250, v250, v251
	v_add_f32_e32 v161, v158, v250
	v_mul_f32_e32 v156, v16, v224
	v_mul_f32_e32 v157, v17, v225
	v_mul_f32_e32 v158, v18, v226
	v_mul_f32_e32 v159, v19, v227
	v_cvt_pk_bf16_f32 v156, v156, v157
	v_cvt_pk_bf16_f32 v157, v158, v159
	v_add_f32_e32 v20, v92, v20
	v_add_f32_e32 v21, v93, v21
	v_add_f32_e32 v22, v94, v22
	v_add_f32_e32 v23, v95, v23
	global_store_dwordx4 v244, v[20:23], s[26:27] offset:320
	v_mul_f32_e32 v158, v20, v20
	v_mul_f32_e32 v159, v21, v21
	v_mul_f32_e32 v250, v22, v22
	v_mul_f32_e32 v251, v23, v23
	v_add_f32_e32 v158, v158, v159
	v_add_f32_e32 v250, v250, v251
	v_add_f32_e32 v158, v158, v250
	v_add_f32_e32 v161, v161, v158
	v_mul_f32_e32 v158, v20, v228
	v_mul_f32_e32 v159, v21, v229
	v_mul_f32_e32 v250, v22, v230
	v_mul_f32_e32 v251, v23, v231
	v_cvt_pk_bf16_f32 v158, v158, v159
	v_cvt_pk_bf16_f32 v159, v250, v251
	s_nop 1
	v_permlane16_swap_b32_e32 v156, v158
	v_permlane16_swap_b32_e32 v157, v159
	global_store_dwordx4 v254, v[156:159], s[28:29] offset:128
	v_add_f32_e32 v162, v96, v162
	v_add_f32_e32 v163, v97, v163
	v_add_f32_e32 v164, v98, v164
	v_add_f32_e32 v165, v99, v165
	global_store_dwordx4 v244, v[162:165], s[26:27] offset:384
	v_mul_f32_e32 v158, v162, v162
	v_mul_f32_e32 v159, v163, v163
	v_mul_f32_e32 v250, v164, v164
	v_mul_f32_e32 v251, v165, v165
	v_add_f32_e32 v158, v158, v159
	v_add_f32_e32 v250, v250, v251
	v_add_f32_e32 v158, v158, v250
	v_add_f32_e32 v161, v161, v158
	v_mul_f32_e32 v156, v162, v232
	v_mul_f32_e32 v157, v163, v233
	v_mul_f32_e32 v158, v164, v234
	v_mul_f32_e32 v159, v165, v235
	v_cvt_pk_bf16_f32 v156, v156, v157
	v_cvt_pk_bf16_f32 v157, v158, v159
	v_add_f32_e32 v166, v84, v166
	v_add_f32_e32 v167, v85, v167
	v_add_f32_e32 v168, v86, v168
	v_add_f32_e32 v169, v87, v169
	global_store_dwordx4 v244, v[166:169], s[26:27] offset:448
	v_mul_f32_e32 v158, v166, v166
	v_mul_f32_e32 v159, v167, v167
	v_mul_f32_e32 v250, v168, v168
	v_mul_f32_e32 v251, v169, v169
	v_add_f32_e32 v158, v158, v159
	v_add_f32_e32 v250, v250, v251
	v_add_f32_e32 v158, v158, v250
	v_add_f32_e32 v161, v161, v158
	v_mul_f32_e32 v158, v166, v236
	v_mul_f32_e32 v159, v167, v237
	v_mul_f32_e32 v250, v168, v238
	v_mul_f32_e32 v251, v169, v239
	v_cvt_pk_bf16_f32 v158, v158, v159
	v_cvt_pk_bf16_f32 v159, v250, v251
	s_nop 1
	v_permlane16_swap_b32_e32 v156, v158
	v_permlane16_swap_b32_e32 v157, v159
	global_store_dwordx4 v254, v[156:159], s[28:29] offset:192
	ds_bpermute_b32 v158, v248, v161
	s_waitcnt lgkmcnt(0)
	v_add_f32_e32 v161, v161, v158
	ds_bpermute_b32 v158, v249, v161
	s_waitcnt lgkmcnt(0)
	v_add_f32_e32 v161, v161, v158
	global_store_dword v247, v161, s[30:31] offset:4
	s_add_u32 s26, s26, 0x10000
	s_addc_u32 s27, s27, 0
	s_add_u32 s28, s28, 0x8000
	s_addc_u32 s29, s29, 0
	s_add_u32 s30, s30, 0x400
	s_addc_u32 s31, s31, 0
	s_waitcnt vmcnt(25)
	v_add_f32_e32 v170, v132, v170
	v_add_f32_e32 v171, v133, v171
	v_add_f32_e32 v172, v134, v172
	v_add_f32_e32 v173, v135, v173
	global_store_dwordx4 v244, v[170:173], s[26:27]
	v_mul_f32_e32 v158, v170, v170
	v_mul_f32_e32 v159, v171, v171
	v_mul_f32_e32 v250, v172, v172
	v_mul_f32_e32 v251, v173, v173
	v_add_f32_e32 v158, v158, v159
	v_add_f32_e32 v250, v250, v251
	v_add_f32_e32 v161, v158, v250
	v_mul_f32_e32 v156, v170, v208
	v_mul_f32_e32 v157, v171, v209
	v_mul_f32_e32 v158, v172, v210
	v_mul_f32_e32 v159, v173, v211
	v_cvt_pk_bf16_f32 v156, v156, v157
	v_cvt_pk_bf16_f32 v157, v158, v159
	v_add_f32_e32 v174, v136, v174
	v_add_f32_e32 v175, v137, v175
	v_add_f32_e32 v176, v138, v176
	v_add_f32_e32 v177, v139, v177
	global_store_dwordx4 v244, v[174:177], s[26:27] offset:64
	v_mul_f32_e32 v158, v174, v174
	v_mul_f32_e32 v159, v175, v175
	v_mul_f32_e32 v250, v176, v176
	v_mul_f32_e32 v251, v177, v177
	v_add_f32_e32 v158, v158, v159
	v_add_f32_e32 v250, v250, v251
	v_add_f32_e32 v158, v158, v250
	v_add_f32_e32 v161, v161, v158
	v_mul_f32_e32 v158, v174, v212
	v_mul_f32_e32 v159, v175, v213
	v_mul_f32_e32 v250, v176, v214
	v_mul_f32_e32 v251, v177, v215
	v_cvt_pk_bf16_f32 v158, v158, v159
	v_cvt_pk_bf16_f32 v159, v250, v251
	s_nop 1
	v_permlane16_swap_b32_e32 v156, v158
	v_permlane16_swap_b32_e32 v157, v159
	global_store_dwordx4 v254, v[156:159], s[28:29]
	v_add_f32_e32 v178, v140, v178
	v_add_f32_e32 v179, v141, v179
	v_add_f32_e32 v180, v142, v180
	v_add_f32_e32 v181, v143, v181
	global_store_dwordx4 v244, v[178:181], s[26:27] offset:128
	v_mul_f32_e32 v158, v178, v178
	v_mul_f32_e32 v159, v179, v179
	v_mul_f32_e32 v250, v180, v180
	v_mul_f32_e32 v251, v181, v181
	v_add_f32_e32 v158, v158, v159
	v_add_f32_e32 v250, v250, v251
	v_add_f32_e32 v158, v158, v250
	v_add_f32_e32 v161, v161, v158
	v_mul_f32_e32 v156, v178, v216
	v_mul_f32_e32 v157, v179, v217
	v_mul_f32_e32 v158, v180, v218
	v_mul_f32_e32 v159, v181, v219
	v_cvt_pk_bf16_f32 v156, v156, v157
	v_cvt_pk_bf16_f32 v157, v158, v159
	v_add_f32_e32 v182, v144, v182
	v_add_f32_e32 v183, v145, v183
	v_add_f32_e32 v184, v146, v184
	v_add_f32_e32 v185, v147, v185
	global_store_dwordx4 v244, v[182:185], s[26:27] offset:192
	v_mul_f32_e32 v158, v182, v182
	v_mul_f32_e32 v159, v183, v183
	v_mul_f32_e32 v250, v184, v184
	v_mul_f32_e32 v251, v185, v185
	v_add_f32_e32 v158, v158, v159
	v_add_f32_e32 v250, v250, v251
	v_add_f32_e32 v158, v158, v250
	v_add_f32_e32 v161, v161, v158
	v_mul_f32_e32 v158, v182, v220
	v_mul_f32_e32 v159, v183, v221
	v_mul_f32_e32 v250, v184, v222
	v_mul_f32_e32 v251, v185, v223
	v_cvt_pk_bf16_f32 v158, v158, v159
	v_cvt_pk_bf16_f32 v159, v250, v251
	s_nop 1
	v_permlane16_swap_b32_e32 v156, v158
	v_permlane16_swap_b32_e32 v157, v159
	global_store_dwordx4 v254, v[156:159], s[28:29] offset:64
	ds_bpermute_b32 v158, v248, v161
	s_waitcnt lgkmcnt(0)
	v_add_f32_e32 v161, v161, v158
	ds_bpermute_b32 v158, v249, v161
	s_waitcnt lgkmcnt(0)
	v_add_f32_e32 v161, v161, v158
	global_store_dword v247, v161, s[30:31]
	s_waitcnt vmcnt(21)
	v_add_f32_e32 v186, v76, v186
	v_add_f32_e32 v187, v77, v187
	v_add_f32_e32 v188, v78, v188
	v_add_f32_e32 v189, v79, v189
	global_store_dwordx4 v244, v[186:189], s[26:27] offset:256
	v_mul_f32_e32 v158, v186, v186
	v_mul_f32_e32 v159, v187, v187
	v_mul_f32_e32 v250, v188, v188
	v_mul_f32_e32 v251, v189, v189
	v_add_f32_e32 v158, v158, v159
	v_add_f32_e32 v250, v250, v251
	v_add_f32_e32 v161, v158, v250
	v_mul_f32_e32 v156, v186, v224
	v_mul_f32_e32 v157, v187, v225
	v_mul_f32_e32 v158, v188, v226
	v_mul_f32_e32 v159, v189, v227
	v_cvt_pk_bf16_f32 v156, v156, v157
	v_cvt_pk_bf16_f32 v157, v158, v159
	v_add_f32_e32 v190, v52, v190
	v_add_f32_e32 v191, v53, v191
	v_add_f32_e32 v192, v54, v192
	v_add_f32_e32 v193, v55, v193
	global_store_dwordx4 v244, v[190:193], s[26:27] offset:320
	v_mul_f32_e32 v158, v190, v190
	v_mul_f32_e32 v159, v191, v191
	v_mul_f32_e32 v250, v192, v192
	v_mul_f32_e32 v251, v193, v193
	v_add_f32_e32 v158, v158, v159
	v_add_f32_e32 v250, v250, v251
	v_add_f32_e32 v158, v158, v250
	v_add_f32_e32 v161, v161, v158
	v_mul_f32_e32 v158, v190, v228
	v_mul_f32_e32 v159, v191, v229
	v_mul_f32_e32 v250, v192, v230
	v_mul_f32_e32 v251, v193, v231
	v_cvt_pk_bf16_f32 v158, v158, v159
	v_cvt_pk_bf16_f32 v159, v250, v251
	s_nop 1
	v_permlane16_swap_b32_e32 v156, v158
	v_permlane16_swap_b32_e32 v157, v159
	global_store_dwordx4 v254, v[156:159], s[28:29] offset:128
	v_add_f32_e32 v194, v44, v194
	v_add_f32_e32 v195, v45, v195
	v_add_f32_e32 v196, v46, v196
	v_add_f32_e32 v197, v47, v197
	global_store_dwordx4 v244, v[194:197], s[26:27] offset:384
	v_mul_f32_e32 v158, v194, v194
	v_mul_f32_e32 v159, v195, v195
	v_mul_f32_e32 v250, v196, v196
	v_mul_f32_e32 v251, v197, v197
	v_add_f32_e32 v158, v158, v159
	v_add_f32_e32 v250, v250, v251
	v_add_f32_e32 v158, v158, v250
	v_add_f32_e32 v161, v161, v158
	v_mul_f32_e32 v156, v194, v232
	v_mul_f32_e32 v157, v195, v233
	v_mul_f32_e32 v158, v196, v234
	v_mul_f32_e32 v159, v197, v235
	v_cvt_pk_bf16_f32 v156, v156, v157
	v_cvt_pk_bf16_f32 v157, v158, v159
	v_add_f32_e32 v240, v148, v240
	v_add_f32_e32 v241, v149, v241
	v_add_f32_e32 v242, v150, v242
	v_add_f32_e32 v243, v151, v243
	global_store_dwordx4 v244, v[240:243], s[26:27] offset:448
	v_mul_f32_e32 v158, v240, v240
	v_mul_f32_e32 v159, v241, v241
	v_mul_f32_e32 v250, v242, v242
	v_mul_f32_e32 v251, v243, v243
	v_add_f32_e32 v158, v158, v159
	v_add_f32_e32 v250, v250, v251
	v_add_f32_e32 v158, v158, v250
	v_add_f32_e32 v161, v161, v158
	v_mul_f32_e32 v158, v240, v236
	v_mul_f32_e32 v159, v241, v237
	v_mul_f32_e32 v250, v242, v238
	v_mul_f32_e32 v251, v243, v239
	v_cvt_pk_bf16_f32 v158, v158, v159
	v_cvt_pk_bf16_f32 v159, v250, v251
	s_nop 1
	v_permlane16_swap_b32_e32 v156, v158
	v_permlane16_swap_b32_e32 v157, v159
	global_store_dwordx4 v254, v[156:159], s[28:29] offset:192
	ds_bpermute_b32 v158, v248, v161
	s_waitcnt lgkmcnt(0)
	v_add_f32_e32 v161, v161, v158
	ds_bpermute_b32 v158, v249, v161
	s_waitcnt lgkmcnt(0)
	v_add_f32_e32 v161, v161, v158
	global_store_dword v247, v161, s[30:31] offset:4
	s_add_u32 s26, s26, 0x10000
	s_addc_u32 s27, s27, 0
	s_add_u32 s28, s28, 0x8000
	s_addc_u32 s29, s29, 0
	s_add_u32 s30, s30, 0x400
	s_addc_u32 s31, s31, 0
	s_branch .LBB0_23

.LBB0_362:
	s_lshr_b32 s4, s20, 2
	s_and_b32 s4, s4, 24
	s_and_b32 s5, s20, 7
	s_or_b32 s4, s4, s5
	s_lshl_b32 s4, s4, 10
	v_mov_b32 v8, v198
	s_or_b32 s4, s4, s65
	v_ashrrev_i32_e32 v12, 2, v8
	v_add_u32_e32 v0, s4, v12
	s_waitcnt lgkmcnt(0)
	v_ashrrev_i32_e32 v1, 31, v0
	s_lshl_b32 s5, s20, 5
	v_lshlrev_b64 v[0:1], 13, v[0:1]
	v_lshlrev_b32_e32 v2, 4, v8
	s_and_b32 s5, s5, 0x300
	v_lshl_add_u64 v[0:1], s[92:93], 0, v[0:1]
	v_and_b32_e32 v152, 48, v2
	v_lshl_add_u64 v[14:15], v[0:1], 0, v[152:153]
	v_add_u32_e32 v0, s5, v12
	v_ashrrev_i32_e32 v1, 31, v0
	v_lshlrev_b64 v[0:1], 6, v[0:1]
	s_mov_b32 s12, 0x80000
	v_lshl_add_u64 v[0:1], s[6:7], 0, v[0:1]
	v_add_co_u32_e32 v54, vcc, s12, v14
	v_lshl_add_u64 v[0:1], v[0:1], 0, v[152:153]
	s_nop 0
	v_addc_co_u32_e32 v55, vcc, 0, v15, vcc
	s_lshl_b32 s13, s19, 13
	s_lshl_b32 s21, s20, 8
	s_and_b32 s22, s18, 7
	v_lshrrev_b32_e32 v6, 2, v8
	v_add_co_u32_e32 v2, vcc, s12, v0
	s_and_b32 s13, s13, 0x600000
	s_and_b32 s21, s21, 0x6000
	s_lshl_b32 s24, s22, 10
	v_and_b32_e32 v6, 12, v6
	s_movk_i32 s22, 0x1230
	v_addc_co_u32_e32 v3, vcc, 0, v1, vcc
	s_mov_b32 s12, 0x100000
	v_lshrrev_b32_e64 v10, v6, s22
	s_add_u32 s22, s15, s13
	v_add_co_u32_e32 v4, vcc, s12, v0
	s_addc_u32 s23, s16, 0
	s_or_b32 s13, s24, s21
	v_addc_co_u32_e32 v5, vcc, 0, v1, vcc
	s_mov_b32 s12, 0x180000
	v_and_b32_e32 v22, 3, v8
	v_ashrrev_i32_e32 v13, 31, v12
	v_xor_b32_e32 v8, v10, v8
	s_or_b32 s13, s13, s65
	v_add_co_u32_e32 v20, vcc, s12, v0
	v_lshlrev_b32_e32 v9, 6, v12
	v_lshlrev_b64 v[6:7], 13, v[12:13]
	v_lshlrev_b32_e32 v8, 4, v8
	v_add_u32_e32 v12, s13, v12
	v_addc_co_u32_e32 v21, vcc, 0, v1, vcc
	s_nop 0
	v_readfirstlane_b32 s26, v14
	v_readfirstlane_b32 s27, v15
	v_readfirstlane_b32 s28, v0
	v_readfirstlane_b32 s29, v1
	v_lshrrev_b32_e32 v250, 6, v198
	s_nop 0
	v_readfirstlane_b32 s24, v250
	s_lshl_b32 s24, s24, 10
	v_lshrrev_b32_e32 v250, 2, v200
	v_lshrrev_b32_e32 v251, 4, v200
	v_lshlrev_b32_e32 v251, 2, v251
	v_mov_b32_e32 v248, 0x1230
	v_lshrrev_b32_e32 v251, v251, v248
	v_xor_b32_e32 v251, v251, v200
	v_and_b32_e32 v251, 3, v251
	v_lshlrev_b32_e32 v251, 4, v251
	v_lshl_add_u32 v244, v250, 13, v251
	v_add_u32_e32 v245, 0x80000, v244
	v_add_u32_e32 v246, 0x100000, v244
	v_add_u32_e32 v247, 0x180000, v244
	v_lshl_add_u32 v156, v250, 6, v251
	v_add_u32_e32 v157, 0x1000, v156
	v_add_u32_e32 v158, 0x2000, v156
	v_add_u32_e32 v159, 0x3000, v156
	s_mov_b32 s25, 0
	s_add_u32 m0, s25, s24
	s_nop 0
	global_load_lds_dwordx4 v244, s[26:27]
	s_add_u32 m0, m0, 0x1000
	s_nop 0
	global_load_lds_dwordx4 v245, s[26:27]
	s_add_u32 m0, m0, 0x1000
	s_nop 0
	global_load_lds_dwordx4 v156, s[28:29]
	s_add_u32 m0, m0, 0x1000
	s_nop 0
	global_load_lds_dwordx4 v157, s[28:29]
	s_add_u32 m0, m0, 0x1000
	s_nop 0
	global_load_lds_dwordx4 v158, s[28:29]
	s_add_u32 m0, m0, 0x1000
	s_nop 0
	global_load_lds_dwordx4 v159, s[28:29]
	s_add_u32 s26, s26, 64
	s_addc_u32 s27, s27, 0
	s_add_u32 s28, s28, 0x10000
	s_addc_u32 s29, s29, 0
	s_add_u32 s25, s25, 24576
	s_cmp_eq_u32 s25, 73728
	s_cselect_b32 s25, 0, s25
	s_add_u32 m0, s25, s24
	s_nop 0
	global_load_lds_dwordx4 v244, s[26:27]
	s_add_u32 m0, m0, 0x1000
	s_nop 0
	global_load_lds_dwordx4 v245, s[26:27]
	s_add_u32 m0, m0, 0x1000
	s_nop 0
	global_load_lds_dwordx4 v156, s[28:29]
	s_add_u32 m0, m0, 0x1000
	s_nop 0
	global_load_lds_dwordx4 v157, s[28:29]
	s_add_u32 m0, m0, 0x1000
	s_nop 0
	global_load_lds_dwordx4 v158, s[28:29]
	s_add_u32 m0, m0, 0x1000
	s_nop 0
	global_load_lds_dwordx4 v159, s[28:29]
	s_add_u32 s26, s26, 64
	s_addc_u32 s27, s27, 0
	s_add_u32 s28, s28, 0x10000
	s_addc_u32 s29, s29, 0
	s_add_u32 s25, s25, 24576
	s_cmp_eq_u32 s25, 73728
	s_cselect_b32 s25, 0, s25
	s_add_u32 m0, s25, s24
	s_nop 0
	global_load_lds_dwordx4 v244, s[26:27]
	s_add_u32 m0, m0, 0x1000
	s_nop 0
	global_load_lds_dwordx4 v245, s[26:27]
	s_add_u32 m0, m0, 0x1000
	s_nop 0
	global_load_lds_dwordx4 v156, s[28:29]
	s_add_u32 m0, m0, 0x1000
	s_nop 0
	global_load_lds_dwordx4 v157, s[28:29]
	s_add_u32 m0, m0, 0x1000
	s_nop 0
	global_load_lds_dwordx4 v158, s[28:29]
	s_add_u32 m0, m0, 0x1000
	s_nop 0
	global_load_lds_dwordx4 v159, s[28:29]
	s_add_u32 s26, s26, 64
	s_addc_u32 s27, s27, 0
	s_add_u32 s28, s28, 0x10000
	s_addc_u32 s29, s29, 0
	s_add_u32 s25, s25, 24576
	s_cmp_eq_u32 s25, 73728
	s_cselect_b32 s25, 0, s25
	v_mov_b32_e32 v24, 0
	v_mov_b32_e32 v25, v24
	v_mov_b32_e32 v26, v24
	v_mov_b32_e32 v27, v24
	v_mov_b32_e32 v28, v24
	v_mov_b32_e32 v29, v24
	v_mov_b32_e32 v54, v24
	v_mov_b32_e32 v55, v24
	v_mov_b32_e32 v56, v24
	v_mov_b32_e32 v57, v24
	v_mov_b32_e32 v58, v24
	v_mov_b32_e32 v59, v24
	v_mov_b32_e32 v64, v24
	v_mov_b32_e32 v65, v24
	v_mov_b32_e32 v66, v24
	v_mov_b32_e32 v67, v24
	v_mov_b32_e32 v68, v24
	v_mov_b32_e32 v69, v24
	v_mov_b32_e32 v70, v24
	v_mov_b32_e32 v71, v24
	v_mov_b32_e32 v60, v24
	v_mov_b32_e32 v61, v24
	v_mov_b32_e32 v62, v24
	v_mov_b32_e32 v63, v24
	v_mov_b32_e32 v100, v24
	v_mov_b32_e32 v30, v24
	v_mov_b32_e32 v31, v24
	v_mov_b32_e32 v32, v24
	v_mov_b32_e32 v33, v24
	v_mov_b32_e32 v34, v24
	v_mov_b32_e32 v35, v24
	v_mov_b32_e32 v36, v24
	v_mov_b32_e32 v37, v24
	v_mov_b32_e32 v38, v24
	v_mov_b32_e32 v39, v24
	v_mov_b32_e32 v52, v24
	v_mov_b32_e32 v53, v24
	v_mov_b32_e32 v40, v24
	v_mov_b32_e32 v41, v24
	v_mov_b32_e32 v42, v24
	v_mov_b32_e32 v43, v24
	v_mov_b32_e32 v44, v24
	v_mov_b32_e32 v45, v24
	v_mov_b32_e32 v46, v24
	v_mov_b32_e32 v47, v24
	v_mov_b32_e32 v48, v24
	v_mov_b32_e32 v49, v24
	v_mov_b32_e32 v50, v24
	v_mov_b32_e32 v51, v24
	v_mov_b32_e32 v101, v24
	v_mov_b32_e32 v102, v24
	v_mov_b32_e32 v103, v24
	v_mov_b32_e32 v104, v24
	v_mov_b32_e32 v105, v24
	v_mov_b32_e32 v106, v24
	v_mov_b32_e32 v107, v24
	v_mov_b32_e32 v120, v24
	v_mov_b32_e32 v121, v24
	v_mov_b32_e32 v122, v24
	v_mov_b32_e32 v123, v24
	v_mov_b32_e32 v128, v24
	v_mov_b32_e32 v129, v24
	v_mov_b32_e32 v130, v24
	v_mov_b32_e32 v131, v24
	v_mov_b32_e32 v108, v24
	v_mov_b32_e32 v109, v24
	v_mov_b32_e32 v110, v24
	v_mov_b32_e32 v111, v24
	v_mov_b32_e32 v112, v24
	v_mov_b32_e32 v113, v24
	v_mov_b32_e32 v114, v24
	v_mov_b32_e32 v115, v24
	v_mov_b32_e32 v116, v24
	v_mov_b32_e32 v117, v24
	v_mov_b32_e32 v118, v24
	v_mov_b32_e32 v119, v24
	v_mov_b32_e32 v124, v24
	v_mov_b32_e32 v125, v24
	v_mov_b32_e32 v126, v24
	v_mov_b32_e32 v127, v24
	v_mov_b32_e32 v80, v24
	v_mov_b32_e32 v81, v24
	v_mov_b32_e32 v82, v24
	v_mov_b32_e32 v83, v24
	v_mov_b32_e32 v84, v24
	v_mov_b32_e32 v85, v24
	v_mov_b32_e32 v86, v24
	v_mov_b32_e32 v87, v24
	v_mov_b32_e32 v96, v24
	v_mov_b32_e32 v97, v24
	v_mov_b32_e32 v98, v24
	v_mov_b32_e32 v99, v24
	v_mov_b32_e32 v72, v24
	v_mov_b32_e32 v73, v24
	v_mov_b32_e32 v74, v24
	v_mov_b32_e32 v75, v24
	v_mov_b32_e32 v132, v24
	v_mov_b32_e32 v133, v24
	v_mov_b32_e32 v134, v24
	v_mov_b32_e32 v135, v24
	v_mov_b32_e32 v136, v24
	v_mov_b32_e32 v137, v24
	v_mov_b32_e32 v138, v24
	v_mov_b32_e32 v139, v24
	v_mov_b32_e32 v140, v24
	v_mov_b32_e32 v141, v24
	v_mov_b32_e32 v142, v24
	v_mov_b32_e32 v143, v24
	v_mov_b32_e32 v144, v24
	v_mov_b32_e32 v145, v24
	v_mov_b32_e32 v146, v24
	v_mov_b32_e32 v147, v24
	v_mov_b32_e32 v92, v24
	v_mov_b32_e32 v93, v24
	v_mov_b32_e32 v94, v24
	v_mov_b32_e32 v95, v24
	v_mov_b32_e32 v88, v24
	v_mov_b32_e32 v89, v24
	v_mov_b32_e32 v90, v24
	v_mov_b32_e32 v91, v24
	v_mov_b32_e32 v76, v24
	v_mov_b32_e32 v77, v24
	v_mov_b32_e32 v78, v24
	v_mov_b32_e32 v79, v24
	v_mov_b32_e32 v148, v24
	v_mov_b32_e32 v149, v24
	v_mov_b32_e32 v150, v24
	v_mov_b32_e32 v151, v24
	s_waitcnt vmcnt(12)
	s_barrier
	s_mov_b32 s30, 0
	v_add_u32_e32 v248, s30, v155
	v_add_u32_e32 v249, s30, v160
	ds_read_b128 v[186:189], v248
	ds_read_b128 v[212:215], v249 offset:8192
	ds_read_b128 v[190:193], v248 offset:1024
	ds_read_b128 v[216:219], v249 offset:9216
	ds_read_b128 v[194:197], v248 offset:2048
	ds_read_b128 v[220:223], v249 offset:10240
	ds_read_b128 v[208:211], v248 offset:3072
	ds_read_b128 v[224:227], v249 offset:11264
	ds_read_b128 v[228:231], v249 offset:12288
	ds_read_b128 v[232:235], v249 offset:13312
	ds_read_b128 v[236:239], v249 offset:14336
	ds_read_b128 v[240:243], v249 offset:15360
	s_add_u32 s30, s30, 24576
	s_cmp_eq_u32 s30, 73728
	s_cselect_b32 s30, 0, s30
	s_waitcnt vmcnt(6)
	s_waitcnt lgkmcnt(0)
	s_barrier
	s_mov_b32 s31, 62
.Lgm2_loop:
	v_add_u32_e32 v248, s30, v155
	v_add_u32_e32 v249, s30, v160
	v_mfma_f32_16x16x32_bf16 v[128:131], v[212:215], v[186:189], v[128:131]
	ds_read_b128 v[0:3], v248
	v_mfma_f32_16x16x32_bf16 v[68:71], v[212:215], v[190:193], v[68:71]
	ds_read_b128 v[16:19], v249 offset:8192
	v_mfma_f32_16x16x32_bf16 v[108:111], v[212:215], v[194:197], v[108:111]
	ds_read_b128 v[4:7], v248 offset:1024
	v_mfma_f32_16x16x32_bf16 v[132:135], v[212:215], v[208:211], v[132:135]
	ds_read_b128 v[20:23], v249 offset:9216
	v_mfma_f32_16x16x32_bf16 v[120:123], v[216:219], v[186:189], v[120:123]
	ds_read_b128 v[8:11], v248 offset:2048
	v_mfma_f32_16x16x32_bf16 v[64:67], v[216:219], v[190:193], v[64:67]
	ds_read_b128 v[162:165], v249 offset:10240
	v_mfma_f32_16x16x32_bf16 v[112:115], v[216:219], v[194:197], v[112:115]
	ds_read_b128 v[12:15], v248 offset:3072
	v_mfma_f32_16x16x32_bf16 v[136:139], v[216:219], v[208:211], v[136:139]
	ds_read_b128 v[166:169], v249 offset:11264
	v_mfma_f32_16x16x32_bf16 v[104:107], v[220:223], v[186:189], v[104:107]
	ds_read_b128 v[170:173], v249 offset:12288
	v_mfma_f32_16x16x32_bf16 v[56:59], v[220:223], v[190:193], v[56:59]
	ds_read_b128 v[174:177], v249 offset:13312
	v_mfma_f32_16x16x32_bf16 v[116:119], v[220:223], v[194:197], v[116:119]
	ds_read_b128 v[178:181], v249 offset:14336
	v_mfma_f32_16x16x32_bf16 v[140:143], v[220:223], v[208:211], v[140:143]
	ds_read_b128 v[182:185], v249 offset:15360
	s_add_u32 m0, s25, s24
	v_mfma_f32_16x16x32_bf16 v[100:103], v[224:227], v[186:189], v[100:103]
	global_load_lds_dwordx4 v244, s[26:27]
	v_mfma_f32_16x16x32_bf16 v[52:55], v[224:227], v[190:193], v[52:55]
	v_mfma_f32_16x16x32_bf16 v[124:127], v[224:227], v[194:197], v[124:127]
	s_add_u32 m0, m0, 0x1000
	v_mfma_f32_16x16x32_bf16 v[144:147], v[224:227], v[208:211], v[144:147]
	global_load_lds_dwordx4 v245, s[26:27]
	v_mfma_f32_16x16x32_bf16 v[60:63], v[228:231], v[186:189], v[60:63]
	v_mfma_f32_16x16x32_bf16 v[36:39], v[228:231], v[190:193], v[36:39]
	s_add_u32 m0, m0, 0x1000
	v_mfma_f32_16x16x32_bf16 v[80:83], v[228:231], v[194:197], v[80:83]
	global_load_lds_dwordx4 v156, s[28:29]
	v_mfma_f32_16x16x32_bf16 v[92:95], v[228:231], v[208:211], v[92:95]
	v_mfma_f32_16x16x32_bf16 v[48:51], v[232:235], v[186:189], v[48:51]
	s_add_u32 m0, m0, 0x1000
	v_mfma_f32_16x16x32_bf16 v[32:35], v[232:235], v[190:193], v[32:35]
	global_load_lds_dwordx4 v157, s[28:29]
	v_mfma_f32_16x16x32_bf16 v[84:87], v[232:235], v[194:197], v[84:87]
	v_mfma_f32_16x16x32_bf16 v[88:91], v[232:235], v[208:211], v[88:91]
	s_add_u32 m0, m0, 0x1000
	v_mfma_f32_16x16x32_bf16 v[44:47], v[236:239], v[186:189], v[44:47]
	global_load_lds_dwordx4 v158, s[28:29]
	v_mfma_f32_16x16x32_bf16 v[28:31], v[236:239], v[190:193], v[28:31]
	v_mfma_f32_16x16x32_bf16 v[96:99], v[236:239], v[194:197], v[96:99]
	s_add_u32 m0, m0, 0x1000
	v_mfma_f32_16x16x32_bf16 v[76:79], v[236:239], v[208:211], v[76:79]
	global_load_lds_dwordx4 v159, s[28:29]
	v_mfma_f32_16x16x32_bf16 v[40:43], v[240:243], v[186:189], v[40:43]
	v_mfma_f32_16x16x32_bf16 v[24:27], v[240:243], v[190:193], v[24:27]
	v_mfma_f32_16x16x32_bf16 v[72:75], v[240:243], v[194:197], v[72:75]
	v_mfma_f32_16x16x32_bf16 v[148:151], v[240:243], v[208:211], v[148:151]
	s_add_u32 s26, s26, 64
	s_addc_u32 s27, s27, 0
	s_add_u32 s28, s28, 0x10000
	s_addc_u32 s29, s29, 0
	s_add_u32 s25, s25, 24576
	s_cmp_eq_u32 s25, 73728
	s_cselect_b32 s25, 0, s25
	s_add_u32 s30, s30, 24576
	s_cmp_eq_u32 s30, 73728
	s_cselect_b32 s30, 0, s30
	s_waitcnt vmcnt(6)
	s_waitcnt lgkmcnt(0)
	s_barrier
	v_add_u32_e32 v248, s30, v155
	v_add_u32_e32 v249, s30, v160
	v_mfma_f32_16x16x32_bf16 v[128:131], v[16:19], v[0:3], v[128:131]
	ds_read_b128 v[186:189], v248
	v_mfma_f32_16x16x32_bf16 v[68:71], v[16:19], v[4:7], v[68:71]
	ds_read_b128 v[212:215], v249 offset:8192
	v_mfma_f32_16x16x32_bf16 v[108:111], v[16:19], v[8:11], v[108:111]
	ds_read_b128 v[190:193], v248 offset:1024
	v_mfma_f32_16x16x32_bf16 v[132:135], v[16:19], v[12:15], v[132:135]
	ds_read_b128 v[216:219], v249 offset:9216
	v_mfma_f32_16x16x32_bf16 v[120:123], v[20:23], v[0:3], v[120:123]
	ds_read_b128 v[194:197], v248 offset:2048
	v_mfma_f32_16x16x32_bf16 v[64:67], v[20:23], v[4:7], v[64:67]
	ds_read_b128 v[220:223], v249 offset:10240
	v_mfma_f32_16x16x32_bf16 v[112:115], v[20:23], v[8:11], v[112:115]
	ds_read_b128 v[208:211], v248 offset:3072
	v_mfma_f32_16x16x32_bf16 v[136:139], v[20:23], v[12:15], v[136:139]
	ds_read_b128 v[224:227], v249 offset:11264
	v_mfma_f32_16x16x32_bf16 v[104:107], v[162:165], v[0:3], v[104:107]
	ds_read_b128 v[228:231], v249 offset:12288
	v_mfma_f32_16x16x32_bf16 v[56:59], v[162:165], v[4:7], v[56:59]
	ds_read_b128 v[232:235], v249 offset:13312
	v_mfma_f32_16x16x32_bf16 v[116:119], v[162:165], v[8:11], v[116:119]
	ds_read_b128 v[236:239], v249 offset:14336
	v_mfma_f32_16x16x32_bf16 v[140:143], v[162:165], v[12:15], v[140:143]
	ds_read_b128 v[240:243], v249 offset:15360
	s_add_u32 m0, s25, s24
	v_mfma_f32_16x16x32_bf16 v[100:103], v[166:169], v[0:3], v[100:103]
	global_load_lds_dwordx4 v244, s[26:27]
	v_mfma_f32_16x16x32_bf16 v[52:55], v[166:169], v[4:7], v[52:55]
	v_mfma_f32_16x16x32_bf16 v[124:127], v[166:169], v[8:11], v[124:127]
	s_add_u32 m0, m0, 0x1000
	v_mfma_f32_16x16x32_bf16 v[144:147], v[166:169], v[12:15], v[144:147]
	global_load_lds_dwordx4 v245, s[26:27]
	v_mfma_f32_16x16x32_bf16 v[60:63], v[170:173], v[0:3], v[60:63]
	v_mfma_f32_16x16x32_bf16 v[36:39], v[170:173], v[4:7], v[36:39]
	s_add_u32 m0, m0, 0x1000
	v_mfma_f32_16x16x32_bf16 v[80:83], v[170:173], v[8:11], v[80:83]
	global_load_lds_dwordx4 v156, s[28:29]
	v_mfma_f32_16x16x32_bf16 v[92:95], v[170:173], v[12:15], v[92:95]
	v_mfma_f32_16x16x32_bf16 v[48:51], v[174:177], v[0:3], v[48:51]
	s_add_u32 m0, m0, 0x1000
	v_mfma_f32_16x16x32_bf16 v[32:35], v[174:177], v[4:7], v[32:35]
	global_load_lds_dwordx4 v157, s[28:29]
	v_mfma_f32_16x16x32_bf16 v[84:87], v[174:177], v[8:11], v[84:87]
	v_mfma_f32_16x16x32_bf16 v[88:91], v[174:177], v[12:15], v[88:91]
	s_add_u32 m0, m0, 0x1000
	v_mfma_f32_16x16x32_bf16 v[44:47], v[178:181], v[0:3], v[44:47]
	global_load_lds_dwordx4 v158, s[28:29]
	v_mfma_f32_16x16x32_bf16 v[28:31], v[178:181], v[4:7], v[28:31]
	v_mfma_f32_16x16x32_bf16 v[96:99], v[178:181], v[8:11], v[96:99]
	s_add_u32 m0, m0, 0x1000
	v_mfma_f32_16x16x32_bf16 v[76:79], v[178:181], v[12:15], v[76:79]
	global_load_lds_dwordx4 v159, s[28:29]
	v_mfma_f32_16x16x32_bf16 v[40:43], v[182:185], v[0:3], v[40:43]
	v_mfma_f32_16x16x32_bf16 v[24:27], v[182:185], v[4:7], v[24:27]
	v_mfma_f32_16x16x32_bf16 v[72:75], v[182:185], v[8:11], v[72:75]
	v_mfma_f32_16x16x32_bf16 v[148:151], v[182:185], v[12:15], v[148:151]
	s_add_u32 s26, s26, 64
	s_addc_u32 s27, s27, 0
	s_add_u32 s28, s28, 0x10000
	s_addc_u32 s29, s29, 0
	s_add_u32 s25, s25, 24576
	s_cmp_eq_u32 s25, 73728
	s_cselect_b32 s25, 0, s25
	s_add_u32 s30, s30, 24576
	s_cmp_eq_u32 s30, 73728
	s_cselect_b32 s30, 0, s30
	s_waitcnt vmcnt(6)
	s_waitcnt lgkmcnt(0)
	s_barrier
	s_sub_u32 s31, s31, 1
	s_cmp_lg_u32 s31, 0
	s_cbranch_scc1 .Lgm2_loop
	v_add_u32_e32 v248, s30, v155
	v_add_u32_e32 v249, s30, v160
	v_mfma_f32_16x16x32_bf16 v[128:131], v[212:215], v[186:189], v[128:131]
	ds_read_b128 v[0:3], v248
	v_mfma_f32_16x16x32_bf16 v[68:71], v[212:215], v[190:193], v[68:71]
	ds_read_b128 v[16:19], v249 offset:8192
	v_mfma_f32_16x16x32_bf16 v[108:111], v[212:215], v[194:197], v[108:111]
	ds_read_b128 v[4:7], v248 offset:1024
	v_mfma_f32_16x16x32_bf16 v[132:135], v[212:215], v[208:211], v[132:135]
	ds_read_b128 v[20:23], v249 offset:9216
	v_mfma_f32_16x16x32_bf16 v[120:123], v[216:219], v[186:189], v[120:123]
	ds_read_b128 v[8:11], v248 offset:2048
	v_mfma_f32_16x16x32_bf16 v[64:67], v[216:219], v[190:193], v[64:67]
	ds_read_b128 v[162:165], v249 offset:10240
	v_mfma_f32_16x16x32_bf16 v[112:115], v[216:219], v[194:197], v[112:115]
	ds_read_b128 v[12:15], v248 offset:3072
	v_mfma_f32_16x16x32_bf16 v[136:139], v[216:219], v[208:211], v[136:139]
	ds_read_b128 v[166:169], v249 offset:11264
	v_mfma_f32_16x16x32_bf16 v[104:107], v[220:223], v[186:189], v[104:107]
	ds_read_b128 v[170:173], v249 offset:12288
	v_mfma_f32_16x16x32_bf16 v[56:59], v[220:223], v[190:193], v[56:59]
	ds_read_b128 v[174:177], v249 offset:13312
	v_mfma_f32_16x16x32_bf16 v[116:119], v[220:223], v[194:197], v[116:119]
	ds_read_b128 v[178:181], v249 offset:14336
	v_mfma_f32_16x16x32_bf16 v[140:143], v[220:223], v[208:211], v[140:143]
	ds_read_b128 v[182:185], v249 offset:15360
	s_add_u32 m0, s25, s24
	v_mfma_f32_16x16x32_bf16 v[100:103], v[224:227], v[186:189], v[100:103]
	global_load_lds_dwordx4 v244, s[26:27]
	v_mfma_f32_16x16x32_bf16 v[52:55], v[224:227], v[190:193], v[52:55]
	v_mfma_f32_16x16x32_bf16 v[124:127], v[224:227], v[194:197], v[124:127]
	s_add_u32 m0, m0, 0x1000
	v_mfma_f32_16x16x32_bf16 v[144:147], v[224:227], v[208:211], v[144:147]
	global_load_lds_dwordx4 v245, s[26:27]
	v_mfma_f32_16x16x32_bf16 v[60:63], v[228:231], v[186:189], v[60:63]
	v_mfma_f32_16x16x32_bf16 v[36:39], v[228:231], v[190:193], v[36:39]
	s_add_u32 m0, m0, 0x1000
	v_mfma_f32_16x16x32_bf16 v[80:83], v[228:231], v[194:197], v[80:83]
	global_load_lds_dwordx4 v156, s[28:29]
	v_mfma_f32_16x16x32_bf16 v[92:95], v[228:231], v[208:211], v[92:95]
	v_mfma_f32_16x16x32_bf16 v[48:51], v[232:235], v[186:189], v[48:51]
	s_add_u32 m0, m0, 0x1000
	v_mfma_f32_16x16x32_bf16 v[32:35], v[232:235], v[190:193], v[32:35]
	global_load_lds_dwordx4 v157, s[28:29]
	v_mfma_f32_16x16x32_bf16 v[84:87], v[232:235], v[194:197], v[84:87]
	v_mfma_f32_16x16x32_bf16 v[88:91], v[232:235], v[208:211], v[88:91]
	s_add_u32 m0, m0, 0x1000
	v_mfma_f32_16x16x32_bf16 v[44:47], v[236:239], v[186:189], v[44:47]
	global_load_lds_dwordx4 v158, s[28:29]
	v_mfma_f32_16x16x32_bf16 v[28:31], v[236:239], v[190:193], v[28:31]
	v_mfma_f32_16x16x32_bf16 v[96:99], v[236:239], v[194:197], v[96:99]
	s_add_u32 m0, m0, 0x1000
	v_mfma_f32_16x16x32_bf16 v[76:79], v[236:239], v[208:211], v[76:79]
	global_load_lds_dwordx4 v159, s[28:29]
	v_mfma_f32_16x16x32_bf16 v[40:43], v[240:243], v[186:189], v[40:43]
	v_mfma_f32_16x16x32_bf16 v[24:27], v[240:243], v[190:193], v[24:27]
	v_mfma_f32_16x16x32_bf16 v[72:75], v[240:243], v[194:197], v[72:75]
	v_mfma_f32_16x16x32_bf16 v[148:151], v[240:243], v[208:211], v[148:151]
	s_add_u32 s26, s26, 64
	s_addc_u32 s27, s27, 0
	s_add_u32 s28, s28, 0x10000
	s_addc_u32 s29, s29, 0
	s_add_u32 s25, s25, 24576
	s_cmp_eq_u32 s25, 73728
	s_cselect_b32 s25, 0, s25
	s_add_u32 s30, s30, 24576
	s_cmp_eq_u32 s30, 73728
	s_cselect_b32 s30, 0, s30
	s_waitcnt vmcnt(6)
	s_waitcnt lgkmcnt(0)
	s_barrier
	v_add_u32_e32 v248, s30, v155
	v_add_u32_e32 v249, s30, v160
	v_mfma_f32_16x16x32_bf16 v[128:131], v[16:19], v[0:3], v[128:131]
	ds_read_b128 v[186:189], v248
	v_mfma_f32_16x16x32_bf16 v[68:71], v[16:19], v[4:7], v[68:71]
	ds_read_b128 v[212:215], v249 offset:8192
	v_mfma_f32_16x16x32_bf16 v[108:111], v[16:19], v[8:11], v[108:111]
	ds_read_b128 v[190:193], v248 offset:1024
	v_mfma_f32_16x16x32_bf16 v[132:135], v[16:19], v[12:15], v[132:135]
	ds_read_b128 v[216:219], v249 offset:9216
	v_mfma_f32_16x16x32_bf16 v[120:123], v[20:23], v[0:3], v[120:123]
	ds_read_b128 v[194:197], v248 offset:2048
	v_mfma_f32_16x16x32_bf16 v[64:67], v[20:23], v[4:7], v[64:67]
	ds_read_b128 v[220:223], v249 offset:10240
	v_mfma_f32_16x16x32_bf16 v[112:115], v[20:23], v[8:11], v[112:115]
	ds_read_b128 v[208:211], v248 offset:3072
	v_mfma_f32_16x16x32_bf16 v[136:139], v[20:23], v[12:15], v[136:139]
	ds_read_b128 v[224:227], v249 offset:11264
	v_mfma_f32_16x16x32_bf16 v[104:107], v[162:165], v[0:3], v[104:107]
	ds_read_b128 v[228:231], v249 offset:12288
	v_mfma_f32_16x16x32_bf16 v[56:59], v[162:165], v[4:7], v[56:59]
	ds_read_b128 v[232:235], v249 offset:13312
	v_mfma_f32_16x16x32_bf16 v[116:119], v[162:165], v[8:11], v[116:119]
	ds_read_b128 v[236:239], v249 offset:14336
	v_mfma_f32_16x16x32_bf16 v[140:143], v[162:165], v[12:15], v[140:143]
	ds_read_b128 v[240:243], v249 offset:15360
	v_mfma_f32_16x16x32_bf16 v[100:103], v[166:169], v[0:3], v[100:103]
	v_mfma_f32_16x16x32_bf16 v[52:55], v[166:169], v[4:7], v[52:55]
	v_mfma_f32_16x16x32_bf16 v[124:127], v[166:169], v[8:11], v[124:127]
	v_mfma_f32_16x16x32_bf16 v[144:147], v[166:169], v[12:15], v[144:147]
	v_mfma_f32_16x16x32_bf16 v[60:63], v[170:173], v[0:3], v[60:63]
	v_mfma_f32_16x16x32_bf16 v[36:39], v[170:173], v[4:7], v[36:39]
	v_mfma_f32_16x16x32_bf16 v[80:83], v[170:173], v[8:11], v[80:83]
	v_mfma_f32_16x16x32_bf16 v[92:95], v[170:173], v[12:15], v[92:95]
	v_mfma_f32_16x16x32_bf16 v[48:51], v[174:177], v[0:3], v[48:51]
	v_mfma_f32_16x16x32_bf16 v[32:35], v[174:177], v[4:7], v[32:35]
	v_mfma_f32_16x16x32_bf16 v[84:87], v[174:177], v[8:11], v[84:87]
	v_mfma_f32_16x16x32_bf16 v[88:91], v[174:177], v[12:15], v[88:91]
	v_mfma_f32_16x16x32_bf16 v[44:47], v[178:181], v[0:3], v[44:47]
	v_mfma_f32_16x16x32_bf16 v[28:31], v[178:181], v[4:7], v[28:31]
	v_mfma_f32_16x16x32_bf16 v[96:99], v[178:181], v[8:11], v[96:99]
	v_mfma_f32_16x16x32_bf16 v[76:79], v[178:181], v[12:15], v[76:79]
	v_mfma_f32_16x16x32_bf16 v[40:43], v[182:185], v[0:3], v[40:43]
	v_mfma_f32_16x16x32_bf16 v[24:27], v[182:185], v[4:7], v[24:27]
	v_mfma_f32_16x16x32_bf16 v[72:75], v[182:185], v[8:11], v[72:75]
	v_mfma_f32_16x16x32_bf16 v[148:151], v[182:185], v[12:15], v[148:151]
	s_add_u32 s30, s30, 24576
	s_cmp_eq_u32 s30, 73728
	s_cselect_b32 s30, 0, s30
	s_waitcnt vmcnt(0)
	s_waitcnt lgkmcnt(0)
	s_barrier
	v_add_u32_e32 v248, s30, v155
	v_add_u32_e32 v249, s30, v160
	v_mfma_f32_16x16x32_bf16 v[128:131], v[212:215], v[186:189], v[128:131]
	ds_read_b128 v[0:3], v248
	v_mfma_f32_16x16x32_bf16 v[68:71], v[212:215], v[190:193], v[68:71]
	ds_read_b128 v[16:19], v249 offset:8192
	v_mfma_f32_16x16x32_bf16 v[108:111], v[212:215], v[194:197], v[108:111]
	ds_read_b128 v[4:7], v248 offset:1024
	v_mfma_f32_16x16x32_bf16 v[132:135], v[212:215], v[208:211], v[132:135]
	ds_read_b128 v[20:23], v249 offset:9216
	v_mfma_f32_16x16x32_bf16 v[120:123], v[216:219], v[186:189], v[120:123]
	ds_read_b128 v[8:11], v248 offset:2048
	v_mfma_f32_16x16x32_bf16 v[64:67], v[216:219], v[190:193], v[64:67]
	ds_read_b128 v[162:165], v249 offset:10240
	v_mfma_f32_16x16x32_bf16 v[112:115], v[216:219], v[194:197], v[112:115]
	ds_read_b128 v[12:15], v248 offset:3072
	v_mfma_f32_16x16x32_bf16 v[136:139], v[216:219], v[208:211], v[136:139]
	ds_read_b128 v[166:169], v249 offset:11264
	v_mfma_f32_16x16x32_bf16 v[104:107], v[220:223], v[186:189], v[104:107]
	ds_read_b128 v[170:173], v249 offset:12288
	v_mfma_f32_16x16x32_bf16 v[56:59], v[220:223], v[190:193], v[56:59]
	ds_read_b128 v[174:177], v249 offset:13312
	v_mfma_f32_16x16x32_bf16 v[116:119], v[220:223], v[194:197], v[116:119]
	ds_read_b128 v[178:181], v249 offset:14336
	v_mfma_f32_16x16x32_bf16 v[140:143], v[220:223], v[208:211], v[140:143]
	ds_read_b128 v[182:185], v249 offset:15360
	v_mfma_f32_16x16x32_bf16 v[100:103], v[224:227], v[186:189], v[100:103]
	v_mfma_f32_16x16x32_bf16 v[52:55], v[224:227], v[190:193], v[52:55]
	v_mfma_f32_16x16x32_bf16 v[124:127], v[224:227], v[194:197], v[124:127]
	v_mfma_f32_16x16x32_bf16 v[144:147], v[224:227], v[208:211], v[144:147]
	v_mfma_f32_16x16x32_bf16 v[60:63], v[228:231], v[186:189], v[60:63]
	v_mfma_f32_16x16x32_bf16 v[36:39], v[228:231], v[190:193], v[36:39]
	v_mfma_f32_16x16x32_bf16 v[80:83], v[228:231], v[194:197], v[80:83]
	v_mfma_f32_16x16x32_bf16 v[92:95], v[228:231], v[208:211], v[92:95]
	v_mfma_f32_16x16x32_bf16 v[48:51], v[232:235], v[186:189], v[48:51]
	v_mfma_f32_16x16x32_bf16 v[32:35], v[232:235], v[190:193], v[32:35]
	v_mfma_f32_16x16x32_bf16 v[84:87], v[232:235], v[194:197], v[84:87]
	v_mfma_f32_16x16x32_bf16 v[88:91], v[232:235], v[208:211], v[88:91]
	v_mfma_f32_16x16x32_bf16 v[44:47], v[236:239], v[186:189], v[44:47]
	v_mfma_f32_16x16x32_bf16 v[28:31], v[236:239], v[190:193], v[28:31]
	v_mfma_f32_16x16x32_bf16 v[96:99], v[236:239], v[194:197], v[96:99]
	v_mfma_f32_16x16x32_bf16 v[76:79], v[236:239], v[208:211], v[76:79]
	v_mfma_f32_16x16x32_bf16 v[40:43], v[240:243], v[186:189], v[40:43]
	v_mfma_f32_16x16x32_bf16 v[24:27], v[240:243], v[190:193], v[24:27]
	v_mfma_f32_16x16x32_bf16 v[72:75], v[240:243], v[194:197], v[72:75]
	v_mfma_f32_16x16x32_bf16 v[148:151], v[240:243], v[208:211], v[148:151]
	s_add_u32 s30, s30, 24576
	s_cmp_eq_u32 s30, 73728
	s_cselect_b32 s30, 0, s30
	s_waitcnt lgkmcnt(0)
	s_barrier
	v_mfma_f32_16x16x32_bf16 v[128:131], v[16:19], v[0:3], v[128:131]
	v_mfma_f32_16x16x32_bf16 v[68:71], v[16:19], v[4:7], v[68:71]
	v_mfma_f32_16x16x32_bf16 v[108:111], v[16:19], v[8:11], v[108:111]
	v_mfma_f32_16x16x32_bf16 v[132:135], v[16:19], v[12:15], v[132:135]
	v_mfma_f32_16x16x32_bf16 v[120:123], v[20:23], v[0:3], v[120:123]
	v_mfma_f32_16x16x32_bf16 v[64:67], v[20:23], v[4:7], v[64:67]
	v_mfma_f32_16x16x32_bf16 v[112:115], v[20:23], v[8:11], v[112:115]
	v_mfma_f32_16x16x32_bf16 v[136:139], v[20:23], v[12:15], v[136:139]
	v_mfma_f32_16x16x32_bf16 v[104:107], v[162:165], v[0:3], v[104:107]
	v_mfma_f32_16x16x32_bf16 v[56:59], v[162:165], v[4:7], v[56:59]
	v_mfma_f32_16x16x32_bf16 v[116:119], v[162:165], v[8:11], v[116:119]
	v_mfma_f32_16x16x32_bf16 v[140:143], v[162:165], v[12:15], v[140:143]
	v_mfma_f32_16x16x32_bf16 v[100:103], v[166:169], v[0:3], v[100:103]
	v_mfma_f32_16x16x32_bf16 v[52:55], v[166:169], v[4:7], v[52:55]
	v_mfma_f32_16x16x32_bf16 v[124:127], v[166:169], v[8:11], v[124:127]
	v_mfma_f32_16x16x32_bf16 v[144:147], v[166:169], v[12:15], v[144:147]
	v_mfma_f32_16x16x32_bf16 v[60:63], v[170:173], v[0:3], v[60:63]
	v_mfma_f32_16x16x32_bf16 v[36:39], v[170:173], v[4:7], v[36:39]
	v_mfma_f32_16x16x32_bf16 v[80:83], v[170:173], v[8:11], v[80:83]
	v_mfma_f32_16x16x32_bf16 v[92:95], v[170:173], v[12:15], v[92:95]
	v_mfma_f32_16x16x32_bf16 v[48:51], v[174:177], v[0:3], v[48:51]
	v_mfma_f32_16x16x32_bf16 v[32:35], v[174:177], v[4:7], v[32:35]
	v_mfma_f32_16x16x32_bf16 v[84:87], v[174:177], v[8:11], v[84:87]
	v_mfma_f32_16x16x32_bf16 v[88:91], v[174:177], v[12:15], v[88:91]
	v_mfma_f32_16x16x32_bf16 v[44:47], v[178:181], v[0:3], v[44:47]
	v_mfma_f32_16x16x32_bf16 v[28:31], v[178:181], v[4:7], v[28:31]
	v_mfma_f32_16x16x32_bf16 v[96:99], v[178:181], v[8:11], v[96:99]
	v_mfma_f32_16x16x32_bf16 v[76:79], v[178:181], v[12:15], v[76:79]
	v_mfma_f32_16x16x32_bf16 v[40:43], v[182:185], v[0:3], v[40:43]
	v_mfma_f32_16x16x32_bf16 v[24:27], v[182:185], v[4:7], v[24:27]
	v_mfma_f32_16x16x32_bf16 v[72:75], v[182:185], v[8:11], v[72:75]
	v_mfma_f32_16x16x32_bf16 v[148:151], v[182:185], v[12:15], v[148:151]
	v_mov_b32 v250, v198
	s_nop 0
	v_and_b32_e32 v251, 15, v250
	v_bfe_u32 v156, v250, 4, 2
	v_bfe_u32 v157, v250, 6, 1
	v_bfe_u32 v158, v250, 7, 1
	v_lshl_add_u32 v158, v158, 6, s4
	v_add_u32_e32 v158, v158, v251
	v_lshl_add_u32 v157, v157, 7, s5
	v_lshl_add_u32 v159, v156, 2, v157
	v_lshlrev_b32_e32 v246, 2, v159
	v_lshl_add_u32 v244, v158, 12, v246
	v_lshlrev_b32_e32 v161, 1, v159
	v_lshl_add_u32 v245, v158, 11, v161
	v_and_b32_e32 v254, 1, v156
	v_mul_u32_u24_e32 v254, 24, v254
	v_add_u32_e32 v254, v254, v245
	v_lshrrev_b32_e32 v161, 6, v157
	v_lshlrev_b32_e32 v161, 2, v161
	v_lshl_add_u32 v247, v158, 6, v161
	v_xor_b32_e32 v248, 16, v200
	v_lshlrev_b32_e32 v248, 2, v248
	v_xor_b32_e32 v249, 32, v200
	v_lshlrev_b32_e32 v249, 2, v249
	s_mov_b32 s24, s78
	s_mov_b32 s25, s79
	s_mov_b32 s26, s78
	s_mov_b32 s27, s79
	s_mov_b32 s28, s96
	s_mov_b32 s29, s97
	s_mov_b32 s30, s94
	s_mov_b32 s31, s95
	s_cmp_lg_u64 s[8:9], 0
	s_cbranch_scc0 .Lgm2_noemit
	global_load_dwordx4 v[208:211], v246, s[10:11]
	global_load_dwordx4 v[212:215], v246, s[10:11] offset:64
	global_load_dwordx4 v[216:219], v246, s[10:11] offset:128
	global_load_dwordx4 v[220:223], v246, s[10:11] offset:192
	global_load_dwordx4 v[224:227], v246, s[10:11] offset:256
	global_load_dwordx4 v[228:231], v246, s[10:11] offset:320
	global_load_dwordx4 v[232:235], v246, s[10:11] offset:384
	global_load_dwordx4 v[236:239], v246, s[10:11] offset:448
	global_load_dwordx4 v[0:3], v244, s[24:25]
	global_load_dwordx4 v[4:7], v244, s[24:25] offset:64
	global_load_dwordx4 v[8:11], v244, s[24:25] offset:128
	global_load_dwordx4 v[12:15], v244, s[24:25] offset:192
	global_load_dwordx4 v[16:19], v244, s[24:25] offset:256
	global_load_dwordx4 v[20:23], v244, s[24:25] offset:320
	global_load_dwordx4 v[162:165], v244, s[24:25] offset:384
	global_load_dwordx4 v[166:169], v244, s[24:25] offset:448
	s_add_u32 s24, s24, 0x10000
	s_addc_u32 s25, s25, 0
	global_load_dwordx4 v[170:173], v244, s[24:25]
	global_load_dwordx4 v[174:177], v244, s[24:25] offset:64
	global_load_dwordx4 v[178:181], v244, s[24:25] offset:128
	global_load_dwordx4 v[182:185], v244, s[24:25] offset:192
	global_load_dwordx4 v[186:189], v244, s[24:25] offset:256
	global_load_dwordx4 v[190:193], v244, s[24:25] offset:320
	global_load_dwordx4 v[194:197], v244, s[24:25] offset:384
	global_load_dwordx4 v[240:243], v244, s[24:25] offset:448
	s_add_u32 s24, s24, 0x10000
	s_addc_u32 s25, s25, 0
	s_waitcnt vmcnt(12)
	v_add_f32_e32 v0, v128, v0
	v_add_f32_e32 v1, v129, v1
	v_add_f32_e32 v2, v130, v2
	v_add_f32_e32 v3, v131, v3
	global_store_dwordx4 v244, v[0:3], s[26:27]
	v_mul_f32_e32 v158, v0, v0
	v_mul_f32_e32 v159, v1, v1
	v_mul_f32_e32 v250, v2, v2
	v_mul_f32_e32 v251, v3, v3
	v_add_f32_e32 v158, v158, v159
	v_add_f32_e32 v250, v250, v251
	v_add_f32_e32 v161, v158, v250
	v_mul_f32_e32 v156, v0, v208
	v_mul_f32_e32 v157, v1, v209
	v_mul_f32_e32 v158, v2, v210
	v_mul_f32_e32 v159, v3, v211
	v_cvt_pk_bf16_f32 v156, v156, v157
	v_cvt_pk_bf16_f32 v157, v158, v159
	v_add_f32_e32 v4, v120, v4
	v_add_f32_e32 v5, v121, v5
	v_add_f32_e32 v6, v122, v6
	v_add_f32_e32 v7, v123, v7
	global_store_dwordx4 v244, v[4:7], s[26:27] offset:64
	v_mul_f32_e32 v158, v4, v4
	v_mul_f32_e32 v159, v5, v5
	v_mul_f32_e32 v250, v6, v6
	v_mul_f32_e32 v251, v7, v7
	v_add_f32_e32 v158, v158, v159
	v_add_f32_e32 v250, v250, v251
	v_add_f32_e32 v158, v158, v250
	v_add_f32_e32 v161, v161, v158
	v_mul_f32_e32 v158, v4, v212
	v_mul_f32_e32 v159, v5, v213
	v_mul_f32_e32 v250, v6, v214
	v_mul_f32_e32 v251, v7, v215
	v_cvt_pk_bf16_f32 v158, v158, v159
	v_cvt_pk_bf16_f32 v159, v250, v251
	s_nop 1
	v_permlane16_swap_b32_e32 v156, v158
	v_permlane16_swap_b32_e32 v157, v159
	global_store_dwordx4 v254, v[156:159], s[28:29]
	v_add_f32_e32 v8, v104, v8
	v_add_f32_e32 v9, v105, v9
	v_add_f32_e32 v10, v106, v10
	v_add_f32_e32 v11, v107, v11
	global_store_dwordx4 v244, v[8:11], s[26:27] offset:128
	v_mul_f32_e32 v158, v8, v8
	v_mul_f32_e32 v159, v9, v9
	v_mul_f32_e32 v250, v10, v10
	v_mul_f32_e32 v251, v11, v11
	v_add_f32_e32 v158, v158, v159
	v_add_f32_e32 v250, v250, v251
	v_add_f32_e32 v158, v158, v250
	v_add_f32_e32 v161, v161, v158
	v_mul_f32_e32 v156, v8, v216
	v_mul_f32_e32 v157, v9, v217
	v_mul_f32_e32 v158, v10, v218
	v_mul_f32_e32 v159, v11, v219
	v_cvt_pk_bf16_f32 v156, v156, v157
	v_cvt_pk_bf16_f32 v157, v158, v159
	v_add_f32_e32 v12, v100, v12
	v_add_f32_e32 v13, v101, v13
	v_add_f32_e32 v14, v102, v14
	v_add_f32_e32 v15, v103, v15
	global_store_dwordx4 v244, v[12:15], s[26:27] offset:192
	v_mul_f32_e32 v158, v12, v12
	v_mul_f32_e32 v159, v13, v13
	v_mul_f32_e32 v250, v14, v14
	v_mul_f32_e32 v251, v15, v15
	v_add_f32_e32 v158, v158, v159
	v_add_f32_e32 v250, v250, v251
	v_add_f32_e32 v158, v158, v250
	v_add_f32_e32 v161, v161, v158
	v_mul_f32_e32 v158, v12, v220
	v_mul_f32_e32 v159, v13, v221
	v_mul_f32_e32 v250, v14, v222
	v_mul_f32_e32 v251, v15, v223
	v_cvt_pk_bf16_f32 v158, v158, v159
	v_cvt_pk_bf16_f32 v159, v250, v251
	s_nop 1
	v_permlane16_swap_b32_e32 v156, v158
	v_permlane16_swap_b32_e32 v157, v159
	global_store_dwordx4 v254, v[156:159], s[28:29] offset:64
	ds_bpermute_b32 v158, v248, v161
	s_waitcnt lgkmcnt(0)
	v_add_f32_e32 v161, v161, v158
	ds_bpermute_b32 v158, v249, v161
	s_waitcnt lgkmcnt(0)
	v_add_f32_e32 v161, v161, v158
	global_store_dword v247, v161, s[30:31]
	global_load_dwordx4 v[0:3], v244, s[24:25]
	global_load_dwordx4 v[4:7], v244, s[24:25] offset:64
	global_load_dwordx4 v[8:11], v244, s[24:25] offset:128
	global_load_dwordx4 v[12:15], v244, s[24:25] offset:192
	s_waitcnt vmcnt(19)
	v_add_f32_e32 v16, v60, v16
	v_add_f32_e32 v17, v61, v17
	v_add_f32_e32 v18, v62, v18
	v_add_f32_e32 v19, v63, v19
	global_store_dwordx4 v244, v[16:19], s[26:27] offset:256
	v_mul_f32_e32 v158, v16, v16
	v_mul_f32_e32 v159, v17, v17
	v_mul_f32_e32 v250, v18, v18
	v_mul_f32_e32 v251, v19, v19
	v_add_f32_e32 v158, v158, v159
	v_add_f32_e32 v250, v250, v251
	v_add_f32_e32 v161, v158, v250
	v_mul_f32_e32 v156, v16, v224
	v_mul_f32_e32 v157, v17, v225
	v_mul_f32_e32 v158, v18, v226
	v_mul_f32_e32 v159, v19, v227
	v_cvt_pk_bf16_f32 v156, v156, v157
	v_cvt_pk_bf16_f32 v157, v158, v159
	v_add_f32_e32 v20, v48, v20
	v_add_f32_e32 v21, v49, v21
	v_add_f32_e32 v22, v50, v22
	v_add_f32_e32 v23, v51, v23
	global_store_dwordx4 v244, v[20:23], s[26:27] offset:320
	v_mul_f32_e32 v158, v20, v20
	v_mul_f32_e32 v159, v21, v21
	v_mul_f32_e32 v250, v22, v22
	v_mul_f32_e32 v251, v23, v23
	v_add_f32_e32 v158, v158, v159
	v_add_f32_e32 v250, v250, v251
	v_add_f32_e32 v158, v158, v250
	v_add_f32_e32 v161, v161, v158
	v_mul_f32_e32 v158, v20, v228
	v_mul_f32_e32 v159, v21, v229
	v_mul_f32_e32 v250, v22, v230
	v_mul_f32_e32 v251, v23, v231
	v_cvt_pk_bf16_f32 v158, v158, v159
	v_cvt_pk_bf16_f32 v159, v250, v251
	s_nop 1
	v_permlane16_swap_b32_e32 v156, v158
	v_permlane16_swap_b32_e32 v157, v159
	global_store_dwordx4 v254, v[156:159], s[28:29] offset:128
	v_add_f32_e32 v162, v44, v162
	v_add_f32_e32 v163, v45, v163
	v_add_f32_e32 v164, v46, v164
	v_add_f32_e32 v165, v47, v165
	global_store_dwordx4 v244, v[162:165], s[26:27] offset:384
	v_mul_f32_e32 v158, v162, v162
	v_mul_f32_e32 v159, v163, v163
	v_mul_f32_e32 v250, v164, v164
	v_mul_f32_e32 v251, v165, v165
	v_add_f32_e32 v158, v158, v159
	v_add_f32_e32 v250, v250, v251
	v_add_f32_e32 v158, v158, v250
	v_add_f32_e32 v161, v161, v158
	v_mul_f32_e32 v156, v162, v232
	v_mul_f32_e32 v157, v163, v233
	v_mul_f32_e32 v158, v164, v234
	v_mul_f32_e32 v159, v165, v235
	v_cvt_pk_bf16_f32 v156, v156, v157
	v_cvt_pk_bf16_f32 v157, v158, v159
	v_add_f32_e32 v166, v40, v166
	v_add_f32_e32 v167, v41, v167
	v_add_f32_e32 v168, v42, v168
	v_add_f32_e32 v169, v43, v169
	global_store_dwordx4 v244, v[166:169], s[26:27] offset:448
	v_mul_f32_e32 v158, v166, v166
	v_mul_f32_e32 v159, v167, v167
	v_mul_f32_e32 v250, v168, v168
	v_mul_f32_e32 v251, v169, v169
	v_add_f32_e32 v158, v158, v159
	v_add_f32_e32 v250, v250, v251
	v_add_f32_e32 v158, v158, v250
	v_add_f32_e32 v161, v161, v158
	v_mul_f32_e32 v158, v166, v236
	v_mul_f32_e32 v159, v167, v237
	v_mul_f32_e32 v250, v168, v238
	v_mul_f32_e32 v251, v169, v239
	v_cvt_pk_bf16_f32 v158, v158, v159
	v_cvt_pk_bf16_f32 v159, v250, v251
	s_nop 1
	v_permlane16_swap_b32_e32 v156, v158
	v_permlane16_swap_b32_e32 v157, v159
	global_store_dwordx4 v254, v[156:159], s[28:29] offset:192
	ds_bpermute_b32 v158, v248, v161
	s_waitcnt lgkmcnt(0)
	v_add_f32_e32 v161, v161, v158
	ds_bpermute_b32 v158, v249, v161
	s_waitcnt lgkmcnt(0)
	v_add_f32_e32 v161, v161, v158
	global_store_dword v247, v161, s[30:31] offset:4
	s_add_u32 s26, s26, 0x10000
	s_addc_u32 s27, s27, 0
	s_add_u32 s28, s28, 0x8000
	s_addc_u32 s29, s29, 0
	s_add_u32 s30, s30, 0x400
	s_addc_u32 s31, s31, 0
	global_load_dwordx4 v[16:19], v244, s[24:25] offset:256
	global_load_dwordx4 v[20:23], v244, s[24:25] offset:320
	global_load_dwordx4 v[162:165], v244, s[24:25] offset:384
	global_load_dwordx4 v[166:169], v244, s[24:25] offset:448
	s_add_u32 s24, s24, 0x10000
	s_addc_u32 s25, s25, 0
	s_waitcnt vmcnt(26)
	v_add_f32_e32 v170, v68, v170
	v_add_f32_e32 v171, v69, v171
	v_add_f32_e32 v172, v70, v172
	v_add_f32_e32 v173, v71, v173
	global_store_dwordx4 v244, v[170:173], s[26:27]
	v_mul_f32_e32 v158, v170, v170
	v_mul_f32_e32 v159, v171, v171
	v_mul_f32_e32 v250, v172, v172
	v_mul_f32_e32 v251, v173, v173
	v_add_f32_e32 v158, v158, v159
	v_add_f32_e32 v250, v250, v251
	v_add_f32_e32 v161, v158, v250
	v_mul_f32_e32 v156, v170, v208
	v_mul_f32_e32 v157, v171, v209
	v_mul_f32_e32 v158, v172, v210
	v_mul_f32_e32 v159, v173, v211
	v_cvt_pk_bf16_f32 v156, v156, v157
	v_cvt_pk_bf16_f32 v157, v158, v159
	v_add_f32_e32 v174, v64, v174
	v_add_f32_e32 v175, v65, v175
	v_add_f32_e32 v176, v66, v176
	v_add_f32_e32 v177, v67, v177
	global_store_dwordx4 v244, v[174:177], s[26:27] offset:64
	v_mul_f32_e32 v158, v174, v174
	v_mul_f32_e32 v159, v175, v175
	v_mul_f32_e32 v250, v176, v176
	v_mul_f32_e32 v251, v177, v177
	v_add_f32_e32 v158, v158, v159
	v_add_f32_e32 v250, v250, v251
	v_add_f32_e32 v158, v158, v250
	v_add_f32_e32 v161, v161, v158
	v_mul_f32_e32 v158, v174, v212
	v_mul_f32_e32 v159, v175, v213
	v_mul_f32_e32 v250, v176, v214
	v_mul_f32_e32 v251, v177, v215
	v_cvt_pk_bf16_f32 v158, v158, v159
	v_cvt_pk_bf16_f32 v159, v250, v251
	s_nop 1
	v_permlane16_swap_b32_e32 v156, v158
	v_permlane16_swap_b32_e32 v157, v159
	global_store_dwordx4 v254, v[156:159], s[28:29]
	v_add_f32_e32 v178, v56, v178
	v_add_f32_e32 v179, v57, v179
	v_add_f32_e32 v180, v58, v180
	v_add_f32_e32 v181, v59, v181
	global_store_dwordx4 v244, v[178:181], s[26:27] offset:128
	v_mul_f32_e32 v158, v178, v178
	v_mul_f32_e32 v159, v179, v179
	v_mul_f32_e32 v250, v180, v180
	v_mul_f32_e32 v251, v181, v181
	v_add_f32_e32 v158, v158, v159
	v_add_f32_e32 v250, v250, v251
	v_add_f32_e32 v158, v158, v250
	v_add_f32_e32 v161, v161, v158
	v_mul_f32_e32 v156, v178, v216
	v_mul_f32_e32 v157, v179, v217
	v_mul_f32_e32 v158, v180, v218
	v_mul_f32_e32 v159, v181, v219
	v_cvt_pk_bf16_f32 v156, v156, v157
	v_cvt_pk_bf16_f32 v157, v158, v159
	v_add_f32_e32 v182, v52, v182
	v_add_f32_e32 v183, v53, v183
	v_add_f32_e32 v184, v54, v184
	v_add_f32_e32 v185, v55, v185
	global_store_dwordx4 v244, v[182:185], s[26:27] offset:192
	v_mul_f32_e32 v158, v182, v182
	v_mul_f32_e32 v159, v183, v183
	v_mul_f32_e32 v250, v184, v184
	v_mul_f32_e32 v251, v185, v185
	v_add_f32_e32 v158, v158, v159
	v_add_f32_e32 v250, v250, v251
	v_add_f32_e32 v158, v158, v250
	v_add_f32_e32 v161, v161, v158
	v_mul_f32_e32 v158, v182, v220
	v_mul_f32_e32 v159, v183, v221
	v_mul_f32_e32 v250, v184, v222
	v_mul_f32_e32 v251, v185, v223
	v_cvt_pk_bf16_f32 v158, v158, v159
	v_cvt_pk_bf16_f32 v159, v250, v251
	s_nop 1
	v_permlane16_swap_b32_e32 v156, v158
	v_permlane16_swap_b32_e32 v157, v159
	global_store_dwordx4 v254, v[156:159], s[28:29] offset:64
	ds_bpermute_b32 v158, v248, v161
	s_waitcnt lgkmcnt(0)
	v_add_f32_e32 v161, v161, v158
	ds_bpermute_b32 v158, v249, v161
	s_waitcnt lgkmcnt(0)
	v_add_f32_e32 v161, v161, v158
	global_store_dword v247, v161, s[30:31]
	global_load_dwordx4 v[170:173], v244, s[24:25]
	global_load_dwordx4 v[174:177], v244, s[24:25] offset:64
	global_load_dwordx4 v[178:181], v244, s[24:25] offset:128
	global_load_dwordx4 v[182:185], v244, s[24:25] offset:192
	s_waitcnt vmcnt(33)
	v_add_f32_e32 v186, v36, v186
	v_add_f32_e32 v187, v37, v187
	v_add_f32_e32 v188, v38, v188
	v_add_f32_e32 v189, v39, v189
	global_store_dwordx4 v244, v[186:189], s[26:27] offset:256
	v_mul_f32_e32 v158, v186, v186
	v_mul_f32_e32 v159, v187, v187
	v_mul_f32_e32 v250, v188, v188
	v_mul_f32_e32 v251, v189, v189
	v_add_f32_e32 v158, v158, v159
	v_add_f32_e32 v250, v250, v251
	v_add_f32_e32 v161, v158, v250
	v_mul_f32_e32 v156, v186, v224
	v_mul_f32_e32 v157, v187, v225
	v_mul_f32_e32 v158, v188, v226
	v_mul_f32_e32 v159, v189, v227
	v_cvt_pk_bf16_f32 v156, v156, v157
	v_cvt_pk_bf16_f32 v157, v158, v159
	v_add_f32_e32 v190, v32, v190
	v_add_f32_e32 v191, v33, v191
	v_add_f32_e32 v192, v34, v192
	v_add_f32_e32 v193, v35, v193
	global_store_dwordx4 v244, v[190:193], s[26:27] offset:320
	v_mul_f32_e32 v158, v190, v190
	v_mul_f32_e32 v159, v191, v191
	v_mul_f32_e32 v250, v192, v192
	v_mul_f32_e32 v251, v193, v193
	v_add_f32_e32 v158, v158, v159
	v_add_f32_e32 v250, v250, v251
	v_add_f32_e32 v158, v158, v250
	v_add_f32_e32 v161, v161, v158
	v_mul_f32_e32 v158, v190, v228
	v_mul_f32_e32 v159, v191, v229
	v_mul_f32_e32 v250, v192, v230
	v_mul_f32_e32 v251, v193, v231
	v_cvt_pk_bf16_f32 v158, v158, v159
	v_cvt_pk_bf16_f32 v159, v250, v251
	s_nop 1
	v_permlane16_swap_b32_e32 v156, v158
	v_permlane16_swap_b32_e32 v157, v159
	global_store_dwordx4 v254, v[156:159], s[28:29] offset:128
	v_add_f32_e32 v194, v28, v194
	v_add_f32_e32 v195, v29, v195
	v_add_f32_e32 v196, v30, v196
	v_add_f32_e32 v197, v31, v197
	global_store_dwordx4 v244, v[194:197], s[26:27] offset:384
	v_mul_f32_e32 v158, v194, v194
	v_mul_f32_e32 v159, v195, v195
	v_mul_f32_e32 v250, v196, v196
	v_mul_f32_e32 v251, v197, v197
	v_add_f32_e32 v158, v158, v159
	v_add_f32_e32 v250, v250, v251
	v_add_f32_e32 v158, v158, v250
	v_add_f32_e32 v161, v161, v158
	v_mul_f32_e32 v156, v194, v232
	v_mul_f32_e32 v157, v195, v233
	v_mul_f32_e32 v158, v196, v234
	v_mul_f32_e32 v159, v197, v235
	v_cvt_pk_bf16_f32 v156, v156, v157
	v_cvt_pk_bf16_f32 v157, v158, v159
	v_add_f32_e32 v240, v24, v240
	v_add_f32_e32 v241, v25, v241
	v_add_f32_e32 v242, v26, v242
	v_add_f32_e32 v243, v27, v243
	global_store_dwordx4 v244, v[240:243], s[26:27] offset:448
	v_mul_f32_e32 v158, v240, v240
	v_mul_f32_e32 v159, v241, v241
	v_mul_f32_e32 v250, v242, v242
	v_mul_f32_e32 v251, v243, v243
	v_add_f32_e32 v158, v158, v159
	v_add_f32_e32 v250, v250, v251
	v_add_f32_e32 v158, v158, v250
	v_add_f32_e32 v161, v161, v158
	v_mul_f32_e32 v158, v240, v236
	v_mul_f32_e32 v159, v241, v237
	v_mul_f32_e32 v250, v242, v238
	v_mul_f32_e32 v251, v243, v239
	v_cvt_pk_bf16_f32 v158, v158, v159
	v_cvt_pk_bf16_f32 v159, v250, v251
	s_nop 1
	v_permlane16_swap_b32_e32 v156, v158
	v_permlane16_swap_b32_e32 v157, v159
	global_store_dwordx4 v254, v[156:159], s[28:29] offset:192
	ds_bpermute_b32 v158, v248, v161
	s_waitcnt lgkmcnt(0)
	v_add_f32_e32 v161, v161, v158
	ds_bpermute_b32 v158, v249, v161
	s_waitcnt lgkmcnt(0)
	v_add_f32_e32 v161, v161, v158
	global_store_dword v247, v161, s[30:31] offset:4
	s_add_u32 s26, s26, 0x10000
	s_addc_u32 s27, s27, 0
	s_add_u32 s28, s28, 0x8000
	s_addc_u32 s29, s29, 0
	s_add_u32 s30, s30, 0x400
	s_addc_u32 s31, s31, 0
	global_load_dwordx4 v[186:189], v244, s[24:25] offset:256
	global_load_dwordx4 v[190:193], v244, s[24:25] offset:320
	global_load_dwordx4 v[194:197], v244, s[24:25] offset:384
	global_load_dwordx4 v[240:243], v244, s[24:25] offset:448
	s_add_u32 s24, s24, 0x10000
	s_addc_u32 s25, s25, 0
	s_waitcnt vmcnt(33)
	v_add_f32_e32 v0, v108, v0
	v_add_f32_e32 v1, v109, v1
	v_add_f32_e32 v2, v110, v2
	v_add_f32_e32 v3, v111, v3
	global_store_dwordx4 v244, v[0:3], s[26:27]
	v_mul_f32_e32 v158, v0, v0
	v_mul_f32_e32 v159, v1, v1
	v_mul_f32_e32 v250, v2, v2
	v_mul_f32_e32 v251, v3, v3
	v_add_f32_e32 v158, v158, v159
	v_add_f32_e32 v250, v250, v251
	v_add_f32_e32 v161, v158, v250
	v_mul_f32_e32 v156, v0, v208
	v_mul_f32_e32 v157, v1, v209
	v_mul_f32_e32 v158, v2, v210
	v_mul_f32_e32 v159, v3, v211
	v_cvt_pk_bf16_f32 v156, v156, v157
	v_cvt_pk_bf16_f32 v157, v158, v159
	v_add_f32_e32 v4, v112, v4
	v_add_f32_e32 v5, v113, v5
	v_add_f32_e32 v6, v114, v6
	v_add_f32_e32 v7, v115, v7
	global_store_dwordx4 v244, v[4:7], s[26:27] offset:64
	v_mul_f32_e32 v158, v4, v4
	v_mul_f32_e32 v159, v5, v5
	v_mul_f32_e32 v250, v6, v6
	v_mul_f32_e32 v251, v7, v7
	v_add_f32_e32 v158, v158, v159
	v_add_f32_e32 v250, v250, v251
	v_add_f32_e32 v158, v158, v250
	v_add_f32_e32 v161, v161, v158
	v_mul_f32_e32 v158, v4, v212
	v_mul_f32_e32 v159, v5, v213
	v_mul_f32_e32 v250, v6, v214
	v_mul_f32_e32 v251, v7, v215
	v_cvt_pk_bf16_f32 v158, v158, v159
	v_cvt_pk_bf16_f32 v159, v250, v251
	s_nop 1
	v_permlane16_swap_b32_e32 v156, v158
	v_permlane16_swap_b32_e32 v157, v159
	global_store_dwordx4 v254, v[156:159], s[28:29]
	v_add_f32_e32 v8, v116, v8
	v_add_f32_e32 v9, v117, v9
	v_add_f32_e32 v10, v118, v10
	v_add_f32_e32 v11, v119, v11
	global_store_dwordx4 v244, v[8:11], s[26:27] offset:128
	v_mul_f32_e32 v158, v8, v8
	v_mul_f32_e32 v159, v9, v9
	v_mul_f32_e32 v250, v10, v10
	v_mul_f32_e32 v251, v11, v11
	v_add_f32_e32 v158, v158, v159
	v_add_f32_e32 v250, v250, v251
	v_add_f32_e32 v158, v158, v250
	v_add_f32_e32 v161, v161, v158
	v_mul_f32_e32 v156, v8, v216
	v_mul_f32_e32 v157, v9, v217
	v_mul_f32_e32 v158, v10, v218
	v_mul_f32_e32 v159, v11, v219
	v_cvt_pk_bf16_f32 v156, v156, v157
	v_cvt_pk_bf16_f32 v157, v158, v159
	v_add_f32_e32 v12, v124, v12
	v_add_f32_e32 v13, v125, v13
	v_add_f32_e32 v14, v126, v14
	v_add_f32_e32 v15, v127, v15
	global_store_dwordx4 v244, v[12:15], s[26:27] offset:192
	v_mul_f32_e32 v158, v12, v12
	v_mul_f32_e32 v159, v13, v13
	v_mul_f32_e32 v250, v14, v14
	v_mul_f32_e32 v251, v15, v15
	v_add_f32_e32 v158, v158, v159
	v_add_f32_e32 v250, v250, v251
	v_add_f32_e32 v158, v158, v250
	v_add_f32_e32 v161, v161, v158
	v_mul_f32_e32 v158, v12, v220
	v_mul_f32_e32 v159, v13, v221
	v_mul_f32_e32 v250, v14, v222
	v_mul_f32_e32 v251, v15, v223
	v_cvt_pk_bf16_f32 v158, v158, v159
	v_cvt_pk_bf16_f32 v159, v250, v251
	s_nop 1
	v_permlane16_swap_b32_e32 v156, v158
	v_permlane16_swap_b32_e32 v157, v159
	global_store_dwordx4 v254, v[156:159], s[28:29] offset:64
	ds_bpermute_b32 v158, v248, v161
	s_waitcnt lgkmcnt(0)
	v_add_f32_e32 v161, v161, v158
	ds_bpermute_b32 v158, v249, v161
	s_waitcnt lgkmcnt(0)
	v_add_f32_e32 v161, v161, v158
	global_store_dword v247, v161, s[30:31]
	s_waitcnt vmcnt(29)
	v_add_f32_e32 v16, v80, v16
	v_add_f32_e32 v17, v81, v17
	v_add_f32_e32 v18, v82, v18
	v_add_f32_e32 v19, v83, v19
	global_store_dwordx4 v244, v[16:19], s[26:27] offset:256
	v_mul_f32_e32 v158, v16, v16
	v_mul_f32_e32 v159, v17, v17
	v_mul_f32_e32 v250, v18, v18
	v_mul_f32_e32 v251, v19, v19
	v_add_f32_e32 v158, v158, v159
	v_add_f32_e32 v250, v250, v251
	v_add_f32_e32 v161, v158, v250
	v_mul_f32_e32 v156, v16, v224
	v_mul_f32_e32 v157, v17, v225
	v_mul_f32_e32 v158, v18, v226
	v_mul_f32_e32 v159, v19, v227
	v_cvt_pk_bf16_f32 v156, v156, v157
	v_cvt_pk_bf16_f32 v157, v158, v159
	v_add_f32_e32 v20, v84, v20
	v_add_f32_e32 v21, v85, v21
	v_add_f32_e32 v22, v86, v22
	v_add_f32_e32 v23, v87, v23
	global_store_dwordx4 v244, v[20:23], s[26:27] offset:320
	v_mul_f32_e32 v158, v20, v20
	v_mul_f32_e32 v159, v21, v21
	v_mul_f32_e32 v250, v22, v22
	v_mul_f32_e32 v251, v23, v23
	v_add_f32_e32 v158, v158, v159
	v_add_f32_e32 v250, v250, v251
	v_add_f32_e32 v158, v158, v250
	v_add_f32_e32 v161, v161, v158
	v_mul_f32_e32 v158, v20, v228
	v_mul_f32_e32 v159, v21, v229
	v_mul_f32_e32 v250, v22, v230
	v_mul_f32_e32 v251, v23, v231
	v_cvt_pk_bf16_f32 v158, v158, v159
	v_cvt_pk_bf16_f32 v159, v250, v251
	s_nop 1
	v_permlane16_swap_b32_e32 v156, v158
	v_permlane16_swap_b32_e32 v157, v159
	global_store_dwordx4 v254, v[156:159], s[28:29] offset:128
	v_add_f32_e32 v162, v96, v162
	v_add_f32_e32 v163, v97, v163
	v_add_f32_e32 v164, v98, v164
	v_add_f32_e32 v165, v99, v165
	global_store_dwordx4 v244, v[162:165], s[26:27] offset:384
	v_mul_f32_e32 v158, v162, v162
	v_mul_f32_e32 v159, v163, v163
	v_mul_f32_e32 v250, v164, v164
	v_mul_f32_e32 v251, v165, v165
	v_add_f32_e32 v158, v158, v159
	v_add_f32_e32 v250, v250, v251
	v_add_f32_e32 v158, v158, v250
	v_add_f32_e32 v161, v161, v158
	v_mul_f32_e32 v156, v162, v232
	v_mul_f32_e32 v157, v163, v233
	v_mul_f32_e32 v158, v164, v234
	v_mul_f32_e32 v159, v165, v235
	v_cvt_pk_bf16_f32 v156, v156, v157
	v_cvt_pk_bf16_f32 v157, v158, v159
	v_add_f32_e32 v166, v72, v166
	v_add_f32_e32 v167, v73, v167
	v_add_f32_e32 v168, v74, v168
	v_add_f32_e32 v169, v75, v169
	global_store_dwordx4 v244, v[166:169], s[26:27] offset:448
	v_mul_f32_e32 v158, v166, v166
	v_mul_f32_e32 v159, v167, v167
	v_mul_f32_e32 v250, v168, v168
	v_mul_f32_e32 v251, v169, v169
	v_add_f32_e32 v158, v158, v159
	v_add_f32_e32 v250, v250, v251
	v_add_f32_e32 v158, v158, v250
	v_add_f32_e32 v161, v161, v158
	v_mul_f32_e32 v158, v166, v236
	v_mul_f32_e32 v159, v167, v237
	v_mul_f32_e32 v250, v168, v238
	v_mul_f32_e32 v251, v169, v239
	v_cvt_pk_bf16_f32 v158, v158, v159
	v_cvt_pk_bf16_f32 v159, v250, v251
	s_nop 1
	v_permlane16_swap_b32_e32 v156, v158
	v_permlane16_swap_b32_e32 v157, v159
	global_store_dwordx4 v254, v[156:159], s[28:29] offset:192
	ds_bpermute_b32 v158, v248, v161
	s_waitcnt lgkmcnt(0)
	v_add_f32_e32 v161, v161, v158
	ds_bpermute_b32 v158, v249, v161
	s_waitcnt lgkmcnt(0)
	v_add_f32_e32 v161, v161, v158
	global_store_dword v247, v161, s[30:31] offset:4
	s_add_u32 s26, s26, 0x10000
	s_addc_u32 s27, s27, 0
	s_add_u32 s28, s28, 0x8000
	s_addc_u32 s29, s29, 0
	s_add_u32 s30, s30, 0x400
	s_addc_u32 s31, s31, 0
	s_waitcnt vmcnt(25)
	v_add_f32_e32 v170, v132, v170
	v_add_f32_e32 v171, v133, v171
	v_add_f32_e32 v172, v134, v172
	v_add_f32_e32 v173, v135, v173
	global_store_dwordx4 v244, v[170:173], s[26:27]
	v_mul_f32_e32 v158, v170, v170
	v_mul_f32_e32 v159, v171, v171
	v_mul_f32_e32 v250, v172, v172
	v_mul_f32_e32 v251, v173, v173
	v_add_f32_e32 v158, v158, v159
	v_add_f32_e32 v250, v250, v251
	v_add_f32_e32 v161, v158, v250
	v_mul_f32_e32 v156, v170, v208
	v_mul_f32_e32 v157, v171, v209
	v_mul_f32_e32 v158, v172, v210
	v_mul_f32_e32 v159, v173, v211
	v_cvt_pk_bf16_f32 v156, v156, v157
	v_cvt_pk_bf16_f32 v157, v158, v159
	v_add_f32_e32 v174, v136, v174
	v_add_f32_e32 v175, v137, v175
	v_add_f32_e32 v176, v138, v176
	v_add_f32_e32 v177, v139, v177
	global_store_dwordx4 v244, v[174:177], s[26:27] offset:64
	v_mul_f32_e32 v158, v174, v174
	v_mul_f32_e32 v159, v175, v175
	v_mul_f32_e32 v250, v176, v176
	v_mul_f32_e32 v251, v177, v177
	v_add_f32_e32 v158, v158, v159
	v_add_f32_e32 v250, v250, v251
	v_add_f32_e32 v158, v158, v250
	v_add_f32_e32 v161, v161, v158
	v_mul_f32_e32 v158, v174, v212
	v_mul_f32_e32 v159, v175, v213
	v_mul_f32_e32 v250, v176, v214
	v_mul_f32_e32 v251, v177, v215
	v_cvt_pk_bf16_f32 v158, v158, v159
	v_cvt_pk_bf16_f32 v159, v250, v251
	s_nop 1
	v_permlane16_swap_b32_e32 v156, v158
	v_permlane16_swap_b32_e32 v157, v159
	global_store_dwordx4 v254, v[156:159], s[28:29]
	v_add_f32_e32 v178, v140, v178
	v_add_f32_e32 v179, v141, v179
	v_add_f32_e32 v180, v142, v180
	v_add_f32_e32 v181, v143, v181
	global_store_dwordx4 v244, v[178:181], s[26:27] offset:128
	v_mul_f32_e32 v158, v178, v178
	v_mul_f32_e32 v159, v179, v179
	v_mul_f32_e32 v250, v180, v180
	v_mul_f32_e32 v251, v181, v181
	v_add_f32_e32 v158, v158, v159
	v_add_f32_e32 v250, v250, v251
	v_add_f32_e32 v158, v158, v250
	v_add_f32_e32 v161, v161, v158
	v_mul_f32_e32 v156, v178, v216
	v_mul_f32_e32 v157, v179, v217
	v_mul_f32_e32 v158, v180, v218
	v_mul_f32_e32 v159, v181, v219
	v_cvt_pk_bf16_f32 v156, v156, v157
	v_cvt_pk_bf16_f32 v157, v158, v159
	v_add_f32_e32 v182, v144, v182
	v_add_f32_e32 v183, v145, v183
	v_add_f32_e32 v184, v146, v184
	v_add_f32_e32 v185, v147, v185
	global_store_dwordx4 v244, v[182:185], s[26:27] offset:192
	v_mul_f32_e32 v158, v182, v182
	v_mul_f32_e32 v159, v183, v183
	v_mul_f32_e32 v250, v184, v184
	v_mul_f32_e32 v251, v185, v185
	v_add_f32_e32 v158, v158, v159
	v_add_f32_e32 v250, v250, v251
	v_add_f32_e32 v158, v158, v250
	v_add_f32_e32 v161, v161, v158
	v_mul_f32_e32 v158, v182, v220
	v_mul_f32_e32 v159, v183, v221
	v_mul_f32_e32 v250, v184, v222
	v_mul_f32_e32 v251, v185, v223
	v_cvt_pk_bf16_f32 v158, v158, v159
	v_cvt_pk_bf16_f32 v159, v250, v251
	s_nop 1
	v_permlane16_swap_b32_e32 v156, v158
	v_permlane16_swap_b32_e32 v157, v159
	global_store_dwordx4 v254, v[156:159], s[28:29] offset:64
	ds_bpermute_b32 v158, v248, v161
	s_waitcnt lgkmcnt(0)
	v_add_f32_e32 v161, v161, v158
	ds_bpermute_b32 v158, v249, v161
	s_waitcnt lgkmcnt(0)
	v_add_f32_e32 v161, v161, v158
	global_store_dword v247, v161, s[30:31]
	s_waitcnt vmcnt(21)
	v_add_f32_e32 v186, v92, v186
	v_add_f32_e32 v187, v93, v187
	v_add_f32_e32 v188, v94, v188
	v_add_f32_e32 v189, v95, v189
	global_store_dwordx4 v244, v[186:189], s[26:27] offset:256
	v_mul_f32_e32 v158, v186, v186
	v_mul_f32_e32 v159, v187, v187
	v_mul_f32_e32 v250, v188, v188
	v_mul_f32_e32 v251, v189, v189
	v_add_f32_e32 v158, v158, v159
	v_add_f32_e32 v250, v250, v251
	v_add_f32_e32 v161, v158, v250
	v_mul_f32_e32 v156, v186, v224
	v_mul_f32_e32 v157, v187, v225
	v_mul_f32_e32 v158, v188, v226
	v_mul_f32_e32 v159, v189, v227
	v_cvt_pk_bf16_f32 v156, v156, v157
	v_cvt_pk_bf16_f32 v157, v158, v159
	v_add_f32_e32 v190, v88, v190
	v_add_f32_e32 v191, v89, v191
	v_add_f32_e32 v192, v90, v192
	v_add_f32_e32 v193, v91, v193
	global_store_dwordx4 v244, v[190:193], s[26:27] offset:320
	v_mul_f32_e32 v158, v190, v190
	v_mul_f32_e32 v159, v191, v191
	v_mul_f32_e32 v250, v192, v192
	v_mul_f32_e32 v251, v193, v193
	v_add_f32_e32 v158, v158, v159
	v_add_f32_e32 v250, v250, v251
	v_add_f32_e32 v158, v158, v250
	v_add_f32_e32 v161, v161, v158
	v_mul_f32_e32 v158, v190, v228
	v_mul_f32_e32 v159, v191, v229
	v_mul_f32_e32 v250, v192, v230
	v_mul_f32_e32 v251, v193, v231
	v_cvt_pk_bf16_f32 v158, v158, v159
	v_cvt_pk_bf16_f32 v159, v250, v251
	s_nop 1
	v_permlane16_swap_b32_e32 v156, v158
	v_permlane16_swap_b32_e32 v157, v159
	global_store_dwordx4 v254, v[156:159], s[28:29] offset:128
	v_add_f32_e32 v194, v76, v194
	v_add_f32_e32 v195, v77, v195
	v_add_f32_e32 v196, v78, v196
	v_add_f32_e32 v197, v79, v197
	global_store_dwordx4 v244, v[194:197], s[26:27] offset:384
	v_mul_f32_e32 v158, v194, v194
	v_mul_f32_e32 v159, v195, v195
	v_mul_f32_e32 v250, v196, v196
	v_mul_f32_e32 v251, v197, v197
	v_add_f32_e32 v158, v158, v159
	v_add_f32_e32 v250, v250, v251
	v_add_f32_e32 v158, v158, v250
	v_add_f32_e32 v161, v161, v158
	v_mul_f32_e32 v156, v194, v232
	v_mul_f32_e32 v157, v195, v233
	v_mul_f32_e32 v158, v196, v234
	v_mul_f32_e32 v159, v197, v235
	v_cvt_pk_bf16_f32 v156, v156, v157
	v_cvt_pk_bf16_f32 v157, v158, v159
	v_add_f32_e32 v240, v148, v240
	v_add_f32_e32 v241, v149, v241
	v_add_f32_e32 v242, v150, v242
	v_add_f32_e32 v243, v151, v243
	global_store_dwordx4 v244, v[240:243], s[26:27] offset:448
	v_mul_f32_e32 v158, v240, v240
	v_mul_f32_e32 v159, v241, v241
	v_mul_f32_e32 v250, v242, v242
	v_mul_f32_e32 v251, v243, v243
	v_add_f32_e32 v158, v158, v159
	v_add_f32_e32 v250, v250, v251
	v_add_f32_e32 v158, v158, v250
	v_add_f32_e32 v161, v161, v158
	v_mul_f32_e32 v158, v240, v236
	v_mul_f32_e32 v159, v241, v237
	v_mul_f32_e32 v250, v242, v238
	v_mul_f32_e32 v251, v243, v239
	v_cvt_pk_bf16_f32 v158, v158, v159
	v_cvt_pk_bf16_f32 v159, v250, v251
	s_nop 1
	v_permlane16_swap_b32_e32 v156, v158
	v_permlane16_swap_b32_e32 v157, v159
	global_store_dwordx4 v254, v[156:159], s[28:29] offset:192
	ds_bpermute_b32 v158, v248, v161
	s_waitcnt lgkmcnt(0)
	v_add_f32_e32 v161, v161, v158
	ds_bpermute_b32 v158, v249, v161
	s_waitcnt lgkmcnt(0)
	v_add_f32_e32 v161, v161, v158
	global_store_dword v247, v161, s[30:31] offset:4
	s_add_u32 s26, s26, 0x10000
	s_addc_u32 s27, s27, 0
	s_add_u32 s28, s28, 0x8000
	s_addc_u32 s29, s29, 0
	s_add_u32 s30, s30, 0x400
	s_addc_u32 s31, s31, 0
	s_branch .LBB0_360

.Lproj_cd:
	s_or_b32 s4, s16, s67
	v_mov_b32 v10, v198
	v_ashrrev_i32_e32 v0, 2, v10
	s_lshl_b32 s4, s4, 7
	v_add_u32_e32 v2, s4, v0
	v_ashrrev_i32_e32 v3, 31, v2
	v_lshlrev_b64 v[2:3], 11, v[2:3]
	v_lshlrev_b32_e32 v1, 4, v10
	v_add_u32_e32 v4, s17, v0
	v_lshl_add_u64 v[2:3], s[96:97], 0, v[2:3]
	v_and_b32_e32 v152, 48, v1
	v_ashrrev_i32_e32 v5, 31, v4
	v_lshl_add_u64 v[2:3], v[2:3], 0, v[152:153]
	v_lshlrev_b64 v[4:5], 6, v[4:5]
	v_lshl_add_u64 v[156:157], s[8:9], 0, v[4:5]
	v_add_co_u32_e32 v6, vcc, s62, v2
	v_lshl_add_u64 v[4:5], v[156:157], 0, v[152:153]
	s_nop 0
	v_addc_co_u32_e32 v7, vcc, 0, v3, vcc
	v_add_co_u32_e32 v8, vcc, s62, v4
	s_and_b32 s7, s42, 56
	v_lshrrev_b32_e32 v1, 2, v10
	s_or_b32 s6, s67, s6
	v_addc_co_u32_e32 v9, vcc, 0, v5, vcc
	v_and_b32_e32 v12, 12, v1
	s_movk_i32 s20, 0x1230
	s_or_b32 s84, s6, s7
	v_add_co_u32_e32 v60, vcc, s33, v4
	v_lshrrev_b32_e64 v12, v12, s20
	s_lshl_b64 s[6:7], s[84:85], 18
	v_addc_co_u32_e32 v61, vcc, 0, v5, vcc
	v_and_b32_e32 v11, 3, v10
	v_ashrrev_i32_e32 v1, 31, v0
	v_xor_b32_e32 v10, v12, v10
	s_add_u32 s6, s82, s6
	v_add_co_u32_e32 v62, vcc, s72, v4
	v_lshlrev_b32_e32 v13, 6, v0
	v_lshlrev_b64 v[0:1], 11, v[0:1]
	v_lshlrev_b32_e32 v10, 4, v10
	s_addc_u32 s7, s83, s7
	v_addc_co_u32_e32 v63, vcc, 0, v5, vcc
	s_nop 0
	v_readfirstlane_b32 s26, v2
	v_readfirstlane_b32 s27, v3
	v_readfirstlane_b32 s28, v4
	v_readfirstlane_b32 s29, v5
	v_lshrrev_b32_e32 v250, 6, v198
	s_nop 0
	v_readfirstlane_b32 s24, v250
	s_lshl_b32 s24, s24, 10
	v_lshrrev_b32_e32 v250, 2, v200
	v_lshrrev_b32_e32 v251, 4, v200
	v_lshlrev_b32_e32 v251, 2, v251
	v_mov_b32_e32 v248, 0x1230
	v_lshrrev_b32_e32 v251, v251, v248
	v_xor_b32_e32 v251, v251, v200
	v_and_b32_e32 v251, 3, v251
	v_lshlrev_b32_e32 v251, 4, v251
	v_lshl_add_u32 v244, v250, 11, v251
	v_add_u32_e32 v245, 0x20000, v244
	v_add_u32_e32 v246, 0x40000, v244
	v_add_u32_e32 v247, 0x60000, v244
	v_lshl_add_u32 v156, v250, 6, v251
	v_add_u32_e32 v157, 0x1000, v156
	v_add_u32_e32 v158, 0x2000, v156
	v_add_u32_e32 v159, 0x3000, v156
	s_mov_b32 s25, 0
	s_add_u32 m0, s25, s24
	s_nop 0
	global_load_lds_dwordx4 v244, s[26:27]
	s_add_u32 m0, m0, 0x1000
	s_nop 0
	global_load_lds_dwordx4 v245, s[26:27]
	s_add_u32 m0, m0, 0x1000
	s_nop 0
	global_load_lds_dwordx4 v156, s[28:29]
	s_add_u32 m0, m0, 0x1000
	s_nop 0
	global_load_lds_dwordx4 v157, s[28:29]
	s_add_u32 m0, m0, 0x1000
	s_nop 0
	global_load_lds_dwordx4 v158, s[28:29]
	s_add_u32 m0, m0, 0x1000
	s_nop 0
	global_load_lds_dwordx4 v159, s[28:29]
	s_add_u32 s26, s26, 64
	s_addc_u32 s27, s27, 0
	s_add_u32 s28, s28, 0x34000
	s_addc_u32 s29, s29, 0
	s_add_u32 s25, s25, 24576
	s_cmp_eq_u32 s25, 73728
	s_cselect_b32 s25, 0, s25
	s_add_u32 m0, s25, s24
	s_nop 0
	global_load_lds_dwordx4 v244, s[26:27]
	s_add_u32 m0, m0, 0x1000
	s_nop 0
	global_load_lds_dwordx4 v245, s[26:27]
	s_add_u32 m0, m0, 0x1000
	s_nop 0
	global_load_lds_dwordx4 v156, s[28:29]
	s_add_u32 m0, m0, 0x1000
	s_nop 0
	global_load_lds_dwordx4 v157, s[28:29]
	s_add_u32 m0, m0, 0x1000
	s_nop 0
	global_load_lds_dwordx4 v158, s[28:29]
	s_add_u32 m0, m0, 0x1000
	s_nop 0
	global_load_lds_dwordx4 v159, s[28:29]
	s_add_u32 s26, s26, 64
	s_addc_u32 s27, s27, 0
	s_add_u32 s28, s28, 0x34000
	s_addc_u32 s29, s29, 0
	s_add_u32 s25, s25, 24576
	s_cmp_eq_u32 s25, 73728
	s_cselect_b32 s25, 0, s25
	s_add_u32 m0, s25, s24
	s_nop 0
	global_load_lds_dwordx4 v244, s[26:27]
	s_add_u32 m0, m0, 0x1000
	s_nop 0
	global_load_lds_dwordx4 v245, s[26:27]
	s_add_u32 m0, m0, 0x1000
	s_nop 0
	global_load_lds_dwordx4 v156, s[28:29]
	s_add_u32 m0, m0, 0x1000
	s_nop 0
	global_load_lds_dwordx4 v157, s[28:29]
	s_add_u32 m0, m0, 0x1000
	s_nop 0
	global_load_lds_dwordx4 v158, s[28:29]
	s_add_u32 m0, m0, 0x1000
	s_nop 0
	global_load_lds_dwordx4 v159, s[28:29]
	s_add_u32 s26, s26, 64
	s_addc_u32 s27, s27, 0
	s_add_u32 s28, s28, 0x34000
	s_addc_u32 s29, s29, 0
	s_add_u32 s25, s25, 24576
	s_cmp_eq_u32 s25, 73728
	s_cselect_b32 s25, 0, s25
	v_mov_b32_e32 v24, 0
	v_mov_b32_e32 v25, v24
	v_mov_b32_e32 v26, v24
	v_mov_b32_e32 v27, v24
	v_mov_b32_e32 v28, v24
	v_mov_b32_e32 v29, v24
	v_mov_b32_e32 v30, v24
	v_mov_b32_e32 v31, v24
	v_mov_b32_e32 v32, v24
	v_mov_b32_e32 v33, v24
	v_mov_b32_e32 v34, v24
	v_mov_b32_e32 v35, v24
	v_mov_b32_e32 v64, v24
	v_mov_b32_e32 v65, v24
	v_mov_b32_e32 v66, v24
	v_mov_b32_e32 v67, v24
	v_mov_b32_e32 v68, v24
	v_mov_b32_e32 v69, v24
	v_mov_b32_e32 v70, v24
	v_mov_b32_e32 v71, v24
	v_mov_b32_e32 v60, v24
	v_mov_b32_e32 v61, v24
	v_mov_b32_e32 v62, v24
	v_mov_b32_e32 v63, v24
	v_mov_b32_e32 v100, v24
	v_mov_b32_e32 v101, v24
	v_mov_b32_e32 v102, v24
	v_mov_b32_e32 v103, v24
	v_mov_b32_e32 v104, v24
	v_mov_b32_e32 v105, v24
	v_mov_b32_e32 v106, v24
	v_mov_b32_e32 v107, v24
	v_mov_b32_e32 v120, v24
	v_mov_b32_e32 v121, v24
	v_mov_b32_e32 v122, v24
	v_mov_b32_e32 v36, v24
	v_mov_b32_e32 v37, v24
	v_mov_b32_e32 v38, v24
	v_mov_b32_e32 v39, v24
	v_mov_b32_e32 v52, v24
	v_mov_b32_e32 v53, v24
	v_mov_b32_e32 v54, v24
	v_mov_b32_e32 v55, v24
	v_mov_b32_e32 v56, v24
	v_mov_b32_e32 v57, v24
	v_mov_b32_e32 v58, v24
	v_mov_b32_e32 v59, v24
	v_mov_b32_e32 v40, v24
	v_mov_b32_e32 v41, v24
	v_mov_b32_e32 v42, v24
	v_mov_b32_e32 v43, v24
	v_mov_b32_e32 v44, v24
	v_mov_b32_e32 v45, v24
	v_mov_b32_e32 v46, v24
	v_mov_b32_e32 v47, v24
	v_mov_b32_e32 v48, v24
	v_mov_b32_e32 v49, v24
	v_mov_b32_e32 v50, v24
	v_mov_b32_e32 v51, v24
	v_mov_b32_e32 v123, v24
	v_mov_b32_e32 v128, v24
	v_mov_b32_e32 v129, v24
	v_mov_b32_e32 v130, v24
	v_mov_b32_e32 v131, v24
	v_mov_b32_e32 v108, v24
	v_mov_b32_e32 v109, v24
	v_mov_b32_e32 v110, v24
	v_mov_b32_e32 v111, v24
	v_mov_b32_e32 v112, v24
	v_mov_b32_e32 v113, v24
	v_mov_b32_e32 v114, v24
	v_mov_b32_e32 v115, v24
	v_mov_b32_e32 v116, v24
	v_mov_b32_e32 v117, v24
	v_mov_b32_e32 v118, v24
	v_mov_b32_e32 v119, v24
	v_mov_b32_e32 v124, v24
	v_mov_b32_e32 v125, v24
	v_mov_b32_e32 v126, v24
	v_mov_b32_e32 v127, v24
	v_mov_b32_e32 v80, v24
	v_mov_b32_e32 v81, v24
	v_mov_b32_e32 v82, v24
	v_mov_b32_e32 v83, v24
	v_mov_b32_e32 v88, v24
	v_mov_b32_e32 v89, v24
	v_mov_b32_e32 v90, v24
	v_mov_b32_e32 v91, v24
	v_mov_b32_e32 v92, v24
	v_mov_b32_e32 v93, v24
	v_mov_b32_e32 v94, v24
	v_mov_b32_e32 v95, v24
	v_mov_b32_e32 v76, v24
	v_mov_b32_e32 v77, v24
	v_mov_b32_e32 v78, v24
	v_mov_b32_e32 v79, v24
	v_mov_b32_e32 v132, v24
	v_mov_b32_e32 v133, v24
	v_mov_b32_e32 v134, v24
	v_mov_b32_e32 v135, v24
	v_mov_b32_e32 v136, v24
	v_mov_b32_e32 v137, v24
	v_mov_b32_e32 v138, v24
	v_mov_b32_e32 v139, v24
	v_mov_b32_e32 v140, v24
	v_mov_b32_e32 v141, v24
	v_mov_b32_e32 v142, v24
	v_mov_b32_e32 v143, v24
	v_mov_b32_e32 v144, v24
	v_mov_b32_e32 v145, v24
	v_mov_b32_e32 v146, v24
	v_mov_b32_e32 v147, v24
	v_mov_b32_e32 v96, v24
	v_mov_b32_e32 v97, v24
	v_mov_b32_e32 v98, v24
	v_mov_b32_e32 v99, v24
	v_mov_b32_e32 v84, v24
	v_mov_b32_e32 v85, v24
	v_mov_b32_e32 v86, v24
	v_mov_b32_e32 v87, v24
	v_mov_b32_e32 v72, v24
	v_mov_b32_e32 v73, v24
	v_mov_b32_e32 v74, v24
	v_mov_b32_e32 v75, v24
	v_mov_b32_e32 v148, v24
	v_mov_b32_e32 v149, v24
	v_mov_b32_e32 v150, v24
	v_mov_b32_e32 v151, v24
	s_waitcnt vmcnt(12)
	s_barrier
	s_mov_b32 s30, 0
	v_add_u32_e32 v248, s30, v155
	v_add_u32_e32 v249, s30, v160
	ds_read_b128 v[186:189], v248
	ds_read_b128 v[212:215], v249 offset:8192
	ds_read_b128 v[190:193], v248 offset:1024
	ds_read_b128 v[216:219], v249 offset:9216
	ds_read_b128 v[194:197], v248 offset:2048
	ds_read_b128 v[220:223], v249 offset:10240
	ds_read_b128 v[208:211], v248 offset:3072
	ds_read_b128 v[224:227], v249 offset:11264
	ds_read_b128 v[228:231], v249 offset:12288
	ds_read_b128 v[232:235], v249 offset:13312
	ds_read_b128 v[236:239], v249 offset:14336
	ds_read_b128 v[240:243], v249 offset:15360
	s_add_u32 s30, s30, 24576
	s_cmp_eq_u32 s30, 73728
	s_cselect_b32 s30, 0, s30
	s_waitcnt vmcnt(6)
	s_waitcnt lgkmcnt(0)
	s_barrier
	s_mov_b32 s31, 14
	s_cmpk_lt_u32 s43, 0x180
	s_cbranch_scc0 .Lgm3_cheap
.Lgm3_loop:
	v_add_u32_e32 v248, s30, v155
	v_add_u32_e32 v249, s30, v160
	v_mfma_f32_16x16x32_bf16 v[128:131], v[212:215], v[186:189], v[128:131]
	ds_read_b128 v[0:3], v248
	v_mfma_f32_16x16x32_bf16 v[68:71], v[212:215], v[190:193], v[68:71]
	ds_read_b128 v[16:19], v249 offset:8192
	v_mfma_f32_16x16x32_bf16 v[108:111], v[212:215], v[194:197], v[108:111]
	ds_read_b128 v[4:7], v248 offset:1024
	v_mfma_f32_16x16x32_bf16 v[132:135], v[212:215], v[208:211], v[132:135]
	ds_read_b128 v[20:23], v249 offset:9216
	v_mfma_f32_16x16x32_bf16 v[120:123], v[216:219], v[186:189], v[120:123]
	ds_read_b128 v[8:11], v248 offset:2048
	v_mfma_f32_16x16x32_bf16 v[64:67], v[216:219], v[190:193], v[64:67]
	ds_read_b128 v[162:165], v249 offset:10240
	v_mfma_f32_16x16x32_bf16 v[112:115], v[216:219], v[194:197], v[112:115]
	ds_read_b128 v[12:15], v248 offset:3072
	v_mfma_f32_16x16x32_bf16 v[136:139], v[216:219], v[208:211], v[136:139]
	ds_read_b128 v[166:169], v249 offset:11264
	v_mfma_f32_16x16x32_bf16 v[104:107], v[220:223], v[186:189], v[104:107]
	ds_read_b128 v[170:173], v249 offset:12288
	v_mfma_f32_16x16x32_bf16 v[56:59], v[220:223], v[190:193], v[56:59]
	ds_read_b128 v[174:177], v249 offset:13312
	v_mfma_f32_16x16x32_bf16 v[116:119], v[220:223], v[194:197], v[116:119]
	ds_read_b128 v[178:181], v249 offset:14336
	v_mfma_f32_16x16x32_bf16 v[140:143], v[220:223], v[208:211], v[140:143]
	ds_read_b128 v[182:185], v249 offset:15360
	s_add_u32 m0, s25, s24
	v_mfma_f32_16x16x32_bf16 v[100:103], v[224:227], v[186:189], v[100:103]
	global_load_lds_dwordx4 v244, s[26:27]
	v_mfma_f32_16x16x32_bf16 v[52:55], v[224:227], v[190:193], v[52:55]
	v_mfma_f32_16x16x32_bf16 v[124:127], v[224:227], v[194:197], v[124:127]
	s_add_u32 m0, m0, 0x1000
	v_mfma_f32_16x16x32_bf16 v[144:147], v[224:227], v[208:211], v[144:147]
	global_load_lds_dwordx4 v245, s[26:27]
	v_mfma_f32_16x16x32_bf16 v[60:63], v[228:231], v[186:189], v[60:63]
	v_mfma_f32_16x16x32_bf16 v[36:39], v[228:231], v[190:193], v[36:39]
	s_add_u32 m0, m0, 0x1000
	v_mfma_f32_16x16x32_bf16 v[80:83], v[228:231], v[194:197], v[80:83]
	global_load_lds_dwordx4 v156, s[28:29]
	v_mfma_f32_16x16x32_bf16 v[96:99], v[228:231], v[208:211], v[96:99]
	v_mfma_f32_16x16x32_bf16 v[48:51], v[232:235], v[186:189], v[48:51]
	s_add_u32 m0, m0, 0x1000
	v_mfma_f32_16x16x32_bf16 v[32:35], v[232:235], v[190:193], v[32:35]
	global_load_lds_dwordx4 v157, s[28:29]
	v_mfma_f32_16x16x32_bf16 v[88:91], v[232:235], v[194:197], v[88:91]
	v_mfma_f32_16x16x32_bf16 v[84:87], v[232:235], v[208:211], v[84:87]
	s_add_u32 m0, m0, 0x1000
	v_mfma_f32_16x16x32_bf16 v[44:47], v[236:239], v[186:189], v[44:47]
	global_load_lds_dwordx4 v158, s[28:29]
	v_mfma_f32_16x16x32_bf16 v[28:31], v[236:239], v[190:193], v[28:31]
	v_mfma_f32_16x16x32_bf16 v[92:95], v[236:239], v[194:197], v[92:95]
	s_add_u32 m0, m0, 0x1000
	v_mfma_f32_16x16x32_bf16 v[72:75], v[236:239], v[208:211], v[72:75]
	global_load_lds_dwordx4 v159, s[28:29]
	v_mfma_f32_16x16x32_bf16 v[40:43], v[240:243], v[186:189], v[40:43]
	v_mfma_f32_16x16x32_bf16 v[24:27], v[240:243], v[190:193], v[24:27]
	v_mfma_f32_16x16x32_bf16 v[76:79], v[240:243], v[194:197], v[76:79]
	v_mfma_f32_16x16x32_bf16 v[148:151], v[240:243], v[208:211], v[148:151]
	s_add_u32 s26, s26, 64
	s_addc_u32 s27, s27, 0
	s_add_u32 s28, s28, 0x34000
	s_addc_u32 s29, s29, 0
	s_add_u32 s25, s25, 24576
	s_cmp_eq_u32 s25, 73728
	s_cselect_b32 s25, 0, s25
	s_add_u32 s30, s30, 24576
	s_cmp_eq_u32 s30, 73728
	s_cselect_b32 s30, 0, s30
	s_waitcnt vmcnt(6)
	s_waitcnt lgkmcnt(0)
	s_barrier
	v_add_u32_e32 v248, s30, v155
	v_add_u32_e32 v249, s30, v160
	v_mfma_f32_16x16x32_bf16 v[128:131], v[16:19], v[0:3], v[128:131]
	ds_read_b128 v[186:189], v248
	v_mfma_f32_16x16x32_bf16 v[68:71], v[16:19], v[4:7], v[68:71]
	ds_read_b128 v[212:215], v249 offset:8192
	v_mfma_f32_16x16x32_bf16 v[108:111], v[16:19], v[8:11], v[108:111]
	ds_read_b128 v[190:193], v248 offset:1024
	v_mfma_f32_16x16x32_bf16 v[132:135], v[16:19], v[12:15], v[132:135]
	ds_read_b128 v[216:219], v249 offset:9216
	v_mfma_f32_16x16x32_bf16 v[120:123], v[20:23], v[0:3], v[120:123]
	ds_read_b128 v[194:197], v248 offset:2048
	v_mfma_f32_16x16x32_bf16 v[64:67], v[20:23], v[4:7], v[64:67]
	ds_read_b128 v[220:223], v249 offset:10240
	v_mfma_f32_16x16x32_bf16 v[112:115], v[20:23], v[8:11], v[112:115]
	ds_read_b128 v[208:211], v248 offset:3072
	v_mfma_f32_16x16x32_bf16 v[136:139], v[20:23], v[12:15], v[136:139]
	ds_read_b128 v[224:227], v249 offset:11264
	v_mfma_f32_16x16x32_bf16 v[104:107], v[162:165], v[0:3], v[104:107]
	ds_read_b128 v[228:231], v249 offset:12288
	v_mfma_f32_16x16x32_bf16 v[56:59], v[162:165], v[4:7], v[56:59]
	ds_read_b128 v[232:235], v249 offset:13312
	v_mfma_f32_16x16x32_bf16 v[116:119], v[162:165], v[8:11], v[116:119]
	ds_read_b128 v[236:239], v249 offset:14336
	v_mfma_f32_16x16x32_bf16 v[140:143], v[162:165], v[12:15], v[140:143]
	ds_read_b128 v[240:243], v249 offset:15360
	s_add_u32 m0, s25, s24
	v_mfma_f32_16x16x32_bf16 v[100:103], v[166:169], v[0:3], v[100:103]
	global_load_lds_dwordx4 v244, s[26:27]
	v_mfma_f32_16x16x32_bf16 v[52:55], v[166:169], v[4:7], v[52:55]
	v_mfma_f32_16x16x32_bf16 v[124:127], v[166:169], v[8:11], v[124:127]
	s_add_u32 m0, m0, 0x1000
	v_mfma_f32_16x16x32_bf16 v[144:147], v[166:169], v[12:15], v[144:147]
	global_load_lds_dwordx4 v245, s[26:27]
	v_mfma_f32_16x16x32_bf16 v[60:63], v[170:173], v[0:3], v[60:63]
	v_mfma_f32_16x16x32_bf16 v[36:39], v[170:173], v[4:7], v[36:39]
	s_add_u32 m0, m0, 0x1000
	v_mfma_f32_16x16x32_bf16 v[80:83], v[170:173], v[8:11], v[80:83]
	global_load_lds_dwordx4 v156, s[28:29]
	v_mfma_f32_16x16x32_bf16 v[96:99], v[170:173], v[12:15], v[96:99]
	v_mfma_f32_16x16x32_bf16 v[48:51], v[174:177], v[0:3], v[48:51]
	s_add_u32 m0, m0, 0x1000
	v_mfma_f32_16x16x32_bf16 v[32:35], v[174:177], v[4:7], v[32:35]
	global_load_lds_dwordx4 v157, s[28:29]
	v_mfma_f32_16x16x32_bf16 v[88:91], v[174:177], v[8:11], v[88:91]
	v_mfma_f32_16x16x32_bf16 v[84:87], v[174:177], v[12:15], v[84:87]
	s_add_u32 m0, m0, 0x1000
	v_mfma_f32_16x16x32_bf16 v[44:47], v[178:181], v[0:3], v[44:47]
	global_load_lds_dwordx4 v158, s[28:29]
	v_mfma_f32_16x16x32_bf16 v[28:31], v[178:181], v[4:7], v[28:31]
	v_mfma_f32_16x16x32_bf16 v[92:95], v[178:181], v[8:11], v[92:95]
	s_add_u32 m0, m0, 0x1000
	v_mfma_f32_16x16x32_bf16 v[72:75], v[178:181], v[12:15], v[72:75]
	global_load_lds_dwordx4 v159, s[28:29]
	v_mfma_f32_16x16x32_bf16 v[40:43], v[182:185], v[0:3], v[40:43]
	v_mfma_f32_16x16x32_bf16 v[24:27], v[182:185], v[4:7], v[24:27]
	v_mfma_f32_16x16x32_bf16 v[76:79], v[182:185], v[8:11], v[76:79]
	v_mfma_f32_16x16x32_bf16 v[148:151], v[182:185], v[12:15], v[148:151]
	s_add_u32 s26, s26, 64
	s_addc_u32 s27, s27, 0
	s_add_u32 s28, s28, 0x34000
	s_addc_u32 s29, s29, 0
	s_add_u32 s25, s25, 24576
	s_cmp_eq_u32 s25, 73728
	s_cselect_b32 s25, 0, s25
	s_add_u32 s30, s30, 24576
	s_cmp_eq_u32 s30, 73728
	s_cselect_b32 s30, 0, s30
	s_waitcnt vmcnt(6)
	s_waitcnt lgkmcnt(0)
	s_barrier
	s_sub_u32 s31, s31, 1
	s_cmp_lg_u32 s31, 0
	s_cbranch_scc1 .Lgm3_loop
	v_add_u32_e32 v248, s30, v155
	v_add_u32_e32 v249, s30, v160
	v_mfma_f32_16x16x32_bf16 v[128:131], v[212:215], v[186:189], v[128:131]
	ds_read_b128 v[0:3], v248
	v_mfma_f32_16x16x32_bf16 v[68:71], v[212:215], v[190:193], v[68:71]
	ds_read_b128 v[16:19], v249 offset:8192
	v_mfma_f32_16x16x32_bf16 v[108:111], v[212:215], v[194:197], v[108:111]
	ds_read_b128 v[4:7], v248 offset:1024
	v_mfma_f32_16x16x32_bf16 v[132:135], v[212:215], v[208:211], v[132:135]
	ds_read_b128 v[20:23], v249 offset:9216
	v_mfma_f32_16x16x32_bf16 v[120:123], v[216:219], v[186:189], v[120:123]
	ds_read_b128 v[8:11], v248 offset:2048
	v_mfma_f32_16x16x32_bf16 v[64:67], v[216:219], v[190:193], v[64:67]
	ds_read_b128 v[162:165], v249 offset:10240
	v_mfma_f32_16x16x32_bf16 v[112:115], v[216:219], v[194:197], v[112:115]
	ds_read_b128 v[12:15], v248 offset:3072
	v_mfma_f32_16x16x32_bf16 v[136:139], v[216:219], v[208:211], v[136:139]
	ds_read_b128 v[166:169], v249 offset:11264
	v_mfma_f32_16x16x32_bf16 v[104:107], v[220:223], v[186:189], v[104:107]
	ds_read_b128 v[170:173], v249 offset:12288
	v_mfma_f32_16x16x32_bf16 v[56:59], v[220:223], v[190:193], v[56:59]
	ds_read_b128 v[174:177], v249 offset:13312
	v_mfma_f32_16x16x32_bf16 v[116:119], v[220:223], v[194:197], v[116:119]
	ds_read_b128 v[178:181], v249 offset:14336
	v_mfma_f32_16x16x32_bf16 v[140:143], v[220:223], v[208:211], v[140:143]
	ds_read_b128 v[182:185], v249 offset:15360
	s_add_u32 m0, s25, s24
	v_mfma_f32_16x16x32_bf16 v[100:103], v[224:227], v[186:189], v[100:103]
	global_load_lds_dwordx4 v244, s[26:27]
	v_mfma_f32_16x16x32_bf16 v[52:55], v[224:227], v[190:193], v[52:55]
	v_mfma_f32_16x16x32_bf16 v[124:127], v[224:227], v[194:197], v[124:127]
	s_add_u32 m0, m0, 0x1000
	v_mfma_f32_16x16x32_bf16 v[144:147], v[224:227], v[208:211], v[144:147]
	global_load_lds_dwordx4 v245, s[26:27]
	v_mfma_f32_16x16x32_bf16 v[60:63], v[228:231], v[186:189], v[60:63]
	v_mfma_f32_16x16x32_bf16 v[36:39], v[228:231], v[190:193], v[36:39]
	s_add_u32 m0, m0, 0x1000
	v_mfma_f32_16x16x32_bf16 v[80:83], v[228:231], v[194:197], v[80:83]
	global_load_lds_dwordx4 v156, s[28:29]
	v_mfma_f32_16x16x32_bf16 v[96:99], v[228:231], v[208:211], v[96:99]
	v_mfma_f32_16x16x32_bf16 v[48:51], v[232:235], v[186:189], v[48:51]
	s_add_u32 m0, m0, 0x1000
	v_mfma_f32_16x16x32_bf16 v[32:35], v[232:235], v[190:193], v[32:35]
	global_load_lds_dwordx4 v157, s[28:29]
	v_mfma_f32_16x16x32_bf16 v[88:91], v[232:235], v[194:197], v[88:91]
	v_mfma_f32_16x16x32_bf16 v[84:87], v[232:235], v[208:211], v[84:87]
	s_add_u32 m0, m0, 0x1000
	v_mfma_f32_16x16x32_bf16 v[44:47], v[236:239], v[186:189], v[44:47]
	global_load_lds_dwordx4 v158, s[28:29]
	v_mfma_f32_16x16x32_bf16 v[28:31], v[236:239], v[190:193], v[28:31]
	v_mfma_f32_16x16x32_bf16 v[92:95], v[236:239], v[194:197], v[92:95]
	s_add_u32 m0, m0, 0x1000
	v_mfma_f32_16x16x32_bf16 v[72:75], v[236:239], v[208:211], v[72:75]
	global_load_lds_dwordx4 v159, s[28:29]
	v_mfma_f32_16x16x32_bf16 v[40:43], v[240:243], v[186:189], v[40:43]
	v_mfma_f32_16x16x32_bf16 v[24:27], v[240:243], v[190:193], v[24:27]
	v_mfma_f32_16x16x32_bf16 v[76:79], v[240:243], v[194:197], v[76:79]
	v_mfma_f32_16x16x32_bf16 v[148:151], v[240:243], v[208:211], v[148:151]
	s_add_u32 s26, s26, 64
	s_addc_u32 s27, s27, 0
	s_add_u32 s28, s28, 0x34000
	s_addc_u32 s29, s29, 0
	s_add_u32 s25, s25, 24576
	s_cmp_eq_u32 s25, 73728
	s_cselect_b32 s25, 0, s25
	s_add_u32 s30, s30, 24576
	s_cmp_eq_u32 s30, 73728
	s_cselect_b32 s30, 0, s30
	s_waitcnt vmcnt(6)
	s_waitcnt lgkmcnt(0)
	s_barrier
	v_mfma_f32_16x16x32_bf16 v[128:131], v[16:19], v[0:3], v[128:131]
	v_mfma_f32_16x16x32_bf16 v[68:71], v[16:19], v[4:7], v[68:71]
	v_mfma_f32_16x16x32_bf16 v[108:111], v[16:19], v[8:11], v[108:111]
	v_mfma_f32_16x16x32_bf16 v[132:135], v[16:19], v[12:15], v[132:135]
	v_mfma_f32_16x16x32_bf16 v[120:123], v[20:23], v[0:3], v[120:123]
	v_mfma_f32_16x16x32_bf16 v[64:67], v[20:23], v[4:7], v[64:67]
	v_mfma_f32_16x16x32_bf16 v[112:115], v[20:23], v[8:11], v[112:115]
	v_mfma_f32_16x16x32_bf16 v[136:139], v[20:23], v[12:15], v[136:139]
	v_mfma_f32_16x16x32_bf16 v[104:107], v[162:165], v[0:3], v[104:107]
	v_mfma_f32_16x16x32_bf16 v[56:59], v[162:165], v[4:7], v[56:59]
	v_mfma_f32_16x16x32_bf16 v[116:119], v[162:165], v[8:11], v[116:119]
	v_mfma_f32_16x16x32_bf16 v[140:143], v[162:165], v[12:15], v[140:143]
	v_mfma_f32_16x16x32_bf16 v[100:103], v[166:169], v[0:3], v[100:103]
	v_mfma_f32_16x16x32_bf16 v[52:55], v[166:169], v[4:7], v[52:55]
	v_mfma_f32_16x16x32_bf16 v[124:127], v[166:169], v[8:11], v[124:127]
	v_mfma_f32_16x16x32_bf16 v[144:147], v[166:169], v[12:15], v[144:147]
	v_mfma_f32_16x16x32_bf16 v[60:63], v[170:173], v[0:3], v[60:63]
	v_mfma_f32_16x16x32_bf16 v[36:39], v[170:173], v[4:7], v[36:39]
	v_mfma_f32_16x16x32_bf16 v[80:83], v[170:173], v[8:11], v[80:83]
	v_mfma_f32_16x16x32_bf16 v[96:99], v[170:173], v[12:15], v[96:99]
	v_mfma_f32_16x16x32_bf16 v[48:51], v[174:177], v[0:3], v[48:51]
	v_mfma_f32_16x16x32_bf16 v[32:35], v[174:177], v[4:7], v[32:35]
	v_mfma_f32_16x16x32_bf16 v[88:91], v[174:177], v[8:11], v[88:91]
	v_mfma_f32_16x16x32_bf16 v[84:87], v[174:177], v[12:15], v[84:87]
	v_mfma_f32_16x16x32_bf16 v[44:47], v[178:181], v[0:3], v[44:47]
	v_mfma_f32_16x16x32_bf16 v[28:31], v[178:181], v[4:7], v[28:31]
	v_mfma_f32_16x16x32_bf16 v[92:95], v[178:181], v[8:11], v[92:95]
	v_mfma_f32_16x16x32_bf16 v[72:75], v[178:181], v[12:15], v[72:75]
	v_mfma_f32_16x16x32_bf16 v[40:43], v[182:185], v[0:3], v[40:43]
	v_mfma_f32_16x16x32_bf16 v[24:27], v[182:185], v[4:7], v[24:27]
	v_mfma_f32_16x16x32_bf16 v[76:79], v[182:185], v[8:11], v[76:79]
	v_mfma_f32_16x16x32_bf16 v[148:151], v[182:185], v[12:15], v[148:151]
	s_waitcnt vmcnt(0)
	s_waitcnt lgkmcnt(0)
	s_barrier
	s_branch .Lgm3_tail
.Lgm3_cheap:
	v_add_u32_e32 v248, s30, v155
	v_add_u32_e32 v249, s30, v160
	v_mfma_f32_16x16x32_bf16 v[128:131], v[212:215], v[186:189], v[128:131]
	ds_read_b128 v[0:3], v248
	v_mfma_f32_16x16x32_bf16 v[68:71], v[212:215], v[190:193], v[68:71]
	ds_read_b128 v[16:19], v249 offset:8192
	v_mfma_f32_16x16x32_bf16 v[108:111], v[212:215], v[194:197], v[108:111]
	ds_read_b128 v[4:7], v248 offset:1024
	v_mfma_f32_16x16x32_bf16 v[132:135], v[212:215], v[208:211], v[132:135]
	ds_read_b128 v[20:23], v249 offset:9216
	v_mfma_f32_16x16x32_bf16 v[120:123], v[216:219], v[186:189], v[120:123]
	ds_read_b128 v[8:11], v248 offset:2048
	s_add_u32 m0, s25, s24
	v_mfma_f32_16x16x32_bf16 v[64:67], v[216:219], v[190:193], v[64:67]
	ds_read_b128 v[12:15], v248 offset:3072
	global_load_lds_dwordx4 v244, s[26:27]
	s_add_u32 m0, m0, 0x1000
	v_mfma_f32_16x16x32_bf16 v[112:115], v[216:219], v[194:197], v[112:115]
	global_load_lds_dwordx4 v245, s[26:27]
	s_add_u32 m0, m0, 0x1000
	v_mfma_f32_16x16x32_bf16 v[136:139], v[216:219], v[208:211], v[136:139]
	global_load_lds_dwordx4 v156, s[28:29]
	s_add_u32 s26, s26, 64
	s_addc_u32 s27, s27, 0
	s_add_u32 s28, s28, 0x34000
	s_addc_u32 s29, s29, 0
	s_add_u32 s25, s25, 24576
	s_cmp_eq_u32 s25, 73728
	s_cselect_b32 s25, 0, s25
	s_add_u32 s30, s30, 24576
	s_cmp_eq_u32 s30, 73728
	s_cselect_b32 s30, 0, s30
	s_waitcnt vmcnt(3)
	s_waitcnt lgkmcnt(0)
	s_barrier
	v_add_u32_e32 v248, s30, v155
	v_add_u32_e32 v249, s30, v160
	v_mfma_f32_16x16x32_bf16 v[128:131], v[16:19], v[0:3], v[128:131]
	ds_read_b128 v[186:189], v248
	v_mfma_f32_16x16x32_bf16 v[68:71], v[16:19], v[4:7], v[68:71]
	ds_read_b128 v[212:215], v249 offset:8192
	v_mfma_f32_16x16x32_bf16 v[108:111], v[16:19], v[8:11], v[108:111]
	ds_read_b128 v[190:193], v248 offset:1024
	v_mfma_f32_16x16x32_bf16 v[132:135], v[16:19], v[12:15], v[132:135]
	ds_read_b128 v[216:219], v249 offset:9216
	v_mfma_f32_16x16x32_bf16 v[120:123], v[20:23], v[0:3], v[120:123]
	ds_read_b128 v[194:197], v248 offset:2048
	s_add_u32 m0, s25, s24
	v_mfma_f32_16x16x32_bf16 v[64:67], v[20:23], v[4:7], v[64:67]
	ds_read_b128 v[208:211], v248 offset:3072
	global_load_lds_dwordx4 v244, s[26:27]
	s_add_u32 m0, m0, 0x1000
	v_mfma_f32_16x16x32_bf16 v[112:115], v[20:23], v[8:11], v[112:115]
	global_load_lds_dwordx4 v245, s[26:27]
	s_add_u32 m0, m0, 0x1000
	v_mfma_f32_16x16x32_bf16 v[136:139], v[20:23], v[12:15], v[136:139]
	global_load_lds_dwordx4 v156, s[28:29]
	s_add_u32 s26, s26, 64
	s_addc_u32 s27, s27, 0
	s_add_u32 s28, s28, 0x34000
	s_addc_u32 s29, s29, 0
	s_add_u32 s25, s25, 24576
	s_cmp_eq_u32 s25, 73728
	s_cselect_b32 s25, 0, s25
	s_add_u32 s30, s30, 24576
	s_cmp_eq_u32 s30, 73728
	s_cselect_b32 s30, 0, s30
	s_waitcnt vmcnt(3)
	s_waitcnt lgkmcnt(0)
	s_barrier
	s_sub_u32 s31, s31, 1
	s_cmp_lg_u32 s31, 0
	s_cbranch_scc1 .Lgm3_cheap
	v_add_u32_e32 v248, s30, v155
	v_add_u32_e32 v249, s30, v160
	v_mfma_f32_16x16x32_bf16 v[128:131], v[212:215], v[186:189], v[128:131]
	ds_read_b128 v[0:3], v248
	v_mfma_f32_16x16x32_bf16 v[68:71], v[212:215], v[190:193], v[68:71]
	ds_read_b128 v[16:19], v249 offset:8192
	v_mfma_f32_16x16x32_bf16 v[108:111], v[212:215], v[194:197], v[108:111]
	ds_read_b128 v[4:7], v248 offset:1024
	v_mfma_f32_16x16x32_bf16 v[132:135], v[212:215], v[208:211], v[132:135]
	ds_read_b128 v[20:23], v249 offset:9216
	v_mfma_f32_16x16x32_bf16 v[120:123], v[216:219], v[186:189], v[120:123]
	ds_read_b128 v[8:11], v248 offset:2048
	s_add_u32 m0, s25, s24
	v_mfma_f32_16x16x32_bf16 v[64:67], v[216:219], v[190:193], v[64:67]
	ds_read_b128 v[12:15], v248 offset:3072
	global_load_lds_dwordx4 v244, s[26:27]
	s_add_u32 m0, m0, 0x1000
	v_mfma_f32_16x16x32_bf16 v[112:115], v[216:219], v[194:197], v[112:115]
	global_load_lds_dwordx4 v245, s[26:27]
	s_add_u32 m0, m0, 0x1000
	v_mfma_f32_16x16x32_bf16 v[136:139], v[216:219], v[208:211], v[136:139]
	global_load_lds_dwordx4 v156, s[28:29]
	s_add_u32 s26, s26, 64
	s_addc_u32 s27, s27, 0
	s_add_u32 s28, s28, 0x34000
	s_addc_u32 s29, s29, 0
	s_add_u32 s25, s25, 24576
	s_cmp_eq_u32 s25, 73728
	s_cselect_b32 s25, 0, s25
	s_add_u32 s30, s30, 24576
	s_cmp_eq_u32 s30, 73728
	s_cselect_b32 s30, 0, s30
	s_waitcnt vmcnt(3)
	s_waitcnt lgkmcnt(0)
	s_barrier
	v_mfma_f32_16x16x32_bf16 v[128:131], v[16:19], v[0:3], v[128:131]
	v_mfma_f32_16x16x32_bf16 v[68:71], v[16:19], v[4:7], v[68:71]
	v_mfma_f32_16x16x32_bf16 v[108:111], v[16:19], v[8:11], v[108:111]
	v_mfma_f32_16x16x32_bf16 v[132:135], v[16:19], v[12:15], v[132:135]
	v_mfma_f32_16x16x32_bf16 v[120:123], v[20:23], v[0:3], v[120:123]
	v_mfma_f32_16x16x32_bf16 v[64:67], v[20:23], v[4:7], v[64:67]
	v_mfma_f32_16x16x32_bf16 v[112:115], v[20:23], v[8:11], v[112:115]
	v_mfma_f32_16x16x32_bf16 v[136:139], v[20:23], v[12:15], v[136:139]
	s_waitcnt vmcnt(0)
	s_waitcnt lgkmcnt(0)
	s_barrier

.LBB0_743:
	s_or_b64 exec, exec, s[6:7]
	v_mul_u32_u24_e32 v16, 0x41, v20
	v_lshlrev_b32_e32 v16, 2, v16
	v_lshl_add_u32 v16, v21, 2, v16
	s_waitcnt vmcnt(0)
	ds_write2_b32 v16, v0, v1 offset1:65
	ds_write2_b32 v16, v2, v3 offset0:130 offset1:195
	v_add_u32_e32 v0, 0x400, v16
	ds_write2_b32 v0, v4, v5 offset0:4 offset1:69
	ds_write2_b32 v0, v6, v7 offset0:134 offset1:199
	v_add_u32_e32 v0, 0x800, v16
	ds_write2_b32 v0, v8, v9 offset0:8 offset1:73
	ds_write2_b32 v0, v10, v11 offset0:138 offset1:203
	v_add_u32_e32 v0, 0xc00, v16
	ds_write2_b32 v0, v12, v13 offset0:12 offset1:77
	ds_write2_b32 v0, v14, v15 offset0:142 offset1:207
	v_mul_lo_u32 v0, v21, s81
	v_lshl_add_u32 v12, v20, 2, v0
	s_waitcnt lgkmcnt(0)
	s_barrier
	ds_read2_b32 v[0:1], v12 offset1:1
	ds_read2_b32 v[2:3], v12 offset0:2 offset1:3
	ds_read2_b32 v[4:5], v12 offset0:4 offset1:5
	ds_read2_b32 v[6:7], v12 offset0:6 offset1:7
	s_waitcnt lgkmcnt(3)
	v_cvt_pk_bf16_f32 v0, v0, v1
	s_waitcnt lgkmcnt(2)
	v_cvt_pk_bf16_f32 v1, v2, v3
	s_waitcnt lgkmcnt(1)
	v_cvt_pk_bf16_f32 v2, v4, v5
	ds_read2_b32 v[4:5], v12 offset0:8 offset1:9
	ds_read2_b32 v[8:9], v12 offset0:10 offset1:11
	ds_read2_b32 v[10:11], v12 offset0:12 offset1:13
	ds_read2_b32 v[12:13], v12 offset0:14 offset1:15
	s_mul_hi_i32 s7, s13, 0x680000
	s_mul_i32 s13, s13, 0x680000
	s_waitcnt lgkmcnt(3)
	v_cvt_pk_bf16_f32 v4, v4, v5
	s_waitcnt lgkmcnt(2)
	v_cvt_pk_bf16_f32 v5, v8, v9
	v_add_u32_e32 v8, s5, v21
	s_add_u32 s6, s82, s13
	v_ashrrev_i32_e32 v9, 31, v8
	s_addc_u32 s7, s83, s7
	v_lshlrev_b64 v[8:9], 6, v[8:9]
	v_lshl_add_u64 v[8:9], s[6:7], 0, v[8:9]
	s_mul_i32 s4, s4, 0x1a00
	s_ashr_i32 s5, s4, 31
	v_lshl_add_u64 v[8:9], s[4:5], 0, v[8:9]
	v_and_b32_e32 v152, 32, v20
	v_mul_u32_u24_e32 v152, 0x1a00, v152
	v_and_b32_e32 v14, 16, v20
	v_lshl_add_u32 v152, v14, 1, v152
	v_cvt_pk_bf16_f32 v3, v6, v7
	v_lshl_add_u64 v[8:9], v[8:9], 0, v[152:153]
	s_waitcnt lgkmcnt(1)
	v_cvt_pk_bf16_f32 v6, v10, v11
	s_waitcnt lgkmcnt(0)
	v_cvt_pk_bf16_f32 v7, v12, v13
	global_store_dwordx4 v[8:9], v[0:3], off
	global_store_dwordx4 v[8:9], v[4:7], off offset:16
	s_barrier

.LBB0_766:
	s_andn2_b64 vcc, exec, s[4:5]
	s_cbranch_vccnz .LBB0_768
	s_add_i32 s6, s12, 0xffffef80
	s_lshr_b32 s84, s6, 10
	s_lshl_b64 s[4:5], s[84:85], 24
	s_add_u32 s8, s76, s4
	s_addc_u32 s9, s77, s5
	s_lshl_b64 s[4:5], s[84:85], 23
	v_readlane_b32 s7, v253, 55
	s_add_u32 s4, s7, s4
	v_readlane_b32 s7, v253, 56
	s_addc_u32 s5, s7, s5
	s_lshl_b32 s6, s6, 2
	s_and_b32 s6, s6, 0xfc0
	v_mov_b32 v16, v198
	s_lshl_b32 s7, s12, 6
	v_ashrrev_i32_e32 v17, 2, v16
	v_lshlrev_b32_e32 v0, 4, v16
	v_and_b32_e32 v18, 48, v0
	v_add_u32_e32 v0, s6, v17
	s_and_b32 s7, s7, 0x3c0
	s_waitcnt lgkmcnt(0)
	v_ashrrev_i32_e32 v1, 31, v0
	v_lshlrev_b64 v[0:1], 12, v[0:1]
	v_or_b32_e32 v2, s7, v18
	v_lshl_add_u64 v[0:1], s[8:9], 0, v[0:1]
	v_lshlrev_b32_e32 v152, 2, v2
	v_lshl_add_u64 v[12:13], v[0:1], 0, v[152:153]
	global_load_dwordx4 v[0:3], v[12:13], off offset:48
	global_load_dwordx4 v[4:7], v[12:13], off offset:32
	global_load_dwordx4 v[8:11], v[12:13], off offset:16
	s_nop 0
	global_load_dwordx4 v[12:15], v[12:13], off
	v_and_b32_e32 v16, -4, v16
	v_mul_u32_u24_e32 v19, 0x41, v18
	v_lshl_add_u32 v16, v19, 2, v16
	s_lshl_b32 s84, s6, 1
	v_lshlrev_b32_e32 v152, 1, v18
	s_waitcnt vmcnt(0)
	ds_write2_b32 v16, v12, v13 offset1:65
	ds_write2_b32 v16, v14, v15 offset0:130 offset1:195
	v_add_u32_e32 v12, 0x400, v16
	ds_write2_b32 v12, v8, v9 offset0:4 offset1:69
	ds_write2_b32 v12, v10, v11 offset0:134 offset1:199
	v_add_u32_e32 v8, 0x800, v16
	ds_write2_b32 v8, v4, v5 offset0:8 offset1:73
	ds_write2_b32 v8, v6, v7 offset0:138 offset1:203
	v_add_u32_e32 v4, 0xc00, v16
	ds_write2_b32 v4, v0, v1 offset0:12 offset1:77
	ds_write2_b32 v4, v2, v3 offset0:142 offset1:207
	v_mul_lo_u32 v0, v17, s81
	v_lshl_add_u32 v8, v18, 2, v0
	s_waitcnt lgkmcnt(0)
	s_barrier
	ds_read2_b32 v[0:1], v8 offset1:1
	ds_read2_b32 v[2:3], v8 offset0:2 offset1:3
	ds_read2_b32 v[4:5], v8 offset0:6 offset1:7
	s_waitcnt lgkmcnt(2)
	v_cvt_pk_bf16_f32 v0, v0, v1
	s_waitcnt lgkmcnt(1)
	v_cvt_pk_bf16_f32 v1, v2, v3
	ds_read2_b32 v[2:3], v8 offset0:4 offset1:5
	ds_read2_b32 v[6:7], v8 offset0:10 offset1:11
	s_waitcnt lgkmcnt(1)
	v_cvt_pk_bf16_f32 v2, v2, v3
	v_cvt_pk_bf16_f32 v3, v4, v5
	ds_read2_b32 v[4:5], v8 offset0:8 offset1:9
	s_waitcnt lgkmcnt(0)
	v_cvt_pk_bf16_f32 v4, v4, v5
	v_cvt_pk_bf16_f32 v5, v6, v7
	ds_read2_b32 v[6:7], v8 offset0:12 offset1:13
	ds_read2_b32 v[8:9], v8 offset0:14 offset1:15
	s_waitcnt lgkmcnt(1)
	v_cvt_pk_bf16_f32 v6, v6, v7
	s_waitcnt lgkmcnt(0)
	v_cvt_pk_bf16_f32 v7, v8, v9
	v_add_u32_e32 v8, s7, v17
	v_ashrrev_i32_e32 v9, 31, v8
	v_lshlrev_b64 v[8:9], 6, v[8:9]
	v_lshl_add_u64 v[8:9], s[4:5], 0, v[8:9]
	s_mul_i32 s84, s84, 0x400
	v_and_b32_e32 v10, 32, v18
	v_mul_u32_u24_e32 v10, 0x800, v10
	v_and_b32_e32 v11, 16, v18
	v_lshl_add_u32 v152, v11, 1, v10
	v_lshl_add_u64 v[8:9], v[8:9], 0, s[84:85]
	v_lshl_add_u64 v[8:9], v[8:9], 0, v[152:153]
	global_store_dwordx4 v[8:9], v[0:3], off
	global_store_dwordx4 v[8:9], v[4:7], off offset:16
	s_barrier

.LBB0_769:
	s_andn2_b64 vcc, exec, s[4:5]
	s_cbranch_vccnz .LBB0_771
	s_add_i32 s4, s12, 0xfffff780
	s_lshr_b32 s84, s4, 10
	v_readlane_b32 s16, v253, 1
	s_and_b32 s6, s4, 0x3c0
	s_lshl_b64 s[4:5], s[84:85], 24
	v_readlane_b32 s30, v253, 15
	v_readlane_b32 s31, v253, 16
	s_add_u32 s8, s30, s4
	s_addc_u32 s9, s31, s5
	s_lshl_b64 s[4:5], s[84:85], 23
	v_readlane_b32 s7, v253, 23
	s_add_u32 s4, s7, s4
	v_readlane_b32 s7, v253, 24
	v_mov_b32 v16, v198
	s_addc_u32 s5, s7, s5
	v_ashrrev_i32_e32 v17, 2, v16
	v_lshlrev_b32_e32 v0, 4, v16
	s_lshl_b32 s7, s12, 6
	v_and_b32_e32 v18, 48, v0
	v_add_u32_e32 v0, s6, v17
	s_and_b32 s7, s7, 0xfc0
	s_waitcnt lgkmcnt(0)
	v_ashrrev_i32_e32 v1, 31, v0
	v_lshlrev_b64 v[0:1], 14, v[0:1]
	v_or_b32_e32 v2, s7, v18
	v_lshl_add_u64 v[0:1], s[8:9], 0, v[0:1]
	v_lshlrev_b32_e32 v152, 2, v2
	v_lshl_add_u64 v[12:13], v[0:1], 0, v[152:153]
	global_load_dwordx4 v[0:3], v[12:13], off offset:48
	global_load_dwordx4 v[4:7], v[12:13], off offset:32
	global_load_dwordx4 v[8:11], v[12:13], off offset:16
	s_nop 0
	global_load_dwordx4 v[12:15], v[12:13], off
	v_and_b32_e32 v16, -4, v16
	v_mul_u32_u24_e32 v19, 0x41, v18
	v_lshl_add_u32 v16, v19, 2, v16
	s_lshl_b32 s84, s6, 1
	v_lshlrev_b32_e32 v152, 1, v18
	v_readlane_b32 s17, v253, 2
	v_readlane_b32 s18, v253, 3
	v_readlane_b32 s19, v253, 4
	v_readlane_b32 s20, v253, 5
	v_readlane_b32 s21, v253, 6
	v_readlane_b32 s22, v253, 7
	v_readlane_b32 s23, v253, 8
	v_readlane_b32 s24, v253, 9
	v_readlane_b32 s25, v253, 10
	v_readlane_b32 s26, v253, 11
	v_readlane_b32 s27, v253, 12
	v_readlane_b32 s28, v253, 13
	v_readlane_b32 s29, v253, 14
	s_waitcnt vmcnt(0)
	ds_write2_b32 v16, v12, v13 offset1:65
	ds_write2_b32 v16, v14, v15 offset0:130 offset1:195
	v_add_u32_e32 v12, 0x400, v16
	ds_write2_b32 v12, v8, v9 offset0:4 offset1:69
	ds_write2_b32 v12, v10, v11 offset0:134 offset1:199
	v_add_u32_e32 v8, 0x800, v16
	ds_write2_b32 v8, v4, v5 offset0:8 offset1:73
	ds_write2_b32 v8, v6, v7 offset0:138 offset1:203
	v_add_u32_e32 v4, 0xc00, v16
	ds_write2_b32 v4, v0, v1 offset0:12 offset1:77
	ds_write2_b32 v4, v2, v3 offset0:142 offset1:207
	v_mul_lo_u32 v0, v17, s81
	v_lshl_add_u32 v8, v18, 2, v0
	s_waitcnt lgkmcnt(0)
	s_barrier
	ds_read2_b32 v[0:1], v8 offset1:1
	ds_read2_b32 v[2:3], v8 offset0:2 offset1:3
	ds_read2_b32 v[4:5], v8 offset0:6 offset1:7
	s_waitcnt lgkmcnt(2)
	v_cvt_pk_bf16_f32 v0, v0, v1
	s_waitcnt lgkmcnt(1)
	v_cvt_pk_bf16_f32 v1, v2, v3
	ds_read2_b32 v[2:3], v8 offset0:4 offset1:5
	ds_read2_b32 v[6:7], v8 offset0:10 offset1:11
	s_waitcnt lgkmcnt(1)
	v_cvt_pk_bf16_f32 v2, v2, v3
	v_cvt_pk_bf16_f32 v3, v4, v5
	ds_read2_b32 v[4:5], v8 offset0:8 offset1:9
	s_waitcnt lgkmcnt(0)
	v_cvt_pk_bf16_f32 v4, v4, v5
	v_cvt_pk_bf16_f32 v5, v6, v7
	ds_read2_b32 v[6:7], v8 offset0:12 offset1:13
	ds_read2_b32 v[8:9], v8 offset0:14 offset1:15
	s_waitcnt lgkmcnt(1)
	v_cvt_pk_bf16_f32 v6, v6, v7
	s_waitcnt lgkmcnt(0)
	v_cvt_pk_bf16_f32 v7, v8, v9
	v_add_u32_e32 v8, s7, v17
	v_ashrrev_i32_e32 v9, 31, v8
	v_lshlrev_b64 v[8:9], 6, v[8:9]
	v_lshl_add_u64 v[8:9], s[4:5], 0, v[8:9]
	s_mul_i32 s84, s84, 0x1000
	v_and_b32_e32 v10, 32, v18
	v_mul_u32_u24_e32 v10, 0x2000, v10
	v_and_b32_e32 v11, 16, v18
	v_lshl_add_u32 v152, v11, 1, v10
	v_lshl_add_u64 v[8:9], v[8:9], 0, s[84:85]
	v_lshl_add_u64 v[8:9], v[8:9], 0, v[152:153]
	global_store_dwordx4 v[8:9], v[0:3], off
	global_store_dwordx4 v[8:9], v[4:7], off offset:16
	s_barrier

.LBB0_772:
	s_andn2_b64 vcc, exec, s[4:5]
	s_cbranch_vccnz .LBB0_774
	s_add_i32 s6, s12, 0xfffff980
	s_lshr_b32 s84, s6, 8
	v_readlane_b32 s16, v253, 1
	s_lshl_b64 s[4:5], s[84:85], 22
	v_readlane_b32 s26, v253, 11
	v_readlane_b32 s27, v253, 12
	s_add_u32 s8, s26, s4
	s_addc_u32 s9, s27, s5
	s_lshl_b64 s[4:5], s[84:85], 21
	v_readlane_b32 s7, v253, 27
	s_add_u32 s4, s7, s4
	v_readlane_b32 s7, v253, 28
	s_addc_u32 s5, s7, s5
	s_lshl_b32 s6, s6, 2
	s_and_b32 s6, s6, 0x3c0
	v_mov_b32 v16, v198
	s_lshl_b32 s7, s12, 6
	v_ashrrev_i32_e32 v17, 2, v16
	v_lshlrev_b32_e32 v0, 4, v16
	v_and_b32_e32 v18, 48, v0
	v_add_u32_e32 v0, s6, v17
	s_and_b32 s7, s7, 0x3c0
	s_waitcnt lgkmcnt(0)
	v_ashrrev_i32_e32 v1, 31, v0
	v_lshlrev_b64 v[0:1], 12, v[0:1]
	v_or_b32_e32 v2, s7, v18
	v_lshl_add_u64 v[0:1], s[8:9], 0, v[0:1]
	v_lshlrev_b32_e32 v152, 2, v2
	v_lshl_add_u64 v[12:13], v[0:1], 0, v[152:153]
	global_load_dwordx4 v[0:3], v[12:13], off offset:48
	global_load_dwordx4 v[4:7], v[12:13], off offset:32
	global_load_dwordx4 v[8:11], v[12:13], off offset:16
	s_nop 0
	global_load_dwordx4 v[12:15], v[12:13], off
	v_and_b32_e32 v16, -4, v16
	v_mul_u32_u24_e32 v19, 0x41, v18
	v_lshl_add_u32 v16, v19, 2, v16
	s_lshl_b32 s84, s6, 1
	v_lshlrev_b32_e32 v152, 1, v18
	v_readlane_b32 s17, v253, 2
	v_readlane_b32 s18, v253, 3
	v_readlane_b32 s19, v253, 4
	v_readlane_b32 s20, v253, 5
	v_readlane_b32 s21, v253, 6
	v_readlane_b32 s22, v253, 7
	v_readlane_b32 s23, v253, 8
	v_readlane_b32 s24, v253, 9
	v_readlane_b32 s25, v253, 10
	v_readlane_b32 s28, v253, 13
	v_readlane_b32 s29, v253, 14
	v_readlane_b32 s30, v253, 15
	v_readlane_b32 s31, v253, 16
	s_waitcnt vmcnt(0)
	ds_write2_b32 v16, v12, v13 offset1:65
	ds_write2_b32 v16, v14, v15 offset0:130 offset1:195
	v_add_u32_e32 v12, 0x400, v16
	ds_write2_b32 v12, v8, v9 offset0:4 offset1:69
	ds_write2_b32 v12, v10, v11 offset0:134 offset1:199
	v_add_u32_e32 v8, 0x800, v16
	ds_write2_b32 v8, v4, v5 offset0:8 offset1:73
	ds_write2_b32 v8, v6, v7 offset0:138 offset1:203
	v_add_u32_e32 v4, 0xc00, v16
	ds_write2_b32 v4, v0, v1 offset0:12 offset1:77
	ds_write2_b32 v4, v2, v3 offset0:142 offset1:207
	v_mul_lo_u32 v0, v17, s81
	v_lshl_add_u32 v8, v18, 2, v0
	s_waitcnt lgkmcnt(0)
	s_barrier
	ds_read2_b32 v[0:1], v8 offset1:1
	ds_read2_b32 v[2:3], v8 offset0:2 offset1:3
	ds_read2_b32 v[4:5], v8 offset0:6 offset1:7
	s_waitcnt lgkmcnt(2)
	v_cvt_pk_bf16_f32 v0, v0, v1
	s_waitcnt lgkmcnt(1)
	v_cvt_pk_bf16_f32 v1, v2, v3
	ds_read2_b32 v[2:3], v8 offset0:4 offset1:5
	ds_read2_b32 v[6:7], v8 offset0:10 offset1:11
	s_waitcnt lgkmcnt(1)
	v_cvt_pk_bf16_f32 v2, v2, v3
	v_cvt_pk_bf16_f32 v3, v4, v5
	ds_read2_b32 v[4:5], v8 offset0:8 offset1:9
	s_waitcnt lgkmcnt(0)
	v_cvt_pk_bf16_f32 v4, v4, v5
	v_cvt_pk_bf16_f32 v5, v6, v7
	ds_read2_b32 v[6:7], v8 offset0:12 offset1:13
	ds_read2_b32 v[8:9], v8 offset0:14 offset1:15
	s_waitcnt lgkmcnt(1)
	v_cvt_pk_bf16_f32 v6, v6, v7
	s_waitcnt lgkmcnt(0)
	v_cvt_pk_bf16_f32 v7, v8, v9
	v_add_u32_e32 v8, s7, v17
	v_ashrrev_i32_e32 v9, 31, v8
	v_lshlrev_b64 v[8:9], 6, v[8:9]
	v_lshl_add_u64 v[8:9], s[4:5], 0, v[8:9]
	s_mul_i32 s84, s84, 0x400
	v_and_b32_e32 v10, 32, v18
	v_mul_u32_u24_e32 v10, 0x800, v10
	v_and_b32_e32 v11, 16, v18
	v_lshl_add_u32 v152, v11, 1, v10
	v_lshl_add_u64 v[8:9], v[8:9], 0, s[84:85]
	v_lshl_add_u64 v[8:9], v[8:9], 0, v[152:153]
	global_store_dwordx4 v[8:9], v[0:3], off
	global_store_dwordx4 v[8:9], v[4:7], off offset:16
	s_barrier
